# unit switch: the trailing wave half takes its re-skew barrier after its next-unit decode and accumulator clear, so that work overlaps the leading half
# baseline (speedup 1.0000x reference)
; #define PG8_STAGE(bufoff, gbase, voff) do { _Pragma("unroll") for (int _i = 0; _i < 2; ++_i) \
;         __builtin_amdgcn_global_load_lds((const unsigned*)((const char*)(gbase) + (voff)[_i]), (PG8_LAS unsigned*)(lds + (bufoff) + ldsw + _i * 8192), 16, 0, 0); } while (0)
; #define PG8_LDA(dst, b, h) do { _Pragma("unroll") for (int m = 0; m < 4; ++m) _Pragma("unroll") for (int k = 0; k < 2; ++k) dst[m][k] = *(const PG8_LAS bf16x8*)(lds + PG8_SA(b, h) + aoff + m * 2048 + k * 1024); } while (0)
; #define PG8_LDB(dst, b, h) do { _Pragma("unroll") for (int n = 0; n < 2; ++n) _Pragma("unroll") for (int k = 0; k < 2; ++k) dst[n][k] = *(const PG8_LAS bf16x8*)(lds + PG8_SB(b, h) + boff + n * 2048 + k * 1024); } while (0)
; #define PG8_MMA(ai, bj, At, Bt) do { __builtin_amdgcn_s_setprio(1); _Pragma("unroll") for (int m = 0; m < 4; ++m) _Pragma("unroll") for (int n = 0; n < 2; ++n) _Pragma("unroll") for (int k = 0; k < 2; ++k) \
;         acc[ai][bj][m][n] = __builtin_amdgcn_mfma_f32_16x16x32_bf16(Bt[n][k], At[m][k], acc[ai][bj][m][n], 0, 0, 0); __builtin_amdgcn_s_setprio(0); } while (0)
; #define PG8_WAIT_V(n) asm volatile("s_waitcnt vmcnt(" #n ")" ::: "memory")
; #define PG8_WAIT_VN(n) asm volatile("s_waitcnt vmcnt(%0)" :: "n"(n) : "memory")
; #define PG8_WAIT_L(n) asm volatile("s_waitcnt lgkmcnt(" #n ")" ::: "memory")
; #define PG8_BAR __builtin_amdgcn_s_barrier()
; template <class Epi, class Sched, bool ALIGN_EPI = false, bool SP2 = false>
; __device__ __forceinline__ void gemm_phase(PG8_LAS unsigned char* lds, const Gemm g, const Sched& S, const Epi& E, const int wave_id) {
;     ...
;             PG8_WAIT_VN(8 + Epi::NS); if (strict) PG8_WAIT_V(8); PG8_WAIT_L(0); PG8_BAR; PG8_MMA(1, 0, At, B0); PG8_MMA(1, 1, At, B1); PG8_BAR; PG8_SCHED;
;             PG8_LDB(B0, 1, 0); PG8_LDB(B1, 1, 1); PG8_SCHED; PG8_LDA(At, 1, 0); PG8_STAGE(PG8_SA(0, 1), a2 + hstep, voffA);
;             PG8_WAIT_V(8); PG8_WAIT_L(0); PG8_BAR; PG8_MMA(0, 0, At, B0); PG8_MMA(0, 1, At, B1); PG8_BAR; PG8_SCHED;
;     ...
;         for (int a = 0; a < 2; ++a)
; #pragma unroll
;             for (int b = 0; b < 2; ++b)
; #pragma unroll
;                 for (int m = 0; m < 4; ++m)
; #pragma unroll
;                     for (int n = 0; n < 2; ++n) acc[a][b][m][n] = (f32x4){0.f, 0.f, 0.f, 0.f};
;         }
;         cur = nxt; cA = nA; cB = nB; ++ui;
;         if constexpr (ALIGN_EPI) { if (wr == 1) PG8_BAR; }
.LBB0_156:
	s_ashr_i32 s13, s12, 31
	s_lshl_b64 s[14:15], s[12:13], 19
	s_add_u32 s14, s35, s14
	s_addc_u32 s15, s36, s15
	s_and_b64 s[16:17], s[4:5], exec
	s_cselect_b32 s13, s15, s21
	s_cselect_b32 s68, s14, s20
	s_ashr_i32 s11, s10, 31
	s_lshl_b64 s[16:17], s[10:11], 19
	s_add_u32 s16, s37, s16
	s_addc_u32 s17, s38, s17
	s_and_b64 s[26:27], s[4:5], exec
	s_cselect_b32 s11, s17, s23
	s_cselect_b32 s69, s16, s22
	s_cmp_eq_u32 s24, 0
	s_cselect_b64 s[24:25], -1, 0
	s_add_u32 s74, s22, 0x100
	s_addc_u32 s75, s23, 0
	s_add_u32 s22, s20, 0x40080
	s_addc_u32 s23, s21, 0
	v_mov_b32_e32 v2, 0
	v_mov_b64_e32 v[196:197], 0x400
	v_cndmask_b32_e64 v250, 0, 1, s[24:25]
	s_and_b32 s101, s24, 1
	v_lshl_add_u64 v[222:223], s[22:23], 0, v[218:219]
	v_lshl_add_u64 v[224:225], s[22:23], 0, v[220:221]
	s_mov_b32 s76, -2
	s_mov_b64 s[22:23], 0
	v_mov_b32_e32 v3, v2
	v_mov_b64_e32 v[4:5], 0
	v_mov_b64_e32 v[6:7], 0
	v_mov_b64_e32 v[8:9], 0
	v_mov_b64_e32 v[10:11], 0
	v_mov_b64_e32 v[12:13], 0
	v_mov_b64_e32 v[14:15], 0
	v_mov_b64_e32 v[16:17], 0
	v_mov_b64_e32 v[18:19], 0
	v_mov_b64_e32 v[20:21], 0
	v_mov_b64_e32 v[22:23], 0
	v_mov_b64_e32 v[24:25], 0
	v_mov_b64_e32 v[26:27], 0
	v_mov_b64_e32 v[28:29], 0
	v_mov_b64_e32 v[30:31], 0
	v_mov_b64_e32 v[32:33], 0
	v_mov_b64_e32 v[34:35], 0
	v_mov_b64_e32 v[36:37], 0
	v_mov_b64_e32 v[38:39], 0
	v_mov_b64_e32 v[40:41], 0
	v_mov_b64_e32 v[42:43], 0
	v_mov_b64_e32 v[44:45], 0
	v_mov_b64_e32 v[46:47], 0
	v_mov_b64_e32 v[48:49], 0
	v_mov_b64_e32 v[50:51], 0
	v_mov_b64_e32 v[52:53], 0
	v_mov_b64_e32 v[54:55], 0
	v_mov_b64_e32 v[56:57], 0
	v_mov_b64_e32 v[58:59], 0
	v_mov_b64_e32 v[60:61], 0
	v_mov_b64_e32 v[62:63], 0
	v_mov_b64_e32 v[64:65], 0
	v_mov_b64_e32 v[66:67], 0
	v_mov_b64_e32 v[68:69], 0
	v_mov_b64_e32 v[70:71], 0
	v_mov_b64_e32 v[72:73], 0
	v_mov_b64_e32 v[74:75], 0
	v_mov_b64_e32 v[76:77], 0
	v_mov_b64_e32 v[78:79], 0
	v_mov_b64_e32 v[80:81], 0
	v_mov_b64_e32 v[82:83], 0
	v_mov_b64_e32 v[84:85], 0
	v_mov_b64_e32 v[86:87], 0
	v_mov_b64_e32 v[88:89], 0
	v_mov_b64_e32 v[90:91], 0
	v_mov_b64_e32 v[92:93], 0
	v_mov_b64_e32 v[94:95], 0
	v_mov_b64_e32 v[96:97], 0
	v_mov_b64_e32 v[98:99], 0
	v_mov_b64_e32 v[100:101], 0
	v_mov_b64_e32 v[102:103], 0
	v_mov_b64_e32 v[104:105], 0
	v_mov_b64_e32 v[106:107], 0
	v_mov_b64_e32 v[108:109], 0
	v_mov_b64_e32 v[110:111], 0
	v_mov_b64_e32 v[112:113], 0
	v_mov_b64_e32 v[114:115], 0
	v_mov_b64_e32 v[116:117], 0
	v_mov_b64_e32 v[118:119], 0
	v_mov_b64_e32 v[120:121], 0
	v_mov_b64_e32 v[122:123], 0
	v_mov_b64_e32 v[124:125], 0
	v_mov_b64_e32 v[126:127], 0
	v_mov_b64_e32 v[128:129], 0
	s_cmp_eq_u32 s101, 0
	s_cbranch_scc0 .Lskew_skip_5
	s_andn2_b64 vcc, exec, s[2:3]
	s_cbranch_vccnz .Lskew_skip_5
	s_barrier
.Lskew_skip_5:
	s_branch .LBB0_158
.LBB0_157:
	s_waitcnt lgkmcnt(0)
	s_barrier
	s_setprio 1
	s_waitcnt lgkmcnt(0)
	v_mfma_f32_16x16x32_bf16 v[62:65], v[146:149], v[186:189], v[62:65]
	v_mfma_f32_16x16x32_bf16 v[58:61], v[154:157], v[186:189], v[58:61]
	v_mfma_f32_16x16x32_bf16 v[54:57], v[146:149], v[178:181], v[54:57]
	v_mfma_f32_16x16x32_bf16 v[50:53], v[154:157], v[178:181], v[50:53]
	v_mfma_f32_16x16x32_bf16 v[30:33], v[146:149], v[170:173], v[30:33]
	v_mfma_f32_16x16x32_bf16 v[26:29], v[154:157], v[170:173], v[26:29]
	v_mfma_f32_16x16x32_bf16 v[22:25], v[146:149], v[162:165], v[22:25]
	v_mfma_f32_16x16x32_bf16 v[18:21], v[154:157], v[162:165], v[18:21]
	v_mfma_f32_16x16x32_bf16 v[62:65], v[150:153], v[190:193], v[62:65]
	v_mfma_f32_16x16x32_bf16 v[58:61], v[158:161], v[190:193], v[58:61]
	v_mfma_f32_16x16x32_bf16 v[54:57], v[150:153], v[182:185], v[54:57]
	v_mfma_f32_16x16x32_bf16 v[50:53], v[158:161], v[182:185], v[50:53]
	v_mfma_f32_16x16x32_bf16 v[30:33], v[150:153], v[174:177], v[30:33]
	v_mfma_f32_16x16x32_bf16 v[26:29], v[158:161], v[174:177], v[26:29]
	v_mfma_f32_16x16x32_bf16 v[22:25], v[150:153], v[166:169], v[22:25]
	v_mfma_f32_16x16x32_bf16 v[18:21], v[158:161], v[166:169], v[18:21]
	s_setprio 0
	s_setprio 1
	v_mfma_f32_16x16x32_bf16 v[46:49], v[130:133], v[186:189], v[46:49]
	v_mfma_f32_16x16x32_bf16 v[42:45], v[138:141], v[186:189], v[42:45]
	v_mfma_f32_16x16x32_bf16 v[38:41], v[130:133], v[178:181], v[38:41]
	v_mfma_f32_16x16x32_bf16 v[34:37], v[138:141], v[178:181], v[34:37]
	v_mfma_f32_16x16x32_bf16 v[14:17], v[130:133], v[170:173], v[14:17]
	v_mfma_f32_16x16x32_bf16 v[10:13], v[138:141], v[170:173], v[10:13]
	v_mfma_f32_16x16x32_bf16 v[6:9], v[130:133], v[162:165], v[6:9]
	v_mfma_f32_16x16x32_bf16 v[2:5], v[138:141], v[162:165], v[2:5]
	v_mfma_f32_16x16x32_bf16 v[46:49], v[134:137], v[190:193], v[46:49]
	v_mfma_f32_16x16x32_bf16 v[42:45], v[142:145], v[190:193], v[42:45]
	v_mfma_f32_16x16x32_bf16 v[38:41], v[134:137], v[182:185], v[38:41]
	v_mfma_f32_16x16x32_bf16 v[34:37], v[142:145], v[182:185], v[34:37]
	v_mfma_f32_16x16x32_bf16 v[14:17], v[134:137], v[174:177], v[14:17]
	v_mfma_f32_16x16x32_bf16 v[10:13], v[142:145], v[174:177], v[10:13]
	v_mfma_f32_16x16x32_bf16 v[6:9], v[134:137], v[166:169], v[6:9]
	v_mfma_f32_16x16x32_bf16 v[2:5], v[142:145], v[166:169], v[2:5]
	s_setprio 0
	s_barrier
	s_add_i32 s28, 0, 0x18000
	s_add_i32 s29, 0, 0x1c000
	v_add_u32_e32 v142, s28, v246
	v_add_u32_e32 v158, s29, v246
	ds_read_b128 v[130:133], v142
	ds_read_b128 v[134:137], v142 offset:1024
	ds_read_b128 v[138:141], v142 offset:2048
	ds_read_b128 v[142:145], v142 offset:3072
	ds_read_b128 v[146:149], v158
	ds_read_b128 v[150:153], v158 offset:1024
	ds_read_b128 v[154:157], v158 offset:2048
	ds_read_b128 v[158:161], v158 offset:3072
	s_add_u32 s26, s26, 0x40000
	s_addc_u32 s27, s27, 0
	s_mov_b32 m0, s52
	v_lshl_add_u64 v[194:195], s[26:27], 0, v[210:211]
	ds_read_b128 v[162:165], v249 offset:32768
	ds_read_b128 v[166:169], v249 offset:33792
	ds_read_b128 v[170:173], v249 offset:34816
	ds_read_b128 v[174:177], v249 offset:35840
	ds_read_b128 v[178:181], v249 offset:36864
	ds_read_b128 v[182:185], v249 offset:37888
	ds_read_b128 v[186:189], v249 offset:38912
	ds_read_b128 v[190:193], v249 offset:39936
	global_load_lds_dwordx4 v[194:195], off
	v_lshl_add_u64 v[194:195], s[26:27], 0, v[214:215]
	s_mov_b32 m0, s54
	s_nop 0
	global_load_lds_dwordx4 v[194:195], off
	s_waitcnt vmcnt(18)
	s_cmp_eq_u32 s100, 0
	s_cbranch_scc1 .Lthird_wait_relaxed_6
	s_waitcnt vmcnt(8)

; __device__ __forceinline__ unsigned cvt_pk_bf16(float lo, float hi) { unsigned r; asm volatile("v_cvt_pk_bf16_f32 %0, %1, %2" : "=v"(r) : "v"(lo), "v"(hi)); return r; }
; #define GAS __attribute__((address_space(1)))
; __device__ __forceinline__ float siluf_(float x) { return x * sigmoidf_(x); }
;     __device__ __forceinline__ bool operator()(AccT& acc, const Unit& u, int wr, int wc, int fr, int fq) const {
;     ...
;         const int row0 = u.pm * 256 + wr * 64 + fr + 16 * (fq & 1), col0 = u.pn * 128 + wc * 16 + 4 * (fq & 2);
; #pragma unroll
;         for (int ai = 0; ai < 2; ++ai)
; #pragma unroll
;             for (int mp = 0; mp < 2; ++mp) { bf16* rowp = act + (size_t)(row0 + ai * 128 + mp * 32) * DFF + col0;
; #pragma unroll
;                 for (int bj = 0; bj < 2; ++bj) { unsigned pk[2][2];
; #pragma unroll
;                     for (int k = 0; k < 2; ++k) { const f32x4 g = acc[ai][bj][2 * mp + k][0], up = acc[ai][bj][2 * mp + k][1];
;                         pk[k][0] = pg8::cvt_pk_bf16(siluf_(g[0]) * up[0], siluf_(g[1]) * up[1]); pk[k][1] = pg8::cvt_pk_bf16(siluf_(g[2]) * up[2], siluf_(g[3]) * up[3]); }
;                     const auto sx = __builtin_amdgcn_permlane16_swap(pk[0][0], pk[1][0], false, false), sy = __builtin_amdgcn_permlane16_swap(pk[0][1], pk[1][1], false, false);
;                     *(GAS v4u*)(rowp + bj * 64) = (v4u){sx[0], sy[0], sx[1], sy[1]}; } }
.LBB0_164:
	s_add_u32 s100, s68, 0x40080
	s_addc_u32 s101, s13, 0
	v_lshl_add_u64 v[194:195], s[100:101], 0, v[220:221]
	s_add_i32 m0, s41, 0xc000
	s_nop 0
	global_load_lds_dwordx4 v[194:195], off
	v_lshl_add_u64 v[194:195], s[100:101], 0, v[218:219]
	s_add_i32 m0, s41, 0xe000
	s_nop 0
	global_load_lds_dwordx4 v[194:195], off
	s_mov_b32 s100, 0xbfb8aa3b
	s_mov_b32 s101, 0xbfb8aa3b
	s_mov_b32 s11, s39
	v_mov_b32_e32 v130, v1
	s_mov_b32 s13, s56
	v_mov_b32_e32 v131, v245
	s_lshl_b32 s19, s19, 7
	s_lshl_b32 s13, s13, 4
	s_lshl_b32 s18, s18, 8
	s_lshl_b32 s11, s11, 6
	v_lshlrev_b32_e32 v132, 4, v131
	s_add_i32 s13, s13, s19
	v_lshlrev_b32_e32 v131, 2, v131
	v_and_b32_e32 v133, 16, v132
	v_and_or_b32 v132, v131, 8, s13
	s_add_i32 s11, s11, s18
	v_add3_u32 v136, s11, v130, v133
	v_ashrrev_i32_e32 v133, 31, v132
	v_mov_b64_e32 v[130:131], s[6:7]
	s_movk_i32 s11, 0x1600
	v_mad_i64_i32 v[134:135], s[18:19], v136, s11, v[130:131]
	v_lshlrev_b64 v[132:133], 1, v[132:133]
	v_lshl_add_u64 v[134:135], v[134:135], 0, v[132:133]
	s_andn2_b64 vcc, exec, s[4:5]
	v_pk_mul_f32 v[138:139], v[126:127], s[100:101]
	v_pk_mul_f32 v[140:141], v[128:129], s[100:101]
	v_pk_mul_f32 v[142:143], v[118:119], s[100:101]
	v_pk_mul_f32 v[144:145], v[120:121], s[100:101]
	v_exp_f32_e32 v138, v138
	v_exp_f32_e32 v139, v139
	v_exp_f32_e32 v140, v140
	v_exp_f32_e32 v141, v141
	v_exp_f32_e32 v142, v142
	v_exp_f32_e32 v143, v143
	v_exp_f32_e32 v144, v144
	v_exp_f32_e32 v145, v145
	v_pk_add_f32 v[138:139], v[138:139], 1.0 op_sel_hi:[1,0]
	v_pk_add_f32 v[140:141], v[140:141], 1.0 op_sel_hi:[1,0]
	v_pk_add_f32 v[142:143], v[142:143], 1.0 op_sel_hi:[1,0]
	v_pk_add_f32 v[144:145], v[144:145], 1.0 op_sel_hi:[1,0]
	v_rcp_f32_e32 v138, v138
	v_rcp_f32_e32 v139, v139
	v_rcp_f32_e32 v140, v140
	v_rcp_f32_e32 v141, v141
	v_rcp_f32_e32 v142, v142
	v_rcp_f32_e32 v143, v143
	v_rcp_f32_e32 v144, v144
	v_rcp_f32_e32 v145, v145
	v_pk_mul_f32 v[126:127], v[126:127], v[138:139]
	v_pk_mul_f32 v[128:129], v[128:129], v[140:141]
	v_pk_mul_f32 v[118:119], v[118:119], v[142:143]
	v_pk_mul_f32 v[120:121], v[120:121], v[144:145]
	v_pk_mul_f32 v[122:123], v[122:123], v[126:127]
	v_pk_mul_f32 v[124:125], v[124:125], v[128:129]
	v_pk_mul_f32 v[114:115], v[114:115], v[118:119]
	v_pk_mul_f32 v[116:117], v[116:117], v[120:121]
	v_cvt_pk_bf16_f32 v122, v122, v123
	v_cvt_pk_bf16_f32 v123, v124, v125
	v_cvt_pk_bf16_f32 v124, v114, v115
	v_cvt_pk_bf16_f32 v125, v116, v117
	s_nop 1
	v_permlane16_swap_b32_e32 v122, v124
	v_permlane16_swap_b32_e32 v123, v125
	global_store_dwordx4 v[134:135], v[122:125], off
	v_pk_mul_f32 v[138:139], v[110:111], s[100:101]
	v_pk_mul_f32 v[140:141], v[112:113], s[100:101]
	v_pk_mul_f32 v[142:143], v[102:103], s[100:101]
	v_pk_mul_f32 v[144:145], v[104:105], s[100:101]
	v_exp_f32_e32 v138, v138
	v_exp_f32_e32 v139, v139
	v_exp_f32_e32 v140, v140
	v_exp_f32_e32 v141, v141
	v_exp_f32_e32 v142, v142
	v_exp_f32_e32 v143, v143
	v_exp_f32_e32 v144, v144
	v_exp_f32_e32 v145, v145
	v_pk_add_f32 v[138:139], v[138:139], 1.0 op_sel_hi:[1,0]
	v_pk_add_f32 v[140:141], v[140:141], 1.0 op_sel_hi:[1,0]
	v_pk_add_f32 v[142:143], v[142:143], 1.0 op_sel_hi:[1,0]
	v_pk_add_f32 v[144:145], v[144:145], 1.0 op_sel_hi:[1,0]
	v_rcp_f32_e32 v138, v138
	v_rcp_f32_e32 v139, v139
	v_rcp_f32_e32 v140, v140
	v_rcp_f32_e32 v141, v141
	v_rcp_f32_e32 v142, v142
	v_rcp_f32_e32 v143, v143
	v_rcp_f32_e32 v144, v144
	v_rcp_f32_e32 v145, v145
	v_pk_mul_f32 v[110:111], v[110:111], v[138:139]
	v_pk_mul_f32 v[112:113], v[112:113], v[140:141]
	v_pk_mul_f32 v[102:103], v[102:103], v[142:143]
	v_pk_mul_f32 v[104:105], v[104:105], v[144:145]
	v_pk_mul_f32 v[106:107], v[106:107], v[110:111]
	v_pk_mul_f32 v[108:109], v[108:109], v[112:113]
	v_pk_mul_f32 v[98:99], v[98:99], v[102:103]
	v_pk_mul_f32 v[100:101], v[100:101], v[104:105]
	v_cvt_pk_bf16_f32 v106, v106, v107
	v_cvt_pk_bf16_f32 v107, v108, v109
	v_cvt_pk_bf16_f32 v108, v98, v99
	v_cvt_pk_bf16_f32 v109, v100, v101
	s_nop 1
	v_permlane16_swap_b32_e32 v106, v108
	v_permlane16_swap_b32_e32 v107, v109
	global_store_dwordx4 v[134:135], v[106:109], off offset:128
	v_add_u32_e32 v98, 32, v136
	v_mad_i64_i32 v[98:99], s[18:19], v98, s11, v[130:131]
	v_lshl_add_u64 v[98:99], v[98:99], 0, v[132:133]
	v_pk_mul_f32 v[138:139], v[94:95], s[100:101]
	v_pk_mul_f32 v[140:141], v[96:97], s[100:101]
	v_pk_mul_f32 v[142:143], v[86:87], s[100:101]
	v_pk_mul_f32 v[144:145], v[88:89], s[100:101]
	v_exp_f32_e32 v138, v138
	v_exp_f32_e32 v139, v139
	v_exp_f32_e32 v140, v140
	v_exp_f32_e32 v141, v141
	v_exp_f32_e32 v142, v142
	v_exp_f32_e32 v143, v143
	v_exp_f32_e32 v144, v144
	v_exp_f32_e32 v145, v145
	v_pk_add_f32 v[138:139], v[138:139], 1.0 op_sel_hi:[1,0]
	v_pk_add_f32 v[140:141], v[140:141], 1.0 op_sel_hi:[1,0]
	v_pk_add_f32 v[142:143], v[142:143], 1.0 op_sel_hi:[1,0]
	v_pk_add_f32 v[144:145], v[144:145], 1.0 op_sel_hi:[1,0]
	v_rcp_f32_e32 v138, v138
	v_rcp_f32_e32 v139, v139
	v_rcp_f32_e32 v140, v140
	v_rcp_f32_e32 v141, v141
	v_rcp_f32_e32 v142, v142
	v_rcp_f32_e32 v143, v143
	v_rcp_f32_e32 v144, v144
	v_rcp_f32_e32 v145, v145
	v_pk_mul_f32 v[94:95], v[94:95], v[138:139]
	v_pk_mul_f32 v[96:97], v[96:97], v[140:141]
	v_pk_mul_f32 v[86:87], v[86:87], v[142:143]
	v_pk_mul_f32 v[88:89], v[88:89], v[144:145]
	v_pk_mul_f32 v[90:91], v[90:91], v[94:95]
	v_pk_mul_f32 v[92:93], v[92:93], v[96:97]
	v_pk_mul_f32 v[82:83], v[82:83], v[86:87]
	v_pk_mul_f32 v[84:85], v[84:85], v[88:89]
	v_cvt_pk_bf16_f32 v90, v90, v91
	v_cvt_pk_bf16_f32 v91, v92, v93
	v_cvt_pk_bf16_f32 v92, v82, v83
	v_cvt_pk_bf16_f32 v93, v84, v85
	s_nop 1
	v_permlane16_swap_b32_e32 v90, v92
	v_permlane16_swap_b32_e32 v91, v93
; __device__ __forceinline__ unsigned cvt_pk_bf16(float lo, float hi) { unsigned r; asm volatile("v_cvt_pk_bf16_f32 %0, %1, %2" : "=v"(r) : "v"(lo), "v"(hi)); return r; }
; #define GAS __attribute__((address_space(1)))
; __device__ __forceinline__ float siluf_(float x) { return x * sigmoidf_(x); }
;     __device__ __forceinline__ bool operator()(AccT& acc, const Unit& u, int wr, int wc, int fr, int fq) const {
;     ...
;         for (int ai = 0; ai < 2; ++ai)
; #pragma unroll
;             for (int mp = 0; mp < 2; ++mp) { bf16* rowp = act + (size_t)(row0 + ai * 128 + mp * 32) * DFF + col0;
; #pragma unroll
;                 for (int bj = 0; bj < 2; ++bj) { unsigned pk[2][2];
; #pragma unroll
;                     for (int k = 0; k < 2; ++k) { const f32x4 g = acc[ai][bj][2 * mp + k][0], up = acc[ai][bj][2 * mp + k][1];
;                         pk[k][0] = pg8::cvt_pk_bf16(siluf_(g[0]) * up[0], siluf_(g[1]) * up[1]); pk[k][1] = pg8::cvt_pk_bf16(siluf_(g[2]) * up[2], siluf_(g[3]) * up[3]); }
;                     const auto sx = __builtin_amdgcn_permlane16_swap(pk[0][0], pk[1][0], false, false), sy = __builtin_amdgcn_permlane16_swap(pk[0][1], pk[1][1], false, false);
;                     *(GAS v4u*)(rowp + bj * 64) = (v4u){sx[0], sy[0], sx[1], sy[1]}; } }
	global_store_dwordx4 v[98:99], v[90:93], off
	v_pk_mul_f32 v[138:139], v[78:79], s[100:101]
	v_pk_mul_f32 v[140:141], v[80:81], s[100:101]
	v_pk_mul_f32 v[142:143], v[70:71], s[100:101]
	v_pk_mul_f32 v[144:145], v[72:73], s[100:101]
	v_exp_f32_e32 v138, v138
	v_exp_f32_e32 v139, v139
	v_exp_f32_e32 v140, v140
	v_exp_f32_e32 v141, v141
	v_exp_f32_e32 v142, v142
	v_exp_f32_e32 v143, v143
	v_exp_f32_e32 v144, v144
	v_exp_f32_e32 v145, v145
	v_pk_add_f32 v[138:139], v[138:139], 1.0 op_sel_hi:[1,0]
	v_pk_add_f32 v[140:141], v[140:141], 1.0 op_sel_hi:[1,0]
	v_pk_add_f32 v[142:143], v[142:143], 1.0 op_sel_hi:[1,0]
	v_pk_add_f32 v[144:145], v[144:145], 1.0 op_sel_hi:[1,0]
	v_rcp_f32_e32 v138, v138
	v_rcp_f32_e32 v139, v139
	v_rcp_f32_e32 v140, v140
	v_rcp_f32_e32 v141, v141
	v_rcp_f32_e32 v142, v142
	v_rcp_f32_e32 v143, v143
	v_rcp_f32_e32 v144, v144
	v_rcp_f32_e32 v145, v145
	v_pk_mul_f32 v[78:79], v[78:79], v[138:139]
	v_pk_mul_f32 v[80:81], v[80:81], v[140:141]
	v_pk_mul_f32 v[70:71], v[70:71], v[142:143]
	v_pk_mul_f32 v[72:73], v[72:73], v[144:145]
	v_pk_mul_f32 v[74:75], v[74:75], v[78:79]
	v_pk_mul_f32 v[76:77], v[76:77], v[80:81]
	v_pk_mul_f32 v[66:67], v[66:67], v[70:71]
	v_pk_mul_f32 v[68:69], v[68:69], v[72:73]
	v_cvt_pk_bf16_f32 v74, v74, v75
	v_cvt_pk_bf16_f32 v75, v76, v77
	v_cvt_pk_bf16_f32 v76, v66, v67
	v_cvt_pk_bf16_f32 v77, v68, v69
	s_nop 1
	v_permlane16_swap_b32_e32 v74, v76
	v_permlane16_swap_b32_e32 v75, v77
	global_store_dwordx4 v[98:99], v[74:77], off offset:128
	v_add_u32_e32 v66, 0x80, v136
	v_mad_i64_i32 v[66:67], s[18:19], v66, s11, v[130:131]
	v_lshl_add_u64 v[66:67], v[66:67], 0, v[132:133]
	v_pk_mul_f32 v[138:139], v[62:63], s[100:101]
	v_pk_mul_f32 v[140:141], v[64:65], s[100:101]
	v_pk_mul_f32 v[142:143], v[54:55], s[100:101]
	v_pk_mul_f32 v[144:145], v[56:57], s[100:101]
	v_exp_f32_e32 v138, v138
	v_exp_f32_e32 v139, v139
	v_exp_f32_e32 v140, v140
	v_exp_f32_e32 v141, v141
	v_exp_f32_e32 v142, v142
	v_exp_f32_e32 v143, v143
	v_exp_f32_e32 v144, v144
	v_exp_f32_e32 v145, v145
	v_pk_add_f32 v[138:139], v[138:139], 1.0 op_sel_hi:[1,0]
	v_pk_add_f32 v[140:141], v[140:141], 1.0 op_sel_hi:[1,0]
	v_pk_add_f32 v[142:143], v[142:143], 1.0 op_sel_hi:[1,0]
	v_pk_add_f32 v[144:145], v[144:145], 1.0 op_sel_hi:[1,0]
	v_rcp_f32_e32 v138, v138
	v_rcp_f32_e32 v139, v139
	v_rcp_f32_e32 v140, v140
	v_rcp_f32_e32 v141, v141
	v_rcp_f32_e32 v142, v142
	v_rcp_f32_e32 v143, v143
	v_rcp_f32_e32 v144, v144
	v_rcp_f32_e32 v145, v145
	v_pk_mul_f32 v[62:63], v[62:63], v[138:139]
	v_pk_mul_f32 v[64:65], v[64:65], v[140:141]
	v_pk_mul_f32 v[54:55], v[54:55], v[142:143]
	v_pk_mul_f32 v[56:57], v[56:57], v[144:145]
	v_pk_mul_f32 v[58:59], v[58:59], v[62:63]
	v_pk_mul_f32 v[60:61], v[60:61], v[64:65]
	v_pk_mul_f32 v[50:51], v[50:51], v[54:55]
	v_pk_mul_f32 v[52:53], v[52:53], v[56:57]
	v_cvt_pk_bf16_f32 v58, v58, v59
	v_cvt_pk_bf16_f32 v59, v60, v61
	v_cvt_pk_bf16_f32 v60, v50, v51
	v_cvt_pk_bf16_f32 v61, v52, v53
	s_nop 1
	v_permlane16_swap_b32_e32 v58, v60
	v_permlane16_swap_b32_e32 v59, v61
	global_store_dwordx4 v[66:67], v[58:61], off
	v_pk_mul_f32 v[138:139], v[46:47], s[100:101]
	v_pk_mul_f32 v[140:141], v[48:49], s[100:101]
	v_pk_mul_f32 v[142:143], v[38:39], s[100:101]
	v_pk_mul_f32 v[144:145], v[40:41], s[100:101]
	v_exp_f32_e32 v138, v138
	v_exp_f32_e32 v139, v139
	v_exp_f32_e32 v140, v140
	v_exp_f32_e32 v141, v141
	v_exp_f32_e32 v142, v142
	v_exp_f32_e32 v143, v143
	v_exp_f32_e32 v144, v144
	v_exp_f32_e32 v145, v145
	v_pk_add_f32 v[138:139], v[138:139], 1.0 op_sel_hi:[1,0]
	v_pk_add_f32 v[140:141], v[140:141], 1.0 op_sel_hi:[1,0]
	v_pk_add_f32 v[142:143], v[142:143], 1.0 op_sel_hi:[1,0]
	v_pk_add_f32 v[144:145], v[144:145], 1.0 op_sel_hi:[1,0]
	v_rcp_f32_e32 v138, v138
	v_rcp_f32_e32 v139, v139
	v_rcp_f32_e32 v140, v140
	v_rcp_f32_e32 v141, v141
	v_rcp_f32_e32 v142, v142
; __device__ __forceinline__ unsigned cvt_pk_bf16(float lo, float hi) { unsigned r; asm volatile("v_cvt_pk_bf16_f32 %0, %1, %2" : "=v"(r) : "v"(lo), "v"(hi)); return r; }
; #define PG8_BAR __builtin_amdgcn_s_barrier()
; #define GAS __attribute__((address_space(1)))
; __device__ __forceinline__ float siluf_(float x) { return x * sigmoidf_(x); }
; template <class Epi, class Sched, bool ALIGN_EPI = false, bool SP2 = false>
; __device__ __forceinline__ void gemm_phase(PG8_LAS unsigned char* lds, const Gemm g, const Sched& S, const Epi& E, const int wave_id) {
;     ...
;         cur = nxt; cA = nA; cB = nB; ++ui;
;         if constexpr (ALIGN_EPI) { if (wr == 1) PG8_BAR; }
;     __device__ __forceinline__ bool operator()(AccT& acc, const Unit& u, int wr, int wc, int fr, int fq) const {
;     ...
;         for (int ai = 0; ai < 2; ++ai)
; #pragma unroll
;             for (int mp = 0; mp < 2; ++mp) { bf16* rowp = act + (size_t)(row0 + ai * 128 + mp * 32) * DFF + col0;
; #pragma unroll
;                 for (int bj = 0; bj < 2; ++bj) { unsigned pk[2][2];
; #pragma unroll
;                     for (int k = 0; k < 2; ++k) { const f32x4 g = acc[ai][bj][2 * mp + k][0], up = acc[ai][bj][2 * mp + k][1];
;                         pk[k][0] = pg8::cvt_pk_bf16(siluf_(g[0]) * up[0], siluf_(g[1]) * up[1]); pk[k][1] = pg8::cvt_pk_bf16(siluf_(g[2]) * up[2], siluf_(g[3]) * up[3]); }
;                     const auto sx = __builtin_amdgcn_permlane16_swap(pk[0][0], pk[1][0], false, false), sy = __builtin_amdgcn_permlane16_swap(pk[0][1], pk[1][1], false, false);
;                     *(GAS v4u*)(rowp + bj * 64) = (v4u){sx[0], sy[0], sx[1], sy[1]}; } }
	v_rcp_f32_e32 v143, v143
	v_rcp_f32_e32 v144, v144
	v_rcp_f32_e32 v145, v145
	v_pk_mul_f32 v[46:47], v[46:47], v[138:139]
	v_pk_mul_f32 v[48:49], v[48:49], v[140:141]
	v_pk_mul_f32 v[38:39], v[38:39], v[142:143]
	v_pk_mul_f32 v[40:41], v[40:41], v[144:145]
	v_pk_mul_f32 v[42:43], v[42:43], v[46:47]
	v_pk_mul_f32 v[44:45], v[44:45], v[48:49]
	v_pk_mul_f32 v[34:35], v[34:35], v[38:39]
	v_pk_mul_f32 v[36:37], v[36:37], v[40:41]
	v_cvt_pk_bf16_f32 v42, v42, v43
	v_cvt_pk_bf16_f32 v43, v44, v45
	v_cvt_pk_bf16_f32 v44, v34, v35
	v_cvt_pk_bf16_f32 v45, v36, v37
	s_nop 1
	v_permlane16_swap_b32_e32 v42, v44
	v_permlane16_swap_b32_e32 v43, v45
	global_store_dwordx4 v[66:67], v[42:45], off offset:128
	v_add_u32_e32 v34, 0xa0, v136
	v_mad_i64_i32 v[34:35], s[18:19], v34, s11, v[130:131]
	v_lshl_add_u64 v[34:35], v[34:35], 0, v[132:133]
	s_mov_b64 s[18:19], -1
	v_pk_mul_f32 v[138:139], v[30:31], s[100:101]
	v_pk_mul_f32 v[140:141], v[32:33], s[100:101]
	v_pk_mul_f32 v[142:143], v[22:23], s[100:101]
	v_pk_mul_f32 v[144:145], v[24:25], s[100:101]
	v_exp_f32_e32 v138, v138
	v_exp_f32_e32 v139, v139
	v_exp_f32_e32 v140, v140
	v_exp_f32_e32 v141, v141
	v_exp_f32_e32 v142, v142
	v_exp_f32_e32 v143, v143
	v_exp_f32_e32 v144, v144
	v_exp_f32_e32 v145, v145
	v_pk_add_f32 v[138:139], v[138:139], 1.0 op_sel_hi:[1,0]
	v_pk_add_f32 v[140:141], v[140:141], 1.0 op_sel_hi:[1,0]
	v_pk_add_f32 v[142:143], v[142:143], 1.0 op_sel_hi:[1,0]
	v_pk_add_f32 v[144:145], v[144:145], 1.0 op_sel_hi:[1,0]
	v_rcp_f32_e32 v138, v138
	v_rcp_f32_e32 v139, v139
	v_rcp_f32_e32 v140, v140
	v_rcp_f32_e32 v141, v141
	v_rcp_f32_e32 v142, v142
	v_rcp_f32_e32 v143, v143
	v_rcp_f32_e32 v144, v144
	v_rcp_f32_e32 v145, v145
	v_pk_mul_f32 v[30:31], v[30:31], v[138:139]
	v_pk_mul_f32 v[32:33], v[32:33], v[140:141]
	v_pk_mul_f32 v[22:23], v[22:23], v[142:143]
	v_pk_mul_f32 v[24:25], v[24:25], v[144:145]
	v_pk_mul_f32 v[26:27], v[26:27], v[30:31]
	v_pk_mul_f32 v[28:29], v[28:29], v[32:33]
	v_pk_mul_f32 v[18:19], v[18:19], v[22:23]
	v_pk_mul_f32 v[20:21], v[20:21], v[24:25]
	v_cvt_pk_bf16_f32 v26, v26, v27
	v_cvt_pk_bf16_f32 v27, v28, v29
	v_cvt_pk_bf16_f32 v28, v18, v19
	v_cvt_pk_bf16_f32 v29, v20, v21
	s_nop 1
	v_permlane16_swap_b32_e32 v26, v28
	v_permlane16_swap_b32_e32 v27, v29
	global_store_dwordx4 v[34:35], v[26:29], off
	v_pk_mul_f32 v[138:139], v[14:15], s[100:101]
	v_pk_mul_f32 v[140:141], v[16:17], s[100:101]
	v_pk_mul_f32 v[142:143], v[6:7], s[100:101]
	v_pk_mul_f32 v[144:145], v[8:9], s[100:101]
	v_exp_f32_e32 v138, v138
	v_exp_f32_e32 v139, v139
	v_exp_f32_e32 v140, v140
	v_exp_f32_e32 v141, v141
	v_exp_f32_e32 v142, v142
	v_exp_f32_e32 v143, v143
	v_exp_f32_e32 v144, v144
	v_exp_f32_e32 v145, v145
	v_pk_add_f32 v[138:139], v[138:139], 1.0 op_sel_hi:[1,0]
	v_pk_add_f32 v[140:141], v[140:141], 1.0 op_sel_hi:[1,0]
	v_pk_add_f32 v[142:143], v[142:143], 1.0 op_sel_hi:[1,0]
	v_pk_add_f32 v[144:145], v[144:145], 1.0 op_sel_hi:[1,0]
	v_rcp_f32_e32 v138, v138
	v_rcp_f32_e32 v139, v139
	v_rcp_f32_e32 v140, v140
	v_rcp_f32_e32 v141, v141
	v_rcp_f32_e32 v142, v142
	v_rcp_f32_e32 v143, v143
	v_rcp_f32_e32 v144, v144
	v_rcp_f32_e32 v145, v145
	v_pk_mul_f32 v[14:15], v[14:15], v[138:139]
	v_pk_mul_f32 v[16:17], v[16:17], v[140:141]
	v_pk_mul_f32 v[6:7], v[6:7], v[142:143]
	v_pk_mul_f32 v[8:9], v[8:9], v[144:145]
	v_pk_mul_f32 v[10:11], v[10:11], v[14:15]
	v_pk_mul_f32 v[12:13], v[12:13], v[16:17]
	v_pk_mul_f32 v[2:3], v[2:3], v[6:7]
	v_pk_mul_f32 v[4:5], v[4:5], v[8:9]
	v_cvt_pk_bf16_f32 v10, v10, v11
	v_cvt_pk_bf16_f32 v11, v12, v13
	v_cvt_pk_bf16_f32 v12, v2, v3
	v_cvt_pk_bf16_f32 v13, v4, v5
	s_nop 1
	v_permlane16_swap_b32_e32 v10, v12
	v_permlane16_swap_b32_e32 v11, v13
	global_store_dwordx4 v[34:35], v[10:13], off offset:128
	s_cbranch_vccnz .LBB0_149
	s_andn2_b64 vcc, exec, s[2:3]
	s_cbranch_vccnz .LBB0_148
	s_branch .LBB0_148

; #define PG8_STAGE(bufoff, gbase, voff) do { _Pragma("unroll") for (int _i = 0; _i < 2; ++_i) \
;         __builtin_amdgcn_global_load_lds((const unsigned*)((const char*)(gbase) + (voff)[_i]), (PG8_LAS unsigned*)(lds + (bufoff) + ldsw + _i * 8192), 16, 0, 0); } while (0)
; #define PG8_LDA(dst, b, h) do { _Pragma("unroll") for (int m = 0; m < 4; ++m) _Pragma("unroll") for (int k = 0; k < 2; ++k) dst[m][k] = *(const PG8_LAS bf16x8*)(lds + PG8_SA(b, h) + aoff + m * 2048 + k * 1024); } while (0)
; #define PG8_LDB(dst, b, h) do { _Pragma("unroll") for (int n = 0; n < 2; ++n) _Pragma("unroll") for (int k = 0; k < 2; ++k) dst[n][k] = *(const PG8_LAS bf16x8*)(lds + PG8_SB(b, h) + boff + n * 2048 + k * 1024); } while (0)
; #define PG8_MMA(ai, bj, At, Bt) do { __builtin_amdgcn_s_setprio(1); _Pragma("unroll") for (int m = 0; m < 4; ++m) _Pragma("unroll") for (int n = 0; n < 2; ++n) _Pragma("unroll") for (int k = 0; k < 2; ++k) \
;         acc[ai][bj][m][n] = __builtin_amdgcn_mfma_f32_16x16x32_bf16(Bt[n][k], At[m][k], acc[ai][bj][m][n], 0, 0, 0); __builtin_amdgcn_s_setprio(0); } while (0)
; #define PG8_WAIT_V(n) asm volatile("s_waitcnt vmcnt(" #n ")" ::: "memory")
; #define PG8_WAIT_VN(n) asm volatile("s_waitcnt vmcnt(%0)" :: "n"(n) : "memory")
; #define PG8_WAIT_L(n) asm volatile("s_waitcnt lgkmcnt(" #n ")" ::: "memory")
; #define PG8_BAR __builtin_amdgcn_s_barrier()
; template <class Epi, class Sched, bool ALIGN_EPI = false, bool SP2 = false>
; __device__ __forceinline__ void gemm_phase(PG8_LAS unsigned char* lds, const Gemm g, const Sched& S, const Epi& E, const int wave_id) {
;     ...
;             PG8_WAIT_VN(8 + Epi::NS); if (strict) PG8_WAIT_V(8); PG8_WAIT_L(0); PG8_BAR; PG8_MMA(1, 0, At, B0); PG8_MMA(1, 1, At, B1); PG8_BAR; PG8_SCHED;
;             PG8_LDB(B0, 1, 0); PG8_LDB(B1, 1, 1); PG8_SCHED; PG8_LDA(At, 1, 0); PG8_STAGE(PG8_SA(0, 1), a2 + hstep, voffA);
;             PG8_WAIT_V(8); PG8_WAIT_L(0); PG8_BAR; PG8_MMA(0, 0, At, B0); PG8_MMA(0, 1, At, B1); PG8_BAR; PG8_SCHED;
;     ...
;         for (int a = 0; a < 2; ++a)
; #pragma unroll
;             for (int b = 0; b < 2; ++b)
; #pragma unroll
;                 for (int m = 0; m < 4; ++m)
; #pragma unroll
;                     for (int n = 0; n < 2; ++n) acc[a][b][m][n] = (f32x4){0.f, 0.f, 0.f, 0.f};
;         }
;         cur = nxt; cA = nA; cB = nB; ++ui;
;         if constexpr (ALIGN_EPI) { if (wr == 1) PG8_BAR; }
.LBB0_234:
	s_cmp_eq_u32 s16, 0
	s_cselect_b64 s[16:17], -1, 0
	s_add_u32 s57, s14, 0x100
	s_addc_u32 s62, s15, 0
	s_add_u32 s14, s12, 0xb0080
	s_addc_u32 s15, s13, 0
	v_mov_b32_e32 v2, 0
	v_cndmask_b32_e64 v248, 0, 1, s[16:17]
	s_and_b32 s101, s16, 1
	v_lshl_add_u64 v[222:223], s[14:15], 0, v[218:219]
	v_lshl_add_u64 v[224:225], s[14:15], 0, v[220:221]
	s_mov_b32 s63, -2
	s_mov_b64 s[14:15], 0
	v_mov_b32_e32 v3, v2
	v_mov_b64_e32 v[4:5], 0
	v_mov_b64_e32 v[6:7], 0
	v_mov_b64_e32 v[8:9], 0
	v_mov_b64_e32 v[10:11], 0
	v_mov_b64_e32 v[12:13], 0
	v_mov_b64_e32 v[14:15], 0
	v_mov_b64_e32 v[16:17], 0
	v_mov_b64_e32 v[18:19], 0
	v_mov_b64_e32 v[20:21], 0
	v_mov_b64_e32 v[22:23], 0
	v_mov_b64_e32 v[24:25], 0
	v_mov_b64_e32 v[26:27], 0
	v_mov_b64_e32 v[28:29], 0
	v_mov_b64_e32 v[30:31], 0
	v_mov_b64_e32 v[32:33], 0
	v_mov_b64_e32 v[34:35], 0
	v_mov_b64_e32 v[36:37], 0
	v_mov_b64_e32 v[38:39], 0
	v_mov_b64_e32 v[40:41], 0
	v_mov_b64_e32 v[42:43], 0
	v_mov_b64_e32 v[44:45], 0
	v_mov_b64_e32 v[46:47], 0
	v_mov_b64_e32 v[48:49], 0
	v_mov_b64_e32 v[50:51], 0
	v_mov_b64_e32 v[52:53], 0
	v_mov_b64_e32 v[54:55], 0
	v_mov_b64_e32 v[56:57], 0
	v_mov_b64_e32 v[58:59], 0
	v_mov_b64_e32 v[60:61], 0
	v_mov_b64_e32 v[62:63], 0
	v_mov_b64_e32 v[64:65], 0
	v_mov_b64_e32 v[66:67], 0
	v_mov_b64_e32 v[68:69], 0
	v_mov_b64_e32 v[70:71], 0
	v_mov_b64_e32 v[72:73], 0
	v_mov_b64_e32 v[74:75], 0
	v_mov_b64_e32 v[76:77], 0
	v_mov_b64_e32 v[78:79], 0
	v_mov_b64_e32 v[80:81], 0
	v_mov_b64_e32 v[82:83], 0
	v_mov_b64_e32 v[84:85], 0
	v_mov_b64_e32 v[86:87], 0
	v_mov_b64_e32 v[88:89], 0
	v_mov_b64_e32 v[90:91], 0
	v_mov_b64_e32 v[92:93], 0
	v_mov_b64_e32 v[94:95], 0
	v_mov_b64_e32 v[96:97], 0
	v_mov_b64_e32 v[98:99], 0
	v_mov_b64_e32 v[100:101], 0
	v_mov_b64_e32 v[102:103], 0
	v_mov_b64_e32 v[104:105], 0
	v_mov_b64_e32 v[106:107], 0
	v_mov_b64_e32 v[108:109], 0
	v_mov_b64_e32 v[110:111], 0
	v_mov_b64_e32 v[112:113], 0
	v_mov_b64_e32 v[114:115], 0
	v_mov_b64_e32 v[116:117], 0
	v_mov_b64_e32 v[118:119], 0
	v_mov_b64_e32 v[120:121], 0
	v_mov_b64_e32 v[122:123], 0
	v_mov_b64_e32 v[124:125], 0
	v_mov_b64_e32 v[126:127], 0
	v_mov_b64_e32 v[128:129], 0
	s_cmp_eq_u32 s101, 0
	s_cbranch_scc0 .Lskew_skip_4
	s_andn2_b64 vcc, exec, s[2:3]
	s_cbranch_vccnz .Lskew_skip_4
	s_barrier
.Lskew_skip_4:
	s_branch .LBB0_236
.LBB0_235:
	s_waitcnt lgkmcnt(0)
	s_barrier
	s_setprio 1
	s_waitcnt lgkmcnt(0)
	v_mfma_f32_16x16x32_bf16 v[62:65], v[146:149], v[186:189], v[62:65]
	v_mfma_f32_16x16x32_bf16 v[58:61], v[154:157], v[186:189], v[58:61]
	v_mfma_f32_16x16x32_bf16 v[46:49], v[146:149], v[178:181], v[46:49]
	v_mfma_f32_16x16x32_bf16 v[42:45], v[154:157], v[178:181], v[42:45]
	v_mfma_f32_16x16x32_bf16 v[30:33], v[146:149], v[170:173], v[30:33]
	v_mfma_f32_16x16x32_bf16 v[26:29], v[154:157], v[170:173], v[26:29]
	v_mfma_f32_16x16x32_bf16 v[14:17], v[146:149], v[162:165], v[14:17]
	v_mfma_f32_16x16x32_bf16 v[10:13], v[154:157], v[162:165], v[10:13]
	v_mfma_f32_16x16x32_bf16 v[62:65], v[150:153], v[190:193], v[62:65]
	v_mfma_f32_16x16x32_bf16 v[58:61], v[158:161], v[190:193], v[58:61]
	v_mfma_f32_16x16x32_bf16 v[46:49], v[150:153], v[182:185], v[46:49]
	v_mfma_f32_16x16x32_bf16 v[42:45], v[158:161], v[182:185], v[42:45]
	v_mfma_f32_16x16x32_bf16 v[30:33], v[150:153], v[174:177], v[30:33]
	v_mfma_f32_16x16x32_bf16 v[26:29], v[158:161], v[174:177], v[26:29]
	v_mfma_f32_16x16x32_bf16 v[14:17], v[150:153], v[166:169], v[14:17]
	v_mfma_f32_16x16x32_bf16 v[10:13], v[158:161], v[166:169], v[10:13]
	s_setprio 0
	s_setprio 1
	v_mfma_f32_16x16x32_bf16 v[54:57], v[130:133], v[186:189], v[54:57]
	v_mfma_f32_16x16x32_bf16 v[50:53], v[138:141], v[186:189], v[50:53]
	v_mfma_f32_16x16x32_bf16 v[38:41], v[130:133], v[178:181], v[38:41]
	v_mfma_f32_16x16x32_bf16 v[34:37], v[138:141], v[178:181], v[34:37]
	v_mfma_f32_16x16x32_bf16 v[22:25], v[130:133], v[170:173], v[22:25]
	v_mfma_f32_16x16x32_bf16 v[18:21], v[138:141], v[170:173], v[18:21]
	v_mfma_f32_16x16x32_bf16 v[6:9], v[130:133], v[162:165], v[6:9]
	v_mfma_f32_16x16x32_bf16 v[2:5], v[138:141], v[162:165], v[2:5]
	v_mfma_f32_16x16x32_bf16 v[54:57], v[134:137], v[190:193], v[54:57]
	v_mfma_f32_16x16x32_bf16 v[50:53], v[142:145], v[190:193], v[50:53]
	v_mfma_f32_16x16x32_bf16 v[38:41], v[134:137], v[182:185], v[38:41]
	v_mfma_f32_16x16x32_bf16 v[34:37], v[142:145], v[182:185], v[34:37]
	v_mfma_f32_16x16x32_bf16 v[22:25], v[134:137], v[174:177], v[22:25]
	v_mfma_f32_16x16x32_bf16 v[18:21], v[142:145], v[174:177], v[18:21]
	v_mfma_f32_16x16x32_bf16 v[6:9], v[134:137], v[166:169], v[6:9]
	v_mfma_f32_16x16x32_bf16 v[2:5], v[142:145], v[166:169], v[2:5]
	s_setprio 0
	s_barrier
	s_add_i32 s20, 0, 0x18000
	s_add_i32 s21, 0, 0x1c000
	v_add_u32_e32 v142, s20, v246
	v_add_u32_e32 v158, s21, v246
	ds_read_b128 v[130:133], v142
	ds_read_b128 v[134:137], v142 offset:1024
	ds_read_b128 v[138:141], v142 offset:2048
	ds_read_b128 v[142:145], v142 offset:3072
	ds_read_b128 v[146:149], v158
	ds_read_b128 v[150:153], v158 offset:1024
	ds_read_b128 v[154:157], v158 offset:2048
	ds_read_b128 v[158:161], v158 offset:3072
	s_add_u32 s18, s18, 0xb0000
	s_addc_u32 s19, s19, 0
	s_mov_b32 m0, s39
	v_lshl_add_u64 v[194:195], s[18:19], 0, v[210:211]
	ds_read_b128 v[162:165], v247 offset:32768
	ds_read_b128 v[166:169], v247 offset:33792
	ds_read_b128 v[170:173], v247 offset:34816
	ds_read_b128 v[174:177], v247 offset:35840
	ds_read_b128 v[178:181], v247 offset:36864
	ds_read_b128 v[182:185], v247 offset:37888
	ds_read_b128 v[186:189], v247 offset:38912
	ds_read_b128 v[190:193], v247 offset:39936
	global_load_lds_dwordx4 v[194:195], off
	v_lshl_add_u64 v[194:195], s[18:19], 0, v[214:215]
	s_mov_b32 m0, s40
	s_nop 0
	global_load_lds_dwordx4 v[194:195], off
	s_waitcnt vmcnt(26)
	s_cmp_eq_u32 s100, 0
	s_cbranch_scc1 .Lthird_wait_relaxed_5
	s_waitcnt vmcnt(8)

; #define GAS __attribute__((address_space(1)))
; __device__ __forceinline__ v4u tr4(int a, v4u x) { return (v4u){bperm(a, x.x), bperm(a, x.y), bperm(a, x.z), bperm(a, x.w)}; }
; __device__ __forceinline__ v4u pack8(const f32x4& a, const f32x4& b) { return (v4u){pg8::cvt_pk_bf16(a[0], a[1]), pg8::cvt_pk_bf16(a[2], a[3]), pg8::cvt_pk_bf16(b[0], b[1]), pg8::cvt_pk_bf16(b[2], b[3])}; }
;     __device__ __forceinline__ bool operator()(AccT& acc, const Unit& u, int wr, int wc, int fr, int fq) const {
;     ...
;         const LaneT t = lane_t(fr, fq);
;         const bf16* src = (const bf16*)(ws + WS_HB); bf16* dst = (bf16*)(ws + WS_YB);
;         const int row0 = u.pm * 256 + wr * 64 + t.tfr, col0 = u.pn * 256 + wc * 32 + 8 * t.tfq;
; #pragma unroll
;         for (int ai = 0; ai < 2; ++ai)
; #pragma unroll
;             for (int m = 0; m < 4; ++m) { const size_t off = (size_t)(row0 + ai * 128 + m * 16) * D + col0;
; #pragma unroll
;                 for (int bj = 0; bj < 2; ++bj) { const v4u r = tr4(t.push, *(const GAS v4u*)(src + off + bj * 128));
;                     const f32x4 y0 = (f32x4){bflo(r.x), bfhi(r.x), bflo(r.y), bfhi(r.y)} * ca + acc[ai][bj][m][0] * cb, y1 = (f32x4){bflo(r.z), bfhi(r.z), bflo(r.w), bfhi(r.w)} * ca + acc[ai][bj][m][1] * cb;
;                     *(GAS v4u*)(dst + off + bj * 128) = tr4(t.pull, pack8(y0, y1)); } }
.LBB0_242:
	s_add_u32 s100, s6, 0xb0080
	s_addc_u32 s101, s7, 0
	v_lshl_add_u64 v[194:195], s[100:101], 0, v[220:221]
	s_add_i32 m0, s31, 0xc000
	s_nop 0
	global_load_lds_dwordx4 v[194:195], off
	v_lshl_add_u64 v[194:195], s[100:101], 0, v[218:219]
	s_add_i32 m0, s31, 0xe000
	s_nop 0
	global_load_lds_dwordx4 v[194:195], off
	s_mov_b32 s12, s41
	v_mov_b32_e32 v130, v1
	s_mov_b32 s13, s29
	v_mov_b32_e32 v131, v245
	s_lshl_b32 s14, s54, 8
	v_lshl_add_u32 v132, v130, 4, v131
	s_lshl_b32 s13, s13, 6
	v_ashrrev_i32_e32 v134, 2, v132
	v_and_b32_e32 v135, 3, v131
	v_lshlrev_b32_e32 v131, 4, v131
	s_add_i32 s13, s13, s14
	v_lshl_add_u32 v133, v130, 2, v131
	v_add_u32_e32 v130, s13, v134
	s_lshl_b32 s13, s56, 8
	s_lshl_b32 s12, s12, 5
	s_add_i32 s12, s12, s13
	v_and_b32_e32 v132, -4, v132
	v_lshl_or_b32 v134, v135, 3, s12
	v_ashrrev_i32_e32 v131, 31, v130
	v_lshl_add_u32 v132, v135, 6, v132
	v_ashrrev_i32_e32 v135, 31, v134
	v_lshlrev_b64 v[130:131], 10, v[130:131]
	v_lshl_add_u64 v[130:131], v[130:131], 0, v[134:135]
	v_readlane_b32 s14, v253, 11
	v_lshlrev_b64 v[130:131], 1, v[130:131]
	v_readlane_b32 s15, v253, 12
	v_lshl_add_u64 v[140:141], s[60:61], 0, v[130:131]
	s_mov_b64 s[12:13], 0x8000
	v_lshl_add_u64 v[138:139], s[14:15], 0, v[130:131]
	v_mov_b64_e32 v[130:131], v[138:139]
	global_load_dwordx4 v[146:149], v[130:131], off
	s_and_b64 vcc, exec, s[4:5]
	global_load_dwordx4 v[150:153], v[130:131], off offset:256
	s_mov_b64 s[12:13], 0x8000
	v_lshl_add_u64 v[130:131], v[138:139], 0, s[12:13]
	global_load_dwordx4 v[154:157], v[130:131], off
	global_load_dwordx4 v[158:161], v[130:131], off offset:256
	s_mov_b64 s[12:13], 0x10000
	v_lshl_add_u64 v[130:131], v[138:139], 0, s[12:13]
	global_load_dwordx4 v[162:165], v[130:131], off
	global_load_dwordx4 v[166:169], v[130:131], off offset:256
	s_mov_b64 s[12:13], 0x18000
	v_lshl_add_u64 v[130:131], v[138:139], 0, s[12:13]
	global_load_dwordx4 v[170:173], v[130:131], off
	global_load_dwordx4 v[174:177], v[130:131], off offset:256
	s_mov_b64 s[12:13], 0x40000
	v_lshl_add_u64 v[130:131], v[138:139], 0, s[12:13]
	global_load_dwordx4 v[178:181], v[130:131], off
	global_load_dwordx4 v[182:185], v[130:131], off offset:256
	s_mov_b64 s[12:13], 0x48000
	v_lshl_add_u64 v[130:131], v[138:139], 0, s[12:13]
	global_load_dwordx4 v[186:189], v[130:131], off
	global_load_dwordx4 v[190:193], v[130:131], off offset:256
	s_waitcnt vmcnt(11)
	ds_bpermute_b32 v143, v133, v147
	ds_bpermute_b32 v142, v133, v146
	ds_bpermute_b32 v145, v133, v149
	ds_bpermute_b32 v144, v133, v148
	v_mov_b64_e32 v[134:135], v[140:141]
	s_waitcnt lgkmcnt(3)
	v_lshlrev_b32_e32 v136, 16, v143
	v_and_b32_e32 v137, 0xffff0000, v143
	s_waitcnt lgkmcnt(2)
	v_and_b32_e32 v143, 0xffff0000, v142
	v_lshlrev_b32_e32 v142, 16, v142
	v_pk_mul_f32 v[136:137], v[136:137], s[96:97] op_sel_hi:[1,0]
	v_pk_fma_f32 v[128:129], v[128:129], 0.5, v[136:137] op_sel_hi:[1,0,1]
	v_pk_mul_f32 v[142:143], v[142:143], s[96:97] op_sel_hi:[1,0]
	v_pk_fma_f32 v[126:127], v[126:127], 0.5, v[142:143] op_sel_hi:[1,0,1]
	s_waitcnt lgkmcnt(1)
	v_lshlrev_b32_e32 v136, 16, v145
	v_and_b32_e32 v137, 0xffff0000, v145
	s_waitcnt lgkmcnt(0)
	v_and_b32_e32 v145, 0xffff0000, v144
	v_lshlrev_b32_e32 v144, 16, v144
	v_pk_mul_f32 v[136:137], v[136:137], s[96:97] op_sel_hi:[1,0]
	v_pk_fma_f32 v[124:125], v[124:125], 0.5, v[136:137] op_sel_hi:[1,0,1]
	v_pk_mul_f32 v[144:145], v[144:145], s[96:97] op_sel_hi:[1,0]
	v_pk_fma_f32 v[122:123], v[122:123], 0.5, v[144:145] op_sel_hi:[1,0,1]
	v_cvt_pk_bf16_f32 v126, v126, v127
	v_cvt_pk_bf16_f32 v127, v128, v129
	v_cvt_pk_bf16_f32 v128, v122, v123
	v_cvt_pk_bf16_f32 v125, v124, v125
	s_nop 1
	ds_bpermute_b32 v122, v132, v126
	ds_bpermute_b32 v123, v132, v127
	ds_bpermute_b32 v124, v132, v128
	ds_bpermute_b32 v125, v132, v125
	s_waitcnt lgkmcnt(0)
	global_store_dwordx4 v[134:135], v[122:125], off
	s_mov_b64 s[12:13], 0x50000
	v_lshl_add_u64 v[130:131], v[138:139], 0, s[12:13]
	global_load_dwordx4 v[126:129], v[130:131], off
	s_waitcnt vmcnt(12)
	ds_bpermute_b32 v143, v133, v151
	ds_bpermute_b32 v142, v133, v150
	ds_bpermute_b32 v145, v133, v153
	ds_bpermute_b32 v144, v133, v152
	s_waitcnt lgkmcnt(3)
	v_lshlrev_b32_e32 v136, 16, v143
	v_and_b32_e32 v137, 0xffff0000, v143
	s_waitcnt lgkmcnt(2)
	v_and_b32_e32 v143, 0xffff0000, v142
	v_lshlrev_b32_e32 v142, 16, v142
	v_pk_mul_f32 v[136:137], v[136:137], s[96:97] op_sel_hi:[1,0]
	v_pk_fma_f32 v[120:121], v[120:121], 0.5, v[136:137] op_sel_hi:[1,0,1]
	v_pk_mul_f32 v[142:143], v[142:143], s[96:97] op_sel_hi:[1,0]
	v_pk_fma_f32 v[118:119], v[118:119], 0.5, v[142:143] op_sel_hi:[1,0,1]
	s_waitcnt lgkmcnt(1)
	v_lshlrev_b32_e32 v136, 16, v145
	v_and_b32_e32 v137, 0xffff0000, v145
	s_waitcnt lgkmcnt(0)
	v_and_b32_e32 v145, 0xffff0000, v144
	v_lshlrev_b32_e32 v144, 16, v144
	v_pk_mul_f32 v[136:137], v[136:137], s[96:97] op_sel_hi:[1,0]
	v_pk_fma_f32 v[116:117], v[116:117], 0.5, v[136:137] op_sel_hi:[1,0,1]
	v_pk_mul_f32 v[144:145], v[144:145], s[96:97] op_sel_hi:[1,0]
	v_pk_fma_f32 v[114:115], v[114:115], 0.5, v[144:145] op_sel_hi:[1,0,1]
	v_cvt_pk_bf16_f32 v118, v118, v119
	v_cvt_pk_bf16_f32 v119, v120, v121
	v_cvt_pk_bf16_f32 v120, v114, v115
	v_cvt_pk_bf16_f32 v117, v116, v117
	s_nop 1
	ds_bpermute_b32 v114, v132, v118
	ds_bpermute_b32 v115, v132, v119
	ds_bpermute_b32 v116, v132, v120
	ds_bpermute_b32 v117, v132, v117
	s_waitcnt lgkmcnt(0)
	global_store_dwordx4 v[134:135], v[114:117], off offset:256
	global_load_dwordx4 v[118:121], v[130:131], off offset:256
	s_waitcnt vmcnt(13)
	ds_bpermute_b32 v143, v133, v155
	ds_bpermute_b32 v142, v133, v154
	ds_bpermute_b32 v145, v133, v157
	ds_bpermute_b32 v144, v133, v156
	s_mov_b64 s[12:13], 0x8000
	v_lshl_add_u64 v[134:135], v[140:141], 0, s[12:13]
	s_waitcnt lgkmcnt(3)
; #define GAS __attribute__((address_space(1)))
; __device__ __forceinline__ v4u tr4(int a, v4u x) { return (v4u){bperm(a, x.x), bperm(a, x.y), bperm(a, x.z), bperm(a, x.w)}; }
; __device__ __forceinline__ v4u pack8(const f32x4& a, const f32x4& b) { return (v4u){pg8::cvt_pk_bf16(a[0], a[1]), pg8::cvt_pk_bf16(a[2], a[3]), pg8::cvt_pk_bf16(b[0], b[1]), pg8::cvt_pk_bf16(b[2], b[3])}; }
;     __device__ __forceinline__ bool operator()(AccT& acc, const Unit& u, int wr, int wc, int fr, int fq) const {
;     ...
;             for (int m = 0; m < 4; ++m) { const size_t off = (size_t)(row0 + ai * 128 + m * 16) * D + col0;
; #pragma unroll
;                 for (int bj = 0; bj < 2; ++bj) { const v4u r = tr4(t.push, *(const GAS v4u*)(src + off + bj * 128));
;                     const f32x4 y0 = (f32x4){bflo(r.x), bfhi(r.x), bflo(r.y), bfhi(r.y)} * ca + acc[ai][bj][m][0] * cb, y1 = (f32x4){bflo(r.z), bfhi(r.z), bflo(r.w), bfhi(r.w)} * ca + acc[ai][bj][m][1] * cb;
;                     *(GAS v4u*)(dst + off + bj * 128) = tr4(t.pull, pack8(y0, y1)); } }
	v_lshlrev_b32_e32 v136, 16, v143
	v_and_b32_e32 v137, 0xffff0000, v143
	s_waitcnt lgkmcnt(2)
	v_and_b32_e32 v143, 0xffff0000, v142
	v_lshlrev_b32_e32 v142, 16, v142
	v_pk_mul_f32 v[136:137], v[136:137], s[96:97] op_sel_hi:[1,0]
	v_pk_fma_f32 v[112:113], v[112:113], 0.5, v[136:137] op_sel_hi:[1,0,1]
	v_pk_mul_f32 v[142:143], v[142:143], s[96:97] op_sel_hi:[1,0]
	v_pk_fma_f32 v[110:111], v[110:111], 0.5, v[142:143] op_sel_hi:[1,0,1]
	s_waitcnt lgkmcnt(1)
	v_lshlrev_b32_e32 v136, 16, v145
	v_and_b32_e32 v137, 0xffff0000, v145
	s_waitcnt lgkmcnt(0)
	v_and_b32_e32 v145, 0xffff0000, v144
	v_lshlrev_b32_e32 v144, 16, v144
	v_pk_mul_f32 v[136:137], v[136:137], s[96:97] op_sel_hi:[1,0]
	v_pk_fma_f32 v[108:109], v[108:109], 0.5, v[136:137] op_sel_hi:[1,0,1]
	v_pk_mul_f32 v[144:145], v[144:145], s[96:97] op_sel_hi:[1,0]
	v_pk_fma_f32 v[106:107], v[106:107], 0.5, v[144:145] op_sel_hi:[1,0,1]
	v_cvt_pk_bf16_f32 v110, v110, v111
	v_cvt_pk_bf16_f32 v111, v112, v113
	v_cvt_pk_bf16_f32 v112, v106, v107
	v_cvt_pk_bf16_f32 v109, v108, v109
	s_nop 1
	ds_bpermute_b32 v106, v132, v110
	ds_bpermute_b32 v107, v132, v111
	ds_bpermute_b32 v108, v132, v112
	ds_bpermute_b32 v109, v132, v109
	s_waitcnt lgkmcnt(0)
	global_store_dwordx4 v[134:135], v[106:109], off
	s_mov_b64 s[12:13], 0x58000
	v_lshl_add_u64 v[130:131], v[138:139], 0, s[12:13]
	global_load_dwordx4 v[110:113], v[130:131], off
	s_waitcnt vmcnt(14)
	ds_bpermute_b32 v143, v133, v159
	ds_bpermute_b32 v142, v133, v158
	ds_bpermute_b32 v145, v133, v161
	ds_bpermute_b32 v144, v133, v160
	s_waitcnt lgkmcnt(3)
	v_lshlrev_b32_e32 v136, 16, v143
	v_and_b32_e32 v137, 0xffff0000, v143
	s_waitcnt lgkmcnt(2)
	v_and_b32_e32 v143, 0xffff0000, v142
	v_lshlrev_b32_e32 v142, 16, v142
	v_pk_mul_f32 v[136:137], v[136:137], s[96:97] op_sel_hi:[1,0]
	v_pk_fma_f32 v[104:105], v[104:105], 0.5, v[136:137] op_sel_hi:[1,0,1]
	v_pk_mul_f32 v[142:143], v[142:143], s[96:97] op_sel_hi:[1,0]
	v_pk_fma_f32 v[102:103], v[102:103], 0.5, v[142:143] op_sel_hi:[1,0,1]
	s_waitcnt lgkmcnt(1)
	v_lshlrev_b32_e32 v136, 16, v145
	v_and_b32_e32 v137, 0xffff0000, v145
	s_waitcnt lgkmcnt(0)
	v_and_b32_e32 v145, 0xffff0000, v144
	v_lshlrev_b32_e32 v144, 16, v144
	v_pk_mul_f32 v[136:137], v[136:137], s[96:97] op_sel_hi:[1,0]
	v_pk_fma_f32 v[100:101], v[100:101], 0.5, v[136:137] op_sel_hi:[1,0,1]
	v_pk_mul_f32 v[144:145], v[144:145], s[96:97] op_sel_hi:[1,0]
	v_pk_fma_f32 v[98:99], v[98:99], 0.5, v[144:145] op_sel_hi:[1,0,1]
	v_cvt_pk_bf16_f32 v102, v102, v103
	v_cvt_pk_bf16_f32 v103, v104, v105
	v_cvt_pk_bf16_f32 v104, v98, v99
	v_cvt_pk_bf16_f32 v101, v100, v101
	s_nop 1
	ds_bpermute_b32 v98, v132, v102
	ds_bpermute_b32 v99, v132, v103
	ds_bpermute_b32 v100, v132, v104
	ds_bpermute_b32 v101, v132, v101
	s_waitcnt lgkmcnt(0)
	global_store_dwordx4 v[134:135], v[98:101], off offset:256
	global_load_dwordx4 v[102:105], v[130:131], off offset:256
	s_waitcnt vmcnt(15)
	ds_bpermute_b32 v143, v133, v163
	ds_bpermute_b32 v142, v133, v162
	ds_bpermute_b32 v145, v133, v165
	ds_bpermute_b32 v144, v133, v164
	s_mov_b64 s[12:13], 0x10000
	v_lshl_add_u64 v[134:135], v[140:141], 0, s[12:13]
	s_waitcnt lgkmcnt(3)
	v_lshlrev_b32_e32 v136, 16, v143
	v_and_b32_e32 v137, 0xffff0000, v143
	s_waitcnt lgkmcnt(2)
	v_and_b32_e32 v143, 0xffff0000, v142
	v_lshlrev_b32_e32 v142, 16, v142
	v_pk_mul_f32 v[136:137], v[136:137], s[96:97] op_sel_hi:[1,0]
	v_pk_fma_f32 v[96:97], v[96:97], 0.5, v[136:137] op_sel_hi:[1,0,1]
	v_pk_mul_f32 v[142:143], v[142:143], s[96:97] op_sel_hi:[1,0]
	v_pk_fma_f32 v[94:95], v[94:95], 0.5, v[142:143] op_sel_hi:[1,0,1]
	s_waitcnt lgkmcnt(1)
	v_lshlrev_b32_e32 v136, 16, v145
	v_and_b32_e32 v137, 0xffff0000, v145
	s_waitcnt lgkmcnt(0)
	v_and_b32_e32 v145, 0xffff0000, v144
	v_lshlrev_b32_e32 v144, 16, v144
	v_pk_mul_f32 v[136:137], v[136:137], s[96:97] op_sel_hi:[1,0]
	v_pk_fma_f32 v[92:93], v[92:93], 0.5, v[136:137] op_sel_hi:[1,0,1]
	v_pk_mul_f32 v[144:145], v[144:145], s[96:97] op_sel_hi:[1,0]
	v_pk_fma_f32 v[90:91], v[90:91], 0.5, v[144:145] op_sel_hi:[1,0,1]
	v_cvt_pk_bf16_f32 v94, v94, v95
	v_cvt_pk_bf16_f32 v95, v96, v97
	v_cvt_pk_bf16_f32 v96, v90, v91
	v_cvt_pk_bf16_f32 v93, v92, v93
	s_nop 1
	ds_bpermute_b32 v90, v132, v94
	ds_bpermute_b32 v91, v132, v95
	ds_bpermute_b32 v92, v132, v96
	ds_bpermute_b32 v93, v132, v93
	s_waitcnt lgkmcnt(0)
	global_store_dwordx4 v[134:135], v[90:93], off
	s_waitcnt vmcnt(15)
	ds_bpermute_b32 v143, v133, v167
	ds_bpermute_b32 v142, v133, v166
	ds_bpermute_b32 v145, v133, v169
	ds_bpermute_b32 v144, v133, v168
	s_waitcnt lgkmcnt(3)
	v_lshlrev_b32_e32 v136, 16, v143
	v_and_b32_e32 v137, 0xffff0000, v143
	s_waitcnt lgkmcnt(2)
	v_and_b32_e32 v143, 0xffff0000, v142
	v_lshlrev_b32_e32 v142, 16, v142
	v_pk_mul_f32 v[136:137], v[136:137], s[96:97] op_sel_hi:[1,0]
	v_pk_fma_f32 v[88:89], v[88:89], 0.5, v[136:137] op_sel_hi:[1,0,1]
	v_pk_mul_f32 v[142:143], v[142:143], s[96:97] op_sel_hi:[1,0]
	v_pk_fma_f32 v[86:87], v[86:87], 0.5, v[142:143] op_sel_hi:[1,0,1]
	s_waitcnt lgkmcnt(1)
	v_lshlrev_b32_e32 v136, 16, v145
	v_and_b32_e32 v137, 0xffff0000, v145
	s_waitcnt lgkmcnt(0)
	v_and_b32_e32 v145, 0xffff0000, v144
	v_lshlrev_b32_e32 v144, 16, v144
	v_pk_mul_f32 v[136:137], v[136:137], s[96:97] op_sel_hi:[1,0]
	v_pk_fma_f32 v[84:85], v[84:85], 0.5, v[136:137] op_sel_hi:[1,0,1]
	v_pk_mul_f32 v[144:145], v[144:145], s[96:97] op_sel_hi:[1,0]
	v_pk_fma_f32 v[82:83], v[82:83], 0.5, v[144:145] op_sel_hi:[1,0,1]
	v_cvt_pk_bf16_f32 v86, v86, v87
	v_cvt_pk_bf16_f32 v87, v88, v89
	v_cvt_pk_bf16_f32 v88, v82, v83
	v_cvt_pk_bf16_f32 v85, v84, v85
	s_nop 1
	ds_bpermute_b32 v82, v132, v86
	ds_bpermute_b32 v83, v132, v87
	ds_bpermute_b32 v84, v132, v88
	ds_bpermute_b32 v85, v132, v85
	s_waitcnt lgkmcnt(0)
; #define GAS __attribute__((address_space(1)))
; __device__ __forceinline__ v4u tr4(int a, v4u x) { return (v4u){bperm(a, x.x), bperm(a, x.y), bperm(a, x.z), bperm(a, x.w)}; }
; __device__ __forceinline__ v4u pack8(const f32x4& a, const f32x4& b) { return (v4u){pg8::cvt_pk_bf16(a[0], a[1]), pg8::cvt_pk_bf16(a[2], a[3]), pg8::cvt_pk_bf16(b[0], b[1]), pg8::cvt_pk_bf16(b[2], b[3])}; }
;     __device__ __forceinline__ bool operator()(AccT& acc, const Unit& u, int wr, int wc, int fr, int fq) const {
;     ...
;             for (int m = 0; m < 4; ++m) { const size_t off = (size_t)(row0 + ai * 128 + m * 16) * D + col0;
; #pragma unroll
;                 for (int bj = 0; bj < 2; ++bj) { const v4u r = tr4(t.push, *(const GAS v4u*)(src + off + bj * 128));
;                     const f32x4 y0 = (f32x4){bflo(r.x), bfhi(r.x), bflo(r.y), bfhi(r.y)} * ca + acc[ai][bj][m][0] * cb, y1 = (f32x4){bflo(r.z), bfhi(r.z), bflo(r.w), bfhi(r.w)} * ca + acc[ai][bj][m][1] * cb;
;                     *(GAS v4u*)(dst + off + bj * 128) = tr4(t.pull, pack8(y0, y1)); } }
	global_store_dwordx4 v[134:135], v[82:85], off offset:256
	s_waitcnt vmcnt(15)
	ds_bpermute_b32 v143, v133, v171
	ds_bpermute_b32 v142, v133, v170
	ds_bpermute_b32 v145, v133, v173
	ds_bpermute_b32 v144, v133, v172
	s_mov_b64 s[12:13], 0x18000
	v_lshl_add_u64 v[134:135], v[140:141], 0, s[12:13]
	s_waitcnt lgkmcnt(3)
	v_lshlrev_b32_e32 v136, 16, v143
	v_and_b32_e32 v137, 0xffff0000, v143
	s_waitcnt lgkmcnt(2)
	v_and_b32_e32 v143, 0xffff0000, v142
	v_lshlrev_b32_e32 v142, 16, v142
	v_pk_mul_f32 v[136:137], v[136:137], s[96:97] op_sel_hi:[1,0]
	v_pk_fma_f32 v[80:81], v[80:81], 0.5, v[136:137] op_sel_hi:[1,0,1]
	v_pk_mul_f32 v[142:143], v[142:143], s[96:97] op_sel_hi:[1,0]
	v_pk_fma_f32 v[78:79], v[78:79], 0.5, v[142:143] op_sel_hi:[1,0,1]
	s_waitcnt lgkmcnt(1)
	v_lshlrev_b32_e32 v136, 16, v145
	v_and_b32_e32 v137, 0xffff0000, v145
	s_waitcnt lgkmcnt(0)
	v_and_b32_e32 v145, 0xffff0000, v144
	v_lshlrev_b32_e32 v144, 16, v144
	v_pk_mul_f32 v[136:137], v[136:137], s[96:97] op_sel_hi:[1,0]
	v_pk_fma_f32 v[76:77], v[76:77], 0.5, v[136:137] op_sel_hi:[1,0,1]
	v_pk_mul_f32 v[144:145], v[144:145], s[96:97] op_sel_hi:[1,0]
	v_pk_fma_f32 v[74:75], v[74:75], 0.5, v[144:145] op_sel_hi:[1,0,1]
	v_cvt_pk_bf16_f32 v78, v78, v79
	v_cvt_pk_bf16_f32 v79, v80, v81
	v_cvt_pk_bf16_f32 v80, v74, v75
	v_cvt_pk_bf16_f32 v77, v76, v77
	s_nop 1
	ds_bpermute_b32 v74, v132, v78
	ds_bpermute_b32 v75, v132, v79
	ds_bpermute_b32 v76, v132, v80
	ds_bpermute_b32 v77, v132, v77
	s_waitcnt lgkmcnt(0)
	global_store_dwordx4 v[134:135], v[74:77], off
	s_waitcnt vmcnt(15)
	ds_bpermute_b32 v143, v133, v175
	ds_bpermute_b32 v142, v133, v174
	ds_bpermute_b32 v145, v133, v177
	ds_bpermute_b32 v144, v133, v176
	s_waitcnt lgkmcnt(3)
	v_lshlrev_b32_e32 v136, 16, v143
	v_and_b32_e32 v137, 0xffff0000, v143
	s_waitcnt lgkmcnt(2)
	v_and_b32_e32 v143, 0xffff0000, v142
	v_lshlrev_b32_e32 v142, 16, v142
	v_pk_mul_f32 v[136:137], v[136:137], s[96:97] op_sel_hi:[1,0]
	v_pk_fma_f32 v[72:73], v[72:73], 0.5, v[136:137] op_sel_hi:[1,0,1]
	v_pk_mul_f32 v[142:143], v[142:143], s[96:97] op_sel_hi:[1,0]
	v_pk_fma_f32 v[70:71], v[70:71], 0.5, v[142:143] op_sel_hi:[1,0,1]
	s_waitcnt lgkmcnt(1)
	v_lshlrev_b32_e32 v136, 16, v145
	v_and_b32_e32 v137, 0xffff0000, v145
	s_waitcnt lgkmcnt(0)
	v_and_b32_e32 v145, 0xffff0000, v144
	v_lshlrev_b32_e32 v144, 16, v144
	v_pk_mul_f32 v[136:137], v[136:137], s[96:97] op_sel_hi:[1,0]
	v_pk_fma_f32 v[68:69], v[68:69], 0.5, v[136:137] op_sel_hi:[1,0,1]
	v_pk_mul_f32 v[144:145], v[144:145], s[96:97] op_sel_hi:[1,0]
	v_pk_fma_f32 v[66:67], v[66:67], 0.5, v[144:145] op_sel_hi:[1,0,1]
	v_cvt_pk_bf16_f32 v70, v70, v71
	v_cvt_pk_bf16_f32 v71, v72, v73
	v_cvt_pk_bf16_f32 v72, v66, v67
	v_cvt_pk_bf16_f32 v69, v68, v69
	s_nop 1
	ds_bpermute_b32 v66, v132, v70
	ds_bpermute_b32 v67, v132, v71
	ds_bpermute_b32 v68, v132, v72
	ds_bpermute_b32 v69, v132, v69
	s_waitcnt lgkmcnt(0)
	global_store_dwordx4 v[134:135], v[66:69], off offset:256
	s_waitcnt vmcnt(15)
	ds_bpermute_b32 v143, v133, v179
	ds_bpermute_b32 v142, v133, v178
	ds_bpermute_b32 v145, v133, v181
	ds_bpermute_b32 v144, v133, v180
	s_mov_b64 s[12:13], 0x40000
	v_lshl_add_u64 v[134:135], v[140:141], 0, s[12:13]
	s_waitcnt lgkmcnt(3)
	v_lshlrev_b32_e32 v136, 16, v143
	v_and_b32_e32 v137, 0xffff0000, v143
	s_waitcnt lgkmcnt(2)
	v_and_b32_e32 v143, 0xffff0000, v142
	v_lshlrev_b32_e32 v142, 16, v142
	v_pk_mul_f32 v[136:137], v[136:137], s[96:97] op_sel_hi:[1,0]
	v_pk_fma_f32 v[64:65], v[64:65], 0.5, v[136:137] op_sel_hi:[1,0,1]
	v_pk_mul_f32 v[142:143], v[142:143], s[96:97] op_sel_hi:[1,0]
	v_pk_fma_f32 v[62:63], v[62:63], 0.5, v[142:143] op_sel_hi:[1,0,1]
	s_waitcnt lgkmcnt(1)
	v_lshlrev_b32_e32 v136, 16, v145
	v_and_b32_e32 v137, 0xffff0000, v145
	s_waitcnt lgkmcnt(0)
	v_and_b32_e32 v145, 0xffff0000, v144
	v_lshlrev_b32_e32 v144, 16, v144
	v_pk_mul_f32 v[136:137], v[136:137], s[96:97] op_sel_hi:[1,0]
	v_pk_fma_f32 v[60:61], v[60:61], 0.5, v[136:137] op_sel_hi:[1,0,1]
	v_pk_mul_f32 v[144:145], v[144:145], s[96:97] op_sel_hi:[1,0]
	v_pk_fma_f32 v[58:59], v[58:59], 0.5, v[144:145] op_sel_hi:[1,0,1]
	v_cvt_pk_bf16_f32 v62, v62, v63
	v_cvt_pk_bf16_f32 v63, v64, v65
	v_cvt_pk_bf16_f32 v64, v58, v59
	v_cvt_pk_bf16_f32 v61, v60, v61
	s_nop 1
	ds_bpermute_b32 v58, v132, v62
	ds_bpermute_b32 v59, v132, v63
	ds_bpermute_b32 v60, v132, v64
	ds_bpermute_b32 v61, v132, v61
	s_waitcnt lgkmcnt(0)
	global_store_dwordx4 v[134:135], v[58:61], off
	s_waitcnt vmcnt(15)
	ds_bpermute_b32 v143, v133, v183
	ds_bpermute_b32 v142, v133, v182
	ds_bpermute_b32 v145, v133, v185
	ds_bpermute_b32 v144, v133, v184
	s_waitcnt lgkmcnt(3)
	v_lshlrev_b32_e32 v136, 16, v143
	v_and_b32_e32 v137, 0xffff0000, v143
	s_waitcnt lgkmcnt(2)
	v_and_b32_e32 v143, 0xffff0000, v142
	v_lshlrev_b32_e32 v142, 16, v142
	v_pk_mul_f32 v[136:137], v[136:137], s[96:97] op_sel_hi:[1,0]
	v_pk_fma_f32 v[56:57], v[56:57], 0.5, v[136:137] op_sel_hi:[1,0,1]
	v_pk_mul_f32 v[142:143], v[142:143], s[96:97] op_sel_hi:[1,0]
	v_pk_fma_f32 v[54:55], v[54:55], 0.5, v[142:143] op_sel_hi:[1,0,1]
	s_waitcnt lgkmcnt(1)
	v_lshlrev_b32_e32 v136, 16, v145
	v_and_b32_e32 v137, 0xffff0000, v145
	s_waitcnt lgkmcnt(0)
	v_and_b32_e32 v145, 0xffff0000, v144
	v_lshlrev_b32_e32 v144, 16, v144
	v_pk_mul_f32 v[136:137], v[136:137], s[96:97] op_sel_hi:[1,0]
	v_pk_fma_f32 v[52:53], v[52:53], 0.5, v[136:137] op_sel_hi:[1,0,1]
	v_pk_mul_f32 v[144:145], v[144:145], s[96:97] op_sel_hi:[1,0]
	v_pk_fma_f32 v[50:51], v[50:51], 0.5, v[144:145] op_sel_hi:[1,0,1]
	v_cvt_pk_bf16_f32 v54, v54, v55
	v_cvt_pk_bf16_f32 v55, v56, v57
	v_cvt_pk_bf16_f32 v56, v50, v51
	v_cvt_pk_bf16_f32 v53, v52, v53
	s_nop 1
	ds_bpermute_b32 v50, v132, v54
	ds_bpermute_b32 v51, v132, v55
	ds_bpermute_b32 v52, v132, v56
	ds_bpermute_b32 v53, v132, v53
	s_waitcnt lgkmcnt(0)
; #define GAS __attribute__((address_space(1)))
; __device__ __forceinline__ v4u tr4(int a, v4u x) { return (v4u){bperm(a, x.x), bperm(a, x.y), bperm(a, x.z), bperm(a, x.w)}; }
; __device__ __forceinline__ v4u pack8(const f32x4& a, const f32x4& b) { return (v4u){pg8::cvt_pk_bf16(a[0], a[1]), pg8::cvt_pk_bf16(a[2], a[3]), pg8::cvt_pk_bf16(b[0], b[1]), pg8::cvt_pk_bf16(b[2], b[3])}; }
;     __device__ __forceinline__ bool operator()(AccT& acc, const Unit& u, int wr, int wc, int fr, int fq) const {
;     ...
;             for (int m = 0; m < 4; ++m) { const size_t off = (size_t)(row0 + ai * 128 + m * 16) * D + col0;
; #pragma unroll
;                 for (int bj = 0; bj < 2; ++bj) { const v4u r = tr4(t.push, *(const GAS v4u*)(src + off + bj * 128));
;                     const f32x4 y0 = (f32x4){bflo(r.x), bfhi(r.x), bflo(r.y), bfhi(r.y)} * ca + acc[ai][bj][m][0] * cb, y1 = (f32x4){bflo(r.z), bfhi(r.z), bflo(r.w), bfhi(r.w)} * ca + acc[ai][bj][m][1] * cb;
;                     *(GAS v4u*)(dst + off + bj * 128) = tr4(t.pull, pack8(y0, y1)); } }
	global_store_dwordx4 v[134:135], v[50:53], off offset:256
	s_waitcnt vmcnt(15)
	ds_bpermute_b32 v143, v133, v187
	ds_bpermute_b32 v142, v133, v186
	ds_bpermute_b32 v145, v133, v189
	ds_bpermute_b32 v144, v133, v188
	s_mov_b64 s[12:13], 0x48000
	v_lshl_add_u64 v[134:135], v[140:141], 0, s[12:13]
	s_waitcnt lgkmcnt(3)
	v_lshlrev_b32_e32 v136, 16, v143
	v_and_b32_e32 v137, 0xffff0000, v143
	s_waitcnt lgkmcnt(2)
	v_and_b32_e32 v143, 0xffff0000, v142
	v_lshlrev_b32_e32 v142, 16, v142
	v_pk_mul_f32 v[136:137], v[136:137], s[96:97] op_sel_hi:[1,0]
	v_pk_fma_f32 v[48:49], v[48:49], 0.5, v[136:137] op_sel_hi:[1,0,1]
	v_pk_mul_f32 v[142:143], v[142:143], s[96:97] op_sel_hi:[1,0]
	v_pk_fma_f32 v[46:47], v[46:47], 0.5, v[142:143] op_sel_hi:[1,0,1]
	s_waitcnt lgkmcnt(1)
	v_lshlrev_b32_e32 v136, 16, v145
	v_and_b32_e32 v137, 0xffff0000, v145
	s_waitcnt lgkmcnt(0)
	v_and_b32_e32 v145, 0xffff0000, v144
	v_lshlrev_b32_e32 v144, 16, v144
	v_pk_mul_f32 v[136:137], v[136:137], s[96:97] op_sel_hi:[1,0]
	v_pk_fma_f32 v[44:45], v[44:45], 0.5, v[136:137] op_sel_hi:[1,0,1]
	v_pk_mul_f32 v[144:145], v[144:145], s[96:97] op_sel_hi:[1,0]
	v_pk_fma_f32 v[42:43], v[42:43], 0.5, v[144:145] op_sel_hi:[1,0,1]
	v_cvt_pk_bf16_f32 v46, v46, v47
	v_cvt_pk_bf16_f32 v47, v48, v49
	v_cvt_pk_bf16_f32 v48, v42, v43
	v_cvt_pk_bf16_f32 v45, v44, v45
	s_nop 1
	ds_bpermute_b32 v42, v132, v46
	ds_bpermute_b32 v43, v132, v47
	ds_bpermute_b32 v44, v132, v48
	ds_bpermute_b32 v45, v132, v45
	s_waitcnt lgkmcnt(0)
	global_store_dwordx4 v[134:135], v[42:45], off
	s_waitcnt vmcnt(15)
	ds_bpermute_b32 v143, v133, v191
	ds_bpermute_b32 v142, v133, v190
	ds_bpermute_b32 v145, v133, v193
	ds_bpermute_b32 v144, v133, v192
	s_waitcnt lgkmcnt(3)
	v_lshlrev_b32_e32 v136, 16, v143
	v_and_b32_e32 v137, 0xffff0000, v143
	s_waitcnt lgkmcnt(2)
	v_and_b32_e32 v143, 0xffff0000, v142
	v_lshlrev_b32_e32 v142, 16, v142
	v_pk_mul_f32 v[136:137], v[136:137], s[96:97] op_sel_hi:[1,0]
	v_pk_fma_f32 v[40:41], v[40:41], 0.5, v[136:137] op_sel_hi:[1,0,1]
	v_pk_mul_f32 v[142:143], v[142:143], s[96:97] op_sel_hi:[1,0]
	v_pk_fma_f32 v[38:39], v[38:39], 0.5, v[142:143] op_sel_hi:[1,0,1]
	s_waitcnt lgkmcnt(1)
	v_lshlrev_b32_e32 v136, 16, v145
	v_and_b32_e32 v137, 0xffff0000, v145
	s_waitcnt lgkmcnt(0)
	v_and_b32_e32 v145, 0xffff0000, v144
	v_lshlrev_b32_e32 v144, 16, v144
	v_pk_mul_f32 v[136:137], v[136:137], s[96:97] op_sel_hi:[1,0]
	v_pk_fma_f32 v[36:37], v[36:37], 0.5, v[136:137] op_sel_hi:[1,0,1]
	v_pk_mul_f32 v[144:145], v[144:145], s[96:97] op_sel_hi:[1,0]
	v_pk_fma_f32 v[34:35], v[34:35], 0.5, v[144:145] op_sel_hi:[1,0,1]
	v_cvt_pk_bf16_f32 v38, v38, v39
	v_cvt_pk_bf16_f32 v39, v40, v41
	v_cvt_pk_bf16_f32 v40, v34, v35
	v_cvt_pk_bf16_f32 v37, v36, v37
	s_nop 1
	ds_bpermute_b32 v34, v132, v38
	ds_bpermute_b32 v35, v132, v39
	ds_bpermute_b32 v36, v132, v40
	ds_bpermute_b32 v37, v132, v37
	s_waitcnt lgkmcnt(0)
	global_store_dwordx4 v[134:135], v[34:37], off offset:256
	s_waitcnt vmcnt(14)
	ds_bpermute_b32 v143, v133, v127
	ds_bpermute_b32 v142, v133, v126
	ds_bpermute_b32 v145, v133, v129
	ds_bpermute_b32 v144, v133, v128
	s_mov_b64 s[12:13], 0x50000
	v_lshl_add_u64 v[134:135], v[140:141], 0, s[12:13]
	s_waitcnt lgkmcnt(3)
	v_lshlrev_b32_e32 v136, 16, v143
	v_and_b32_e32 v137, 0xffff0000, v143
	s_waitcnt lgkmcnt(2)
	v_and_b32_e32 v143, 0xffff0000, v142
	v_lshlrev_b32_e32 v142, 16, v142
	v_pk_mul_f32 v[136:137], v[136:137], s[96:97] op_sel_hi:[1,0]
	v_pk_fma_f32 v[32:33], v[32:33], 0.5, v[136:137] op_sel_hi:[1,0,1]
	v_pk_mul_f32 v[142:143], v[142:143], s[96:97] op_sel_hi:[1,0]
	v_pk_fma_f32 v[30:31], v[30:31], 0.5, v[142:143] op_sel_hi:[1,0,1]
	s_waitcnt lgkmcnt(1)
	v_lshlrev_b32_e32 v136, 16, v145
	v_and_b32_e32 v137, 0xffff0000, v145
	s_waitcnt lgkmcnt(0)
	v_and_b32_e32 v145, 0xffff0000, v144
	v_lshlrev_b32_e32 v144, 16, v144
	v_pk_mul_f32 v[136:137], v[136:137], s[96:97] op_sel_hi:[1,0]
	v_pk_fma_f32 v[28:29], v[28:29], 0.5, v[136:137] op_sel_hi:[1,0,1]
	v_pk_mul_f32 v[144:145], v[144:145], s[96:97] op_sel_hi:[1,0]
	v_pk_fma_f32 v[26:27], v[26:27], 0.5, v[144:145] op_sel_hi:[1,0,1]
	v_cvt_pk_bf16_f32 v30, v30, v31
	v_cvt_pk_bf16_f32 v31, v32, v33
	v_cvt_pk_bf16_f32 v32, v26, v27
	v_cvt_pk_bf16_f32 v29, v28, v29
	s_nop 1
	ds_bpermute_b32 v26, v132, v30
	ds_bpermute_b32 v27, v132, v31
	ds_bpermute_b32 v28, v132, v32
	ds_bpermute_b32 v29, v132, v29
	s_waitcnt lgkmcnt(0)
; #define PG8_BAR __builtin_amdgcn_s_barrier()
; #define GAS __attribute__((address_space(1)))
; __device__ __forceinline__ v4u tr4(int a, v4u x) { return (v4u){bperm(a, x.x), bperm(a, x.y), bperm(a, x.z), bperm(a, x.w)}; }
; __device__ __forceinline__ v4u pack8(const f32x4& a, const f32x4& b) { return (v4u){pg8::cvt_pk_bf16(a[0], a[1]), pg8::cvt_pk_bf16(a[2], a[3]), pg8::cvt_pk_bf16(b[0], b[1]), pg8::cvt_pk_bf16(b[2], b[3])}; }
; template <class Epi, class Sched, bool ALIGN_EPI = false, bool SP2 = false>
; __device__ __forceinline__ void gemm_phase(PG8_LAS unsigned char* lds, const Gemm g, const Sched& S, const Epi& E, const int wave_id) {
;     ...
;         if (!has_next) break;
;         if (!keep_acc) {
; #pragma unroll
;         for (int a = 0; a < 2; ++a)
; #pragma unroll
;             for (int b = 0; b < 2; ++b)
; #pragma unroll
;                 for (int m = 0; m < 4; ++m)
; #pragma unroll
;                     for (int n = 0; n < 2; ++n) acc[a][b][m][n] = (f32x4){0.f, 0.f, 0.f, 0.f};
;         }
;         cur = nxt; cA = nA; cB = nB; ++ui;
;         if constexpr (ALIGN_EPI) { if (wr == 1) PG8_BAR; }
;     __device__ __forceinline__ bool operator()(AccT& acc, const Unit& u, int wr, int wc, int fr, int fq) const {
;     ...
;             for (int m = 0; m < 4; ++m) { const size_t off = (size_t)(row0 + ai * 128 + m * 16) * D + col0;
; #pragma unroll
;                 for (int bj = 0; bj < 2; ++bj) { const v4u r = tr4(t.push, *(const GAS v4u*)(src + off + bj * 128));
;                     const f32x4 y0 = (f32x4){bflo(r.x), bfhi(r.x), bflo(r.y), bfhi(r.y)} * ca + acc[ai][bj][m][0] * cb, y1 = (f32x4){bflo(r.z), bfhi(r.z), bflo(r.w), bfhi(r.w)} * ca + acc[ai][bj][m][1] * cb;
;                     *(GAS v4u*)(dst + off + bj * 128) = tr4(t.pull, pack8(y0, y1)); } }
	global_store_dwordx4 v[134:135], v[26:29], off
	s_waitcnt vmcnt(13)
	ds_bpermute_b32 v143, v133, v119
	ds_bpermute_b32 v142, v133, v118
	ds_bpermute_b32 v145, v133, v121
	ds_bpermute_b32 v144, v133, v120
	s_waitcnt lgkmcnt(3)
	v_lshlrev_b32_e32 v136, 16, v143
	v_and_b32_e32 v137, 0xffff0000, v143
	s_waitcnt lgkmcnt(2)
	v_and_b32_e32 v143, 0xffff0000, v142
	v_lshlrev_b32_e32 v142, 16, v142
	v_pk_mul_f32 v[136:137], v[136:137], s[96:97] op_sel_hi:[1,0]
	v_pk_fma_f32 v[24:25], v[24:25], 0.5, v[136:137] op_sel_hi:[1,0,1]
	v_pk_mul_f32 v[142:143], v[142:143], s[96:97] op_sel_hi:[1,0]
	v_pk_fma_f32 v[22:23], v[22:23], 0.5, v[142:143] op_sel_hi:[1,0,1]
	s_waitcnt lgkmcnt(1)
	v_lshlrev_b32_e32 v136, 16, v145
	v_and_b32_e32 v137, 0xffff0000, v145
	s_waitcnt lgkmcnt(0)
	v_and_b32_e32 v145, 0xffff0000, v144
	v_lshlrev_b32_e32 v144, 16, v144
	v_pk_mul_f32 v[136:137], v[136:137], s[96:97] op_sel_hi:[1,0]
	v_pk_fma_f32 v[20:21], v[20:21], 0.5, v[136:137] op_sel_hi:[1,0,1]
	v_pk_mul_f32 v[144:145], v[144:145], s[96:97] op_sel_hi:[1,0]
	v_pk_fma_f32 v[18:19], v[18:19], 0.5, v[144:145] op_sel_hi:[1,0,1]
	v_cvt_pk_bf16_f32 v22, v22, v23
	v_cvt_pk_bf16_f32 v23, v24, v25
	v_cvt_pk_bf16_f32 v24, v18, v19
	v_cvt_pk_bf16_f32 v21, v20, v21
	s_nop 1
	ds_bpermute_b32 v18, v132, v22
	ds_bpermute_b32 v19, v132, v23
	ds_bpermute_b32 v20, v132, v24
	ds_bpermute_b32 v21, v132, v21
	s_waitcnt lgkmcnt(0)
	global_store_dwordx4 v[134:135], v[18:21], off offset:256
	s_waitcnt vmcnt(12)
	ds_bpermute_b32 v143, v133, v111
	ds_bpermute_b32 v142, v133, v110
	ds_bpermute_b32 v145, v133, v113
	ds_bpermute_b32 v144, v133, v112
	s_mov_b64 s[12:13], 0x58000
	v_lshl_add_u64 v[134:135], v[140:141], 0, s[12:13]
	s_waitcnt lgkmcnt(3)
	v_lshlrev_b32_e32 v136, 16, v143
	v_and_b32_e32 v137, 0xffff0000, v143
	s_waitcnt lgkmcnt(2)
	v_and_b32_e32 v143, 0xffff0000, v142
	v_lshlrev_b32_e32 v142, 16, v142
	v_pk_mul_f32 v[136:137], v[136:137], s[96:97] op_sel_hi:[1,0]
	v_pk_fma_f32 v[16:17], v[16:17], 0.5, v[136:137] op_sel_hi:[1,0,1]
	v_pk_mul_f32 v[142:143], v[142:143], s[96:97] op_sel_hi:[1,0]
	v_pk_fma_f32 v[14:15], v[14:15], 0.5, v[142:143] op_sel_hi:[1,0,1]
	s_waitcnt lgkmcnt(1)
	v_lshlrev_b32_e32 v136, 16, v145
	v_and_b32_e32 v137, 0xffff0000, v145
	s_waitcnt lgkmcnt(0)
	v_and_b32_e32 v145, 0xffff0000, v144
	v_lshlrev_b32_e32 v144, 16, v144
	v_pk_mul_f32 v[136:137], v[136:137], s[96:97] op_sel_hi:[1,0]
	v_pk_fma_f32 v[12:13], v[12:13], 0.5, v[136:137] op_sel_hi:[1,0,1]
	v_pk_mul_f32 v[144:145], v[144:145], s[96:97] op_sel_hi:[1,0]
	v_pk_fma_f32 v[10:11], v[10:11], 0.5, v[144:145] op_sel_hi:[1,0,1]
	v_cvt_pk_bf16_f32 v14, v14, v15
	v_cvt_pk_bf16_f32 v15, v16, v17
	v_cvt_pk_bf16_f32 v16, v10, v11
	v_cvt_pk_bf16_f32 v13, v12, v13
	s_nop 1
	ds_bpermute_b32 v10, v132, v14
	ds_bpermute_b32 v11, v132, v15
	ds_bpermute_b32 v12, v132, v16
	ds_bpermute_b32 v13, v132, v13
	s_waitcnt lgkmcnt(0)
	global_store_dwordx4 v[134:135], v[10:13], off
	s_waitcnt vmcnt(11)
	ds_bpermute_b32 v143, v133, v103
	ds_bpermute_b32 v142, v133, v102
	ds_bpermute_b32 v145, v133, v105
	ds_bpermute_b32 v144, v133, v104
	s_waitcnt lgkmcnt(3)
	v_lshlrev_b32_e32 v136, 16, v143
	v_and_b32_e32 v137, 0xffff0000, v143
	s_waitcnt lgkmcnt(2)
	v_and_b32_e32 v143, 0xffff0000, v142
	v_lshlrev_b32_e32 v142, 16, v142
	v_pk_mul_f32 v[136:137], v[136:137], s[96:97] op_sel_hi:[1,0]
	v_pk_fma_f32 v[8:9], v[8:9], 0.5, v[136:137] op_sel_hi:[1,0,1]
	v_pk_mul_f32 v[142:143], v[142:143], s[96:97] op_sel_hi:[1,0]
	v_pk_fma_f32 v[6:7], v[6:7], 0.5, v[142:143] op_sel_hi:[1,0,1]
	s_waitcnt lgkmcnt(1)
	v_lshlrev_b32_e32 v136, 16, v145
	v_and_b32_e32 v137, 0xffff0000, v145
	s_waitcnt lgkmcnt(0)
	v_and_b32_e32 v145, 0xffff0000, v144
	v_lshlrev_b32_e32 v144, 16, v144
	v_pk_mul_f32 v[136:137], v[136:137], s[96:97] op_sel_hi:[1,0]
	v_pk_fma_f32 v[4:5], v[4:5], 0.5, v[136:137] op_sel_hi:[1,0,1]
	v_pk_mul_f32 v[144:145], v[144:145], s[96:97] op_sel_hi:[1,0]
	v_pk_fma_f32 v[2:3], v[2:3], 0.5, v[144:145] op_sel_hi:[1,0,1]
	v_cvt_pk_bf16_f32 v6, v6, v7
	v_cvt_pk_bf16_f32 v7, v8, v9
	v_cvt_pk_bf16_f32 v8, v2, v3
	v_cvt_pk_bf16_f32 v5, v4, v5
	s_nop 1
	ds_bpermute_b32 v2, v132, v6
	ds_bpermute_b32 v3, v132, v7
	ds_bpermute_b32 v4, v132, v8
	ds_bpermute_b32 v5, v132, v5
	s_waitcnt lgkmcnt(0)
	global_store_dwordx4 v[134:135], v[2:5], off offset:256
	s_mov_b64 s[12:13], -1
	s_cbranch_vccnz .LBB0_223
	s_andn2_b64 vcc, exec, s[2:3]
	s_cbranch_vccnz .LBB0_222
	s_branch .LBB0_222

; #define PG8_STAGE(bufoff, gbase, voff) do { _Pragma("unroll") for (int _i = 0; _i < 2; ++_i) \
;         __builtin_amdgcn_global_load_lds((const unsigned*)((const char*)(gbase) + (voff)[_i]), (PG8_LAS unsigned*)(lds + (bufoff) + ldsw + _i * 8192), 16, 0, 0); } while (0)
; #define PG8_LDA(dst, b, h) do { _Pragma("unroll") for (int m = 0; m < 4; ++m) _Pragma("unroll") for (int k = 0; k < 2; ++k) dst[m][k] = *(const PG8_LAS bf16x8*)(lds + PG8_SA(b, h) + aoff + m * 2048 + k * 1024); } while (0)
; #define PG8_LDB(dst, b, h) do { _Pragma("unroll") for (int n = 0; n < 2; ++n) _Pragma("unroll") for (int k = 0; k < 2; ++k) dst[n][k] = *(const PG8_LAS bf16x8*)(lds + PG8_SB(b, h) + boff + n * 2048 + k * 1024); } while (0)
; #define PG8_MMA(ai, bj, At, Bt) do { __builtin_amdgcn_s_setprio(1); _Pragma("unroll") for (int m = 0; m < 4; ++m) _Pragma("unroll") for (int n = 0; n < 2; ++n) _Pragma("unroll") for (int k = 0; k < 2; ++k) \
;         acc[ai][bj][m][n] = __builtin_amdgcn_mfma_f32_16x16x32_bf16(Bt[n][k], At[m][k], acc[ai][bj][m][n], 0, 0, 0); __builtin_amdgcn_s_setprio(0); } while (0)
; #define PG8_WAIT_V(n) asm volatile("s_waitcnt vmcnt(" #n ")" ::: "memory")
; #define PG8_WAIT_VN(n) asm volatile("s_waitcnt vmcnt(%0)" :: "n"(n) : "memory")
; #define PG8_WAIT_L(n) asm volatile("s_waitcnt lgkmcnt(" #n ")" ::: "memory")
; template <class Epi, class Sched, bool ALIGN_EPI = false, bool SP2 = false>
; __device__ __forceinline__ void gemm_phase(PG8_LAS unsigned char* lds, const Gemm g, const Sched& S, const Epi& E, const int wave_id) {
;     ...
;             PG8_WAIT_VN(8 + Epi::NS); if (strict) PG8_WAIT_V(8); PG8_WAIT_L(0); PG8_BAR; PG8_MMA(1, 0, At, B0); PG8_MMA(1, 1, At, B1); PG8_BAR; PG8_SCHED;
;             PG8_LDB(B0, 1, 0); PG8_LDB(B1, 1, 1); PG8_SCHED; PG8_LDA(At, 1, 0); PG8_STAGE(PG8_SA(0, 1), a2 + hstep, voffA);
;             PG8_WAIT_V(8); PG8_WAIT_L(0); PG8_BAR; PG8_MMA(0, 0, At, B0); PG8_MMA(0, 1, At, B1); PG8_BAR; PG8_SCHED;
;     ...
; #pragma unroll
;         for (int a = 0; a < 2; ++a)
; #pragma unroll
;             for (int b = 0; b < 2; ++b)
; #pragma unroll
;                 for (int m = 0; m < 4; ++m)
; #pragma unroll
;                     for (int n = 0; n < 2; ++n) acc[a][b][m][n] = (f32x4){0.f, 0.f, 0.f, 0.f};
;         }
;         cur = nxt; cA = nA; cB = nB; ++ui;
;         if constexpr (ALIGN_EPI) { if (wr == 1) PG8_BAR; }
.LBB0_419:
	s_ashr_i32 s23, s22, 31
	s_lshl_b64 s[12:13], s[22:23], 19
	s_add_u32 s24, s54, s12
	s_addc_u32 s25, s55, s13
	s_and_b64 s[12:13], s[6:7], exec
	s_cselect_b32 s23, s25, s9
	s_cselect_b32 s29, s24, s8
	s_ashr_i32 s21, s20, 31
	s_lshl_b64 s[12:13], s[20:21], 19
	s_add_u32 s26, s67, s12
	s_addc_u32 s27, s74, s13
	s_and_b64 s[12:13], s[6:7], exec
	s_cselect_b32 s21, s27, s11
	s_cselect_b32 s31, s26, s10
	s_cmp_eq_u32 s14, 0
	s_cselect_b64 s[12:13], -1, 0
	s_add_u32 s36, s10, 0x100
	s_addc_u32 s37, s11, 0
	s_add_u32 s10, s8, 0x40080
	s_addc_u32 s11, s9, 0
	v_mov_b32_e32 v2, 0
	v_cndmask_b32_e64 v248, 0, 1, s[12:13]
	s_and_b32 s101, s12, 1
	v_lshl_add_u64 v[222:223], s[10:11], 0, v[218:219]
	v_lshl_add_u64 v[224:225], s[10:11], 0, v[220:221]
	s_mov_b32 s40, -2
	s_mov_b64 s[10:11], 0
	v_mov_b32_e32 v3, v2
	v_mov_b64_e32 v[4:5], 0
	v_mov_b64_e32 v[6:7], 0
	v_mov_b64_e32 v[8:9], 0
	v_mov_b64_e32 v[10:11], 0
	v_mov_b64_e32 v[12:13], 0
	v_mov_b64_e32 v[14:15], 0
	v_mov_b64_e32 v[16:17], 0
	v_mov_b64_e32 v[18:19], 0
	v_mov_b64_e32 v[20:21], 0
	v_mov_b64_e32 v[22:23], 0
	v_mov_b64_e32 v[24:25], 0
	v_mov_b64_e32 v[26:27], 0
	v_mov_b64_e32 v[28:29], 0
	v_mov_b64_e32 v[30:31], 0
	v_mov_b64_e32 v[32:33], 0
	v_mov_b64_e32 v[34:35], 0
	v_mov_b64_e32 v[36:37], 0
	v_mov_b64_e32 v[38:39], 0
	v_mov_b64_e32 v[40:41], 0
	v_mov_b64_e32 v[42:43], 0
	v_mov_b64_e32 v[44:45], 0
	v_mov_b64_e32 v[46:47], 0
	v_mov_b64_e32 v[48:49], 0
	v_mov_b64_e32 v[50:51], 0
	v_mov_b64_e32 v[52:53], 0
	v_mov_b64_e32 v[54:55], 0
	v_mov_b64_e32 v[56:57], 0
	v_mov_b64_e32 v[58:59], 0
	v_mov_b64_e32 v[60:61], 0
	v_mov_b64_e32 v[62:63], 0
	v_mov_b64_e32 v[64:65], 0
	v_mov_b64_e32 v[66:67], 0
	v_mov_b64_e32 v[68:69], 0
	v_mov_b64_e32 v[70:71], 0
	v_mov_b64_e32 v[72:73], 0
	v_mov_b64_e32 v[74:75], 0
	v_mov_b64_e32 v[76:77], 0
	v_mov_b64_e32 v[78:79], 0
	v_mov_b64_e32 v[80:81], 0
	v_mov_b64_e32 v[82:83], 0
	v_mov_b64_e32 v[84:85], 0
	v_mov_b64_e32 v[86:87], 0
	v_mov_b64_e32 v[88:89], 0
	v_mov_b64_e32 v[90:91], 0
	v_mov_b64_e32 v[92:93], 0
	v_mov_b64_e32 v[94:95], 0
	v_mov_b64_e32 v[96:97], 0
	v_mov_b64_e32 v[98:99], 0
	v_mov_b64_e32 v[100:101], 0
	v_mov_b64_e32 v[102:103], 0
	v_mov_b64_e32 v[104:105], 0
	v_mov_b64_e32 v[106:107], 0
	v_mov_b64_e32 v[108:109], 0
	v_mov_b64_e32 v[110:111], 0
	v_mov_b64_e32 v[112:113], 0
	v_mov_b64_e32 v[114:115], 0
	v_mov_b64_e32 v[116:117], 0
	v_mov_b64_e32 v[118:119], 0
	v_mov_b64_e32 v[120:121], 0
	v_mov_b64_e32 v[122:123], 0
	v_mov_b64_e32 v[124:125], 0
	v_mov_b64_e32 v[126:127], 0
	v_mov_b64_e32 v[128:129], 0
	s_cmp_eq_u32 s101, 0
	s_cbranch_scc0 .Lskew_skip_3
	s_andn2_b64 vcc, exec, s[52:53]
	s_cbranch_vccnz .Lskew_skip_3
	s_barrier
.Lskew_skip_3:
	s_branch .LBB0_421
.LBB0_420:
	s_waitcnt lgkmcnt(0)
	s_barrier
	s_setprio 1
	s_waitcnt lgkmcnt(0)
	v_mfma_f32_16x16x32_bf16 v[62:65], v[146:149], v[186:189], v[62:65]
	v_mfma_f32_16x16x32_bf16 v[58:61], v[154:157], v[186:189], v[58:61]
	v_mfma_f32_16x16x32_bf16 v[46:49], v[146:149], v[178:181], v[46:49]
	v_mfma_f32_16x16x32_bf16 v[42:45], v[154:157], v[178:181], v[42:45]
	v_mfma_f32_16x16x32_bf16 v[30:33], v[146:149], v[170:173], v[30:33]
	v_mfma_f32_16x16x32_bf16 v[26:29], v[154:157], v[170:173], v[26:29]
	v_mfma_f32_16x16x32_bf16 v[14:17], v[146:149], v[162:165], v[14:17]
	v_mfma_f32_16x16x32_bf16 v[10:13], v[154:157], v[162:165], v[10:13]
	v_mfma_f32_16x16x32_bf16 v[62:65], v[150:153], v[190:193], v[62:65]
	v_mfma_f32_16x16x32_bf16 v[58:61], v[158:161], v[190:193], v[58:61]
	v_mfma_f32_16x16x32_bf16 v[46:49], v[150:153], v[182:185], v[46:49]
	v_mfma_f32_16x16x32_bf16 v[42:45], v[158:161], v[182:185], v[42:45]
	v_mfma_f32_16x16x32_bf16 v[30:33], v[150:153], v[174:177], v[30:33]
	v_mfma_f32_16x16x32_bf16 v[26:29], v[158:161], v[174:177], v[26:29]
	v_mfma_f32_16x16x32_bf16 v[14:17], v[150:153], v[166:169], v[14:17]
	v_mfma_f32_16x16x32_bf16 v[10:13], v[158:161], v[166:169], v[10:13]
	s_setprio 0
	s_setprio 1
	v_mfma_f32_16x16x32_bf16 v[54:57], v[130:133], v[186:189], v[54:57]
	v_mfma_f32_16x16x32_bf16 v[50:53], v[138:141], v[186:189], v[50:53]
	v_mfma_f32_16x16x32_bf16 v[38:41], v[130:133], v[178:181], v[38:41]
	v_mfma_f32_16x16x32_bf16 v[34:37], v[138:141], v[178:181], v[34:37]
	v_mfma_f32_16x16x32_bf16 v[22:25], v[130:133], v[170:173], v[22:25]
	v_mfma_f32_16x16x32_bf16 v[18:21], v[138:141], v[170:173], v[18:21]
	v_mfma_f32_16x16x32_bf16 v[6:9], v[130:133], v[162:165], v[6:9]
	v_mfma_f32_16x16x32_bf16 v[2:5], v[138:141], v[162:165], v[2:5]
	v_mfma_f32_16x16x32_bf16 v[54:57], v[134:137], v[190:193], v[54:57]
	v_mfma_f32_16x16x32_bf16 v[50:53], v[142:145], v[190:193], v[50:53]
	v_mfma_f32_16x16x32_bf16 v[38:41], v[134:137], v[182:185], v[38:41]
	v_mfma_f32_16x16x32_bf16 v[34:37], v[142:145], v[182:185], v[34:37]
	v_mfma_f32_16x16x32_bf16 v[22:25], v[134:137], v[174:177], v[22:25]
	v_mfma_f32_16x16x32_bf16 v[18:21], v[142:145], v[174:177], v[18:21]
	v_mfma_f32_16x16x32_bf16 v[6:9], v[134:137], v[166:169], v[6:9]
	v_mfma_f32_16x16x32_bf16 v[2:5], v[142:145], v[166:169], v[2:5]
	s_setprio 0
	s_barrier
	s_add_i32 s34, 0, 0x18000
	s_add_i32 s35, 0, 0x1c000
	v_add_u32_e32 v142, s34, v246
	v_add_u32_e32 v158, s35, v246
	ds_read_b128 v[130:133], v142
	ds_read_b128 v[134:137], v142 offset:1024
	ds_read_b128 v[138:141], v142 offset:2048
	ds_read_b128 v[142:145], v142 offset:3072
	ds_read_b128 v[146:149], v158
	ds_read_b128 v[150:153], v158 offset:1024
	ds_read_b128 v[154:157], v158 offset:2048
	ds_read_b128 v[158:161], v158 offset:3072
	s_add_u32 s14, s14, 0x40000
	s_addc_u32 s15, s15, 0
	s_mov_b32 m0, s3
	v_lshl_add_u64 v[194:195], s[14:15], 0, v[210:211]
	ds_read_b128 v[162:165], v247 offset:32768
	ds_read_b128 v[166:169], v247 offset:33792
	ds_read_b128 v[170:173], v247 offset:34816
	ds_read_b128 v[174:177], v247 offset:35840
	ds_read_b128 v[178:181], v247 offset:36864
	ds_read_b128 v[182:185], v247 offset:37888
	ds_read_b128 v[186:189], v247 offset:38912
	ds_read_b128 v[190:193], v247 offset:39936
	global_load_lds_dwordx4 v[194:195], off
	v_lshl_add_u64 v[194:195], s[14:15], 0, v[214:215]
	s_mov_b32 m0, s4
	s_nop 0
	global_load_lds_dwordx4 v[194:195], off
	s_waitcnt vmcnt(26)
	s_cmp_eq_u32 s100, 0
	s_cbranch_scc1 .Lthird_wait_relaxed_4
	s_waitcnt vmcnt(8)

; #define PG8_BAR __builtin_amdgcn_s_barrier()
; template <class Epi, class Sched, bool ALIGN_EPI = false, bool SP2 = false>
; __device__ __forceinline__ void gemm_phase(PG8_LAS unsigned char* lds, const Gemm g, const Sched& S, const Epi& E, const int wave_id) {
;     ...
;         if constexpr (ALIGN_EPI) { if (wr == 1) PG8_BAR; }
.LBB0_921:
	s_andn2_b64 vcc, exec, s[52:53]
	s_cbranch_vccnz .LBB0_415
	s_branch .LBB0_415

; #define PG8_STAGE(bufoff, gbase, voff) do { _Pragma("unroll") for (int _i = 0; _i < 2; ++_i) \
;         __builtin_amdgcn_global_load_lds((const unsigned*)((const char*)(gbase) + (voff)[_i]), (PG8_LAS unsigned*)(lds + (bufoff) + ldsw + _i * 8192), 16, 0, 0); } while (0)
; #define PG8_LDA(dst, b, h) do { _Pragma("unroll") for (int m = 0; m < 4; ++m) _Pragma("unroll") for (int k = 0; k < 2; ++k) dst[m][k] = *(const PG8_LAS bf16x8*)(lds + PG8_SA(b, h) + aoff + m * 2048 + k * 1024); } while (0)
; #define PG8_LDB(dst, b, h) do { _Pragma("unroll") for (int n = 0; n < 2; ++n) _Pragma("unroll") for (int k = 0; k < 2; ++k) dst[n][k] = *(const PG8_LAS bf16x8*)(lds + PG8_SB(b, h) + boff + n * 2048 + k * 1024); } while (0)
; #define PG8_MMA(ai, bj, At, Bt) do { __builtin_amdgcn_s_setprio(1); _Pragma("unroll") for (int m = 0; m < 4; ++m) _Pragma("unroll") for (int n = 0; n < 2; ++n) _Pragma("unroll") for (int k = 0; k < 2; ++k) \
;         acc[ai][bj][m][n] = __builtin_amdgcn_mfma_f32_16x16x32_bf16(Bt[n][k], At[m][k], acc[ai][bj][m][n], 0, 0, 0); __builtin_amdgcn_s_setprio(0); } while (0)
; #define PG8_WAIT_V(n) asm volatile("s_waitcnt vmcnt(" #n ")" ::: "memory")
; #define PG8_WAIT_VN(n) asm volatile("s_waitcnt vmcnt(%0)" :: "n"(n) : "memory")
; #define PG8_WAIT_L(n) asm volatile("s_waitcnt lgkmcnt(" #n ")" ::: "memory")
; template <class Epi, class Sched, bool ALIGN_EPI = false, bool SP2 = false>
; __device__ __forceinline__ void gemm_phase(PG8_LAS unsigned char* lds, const Gemm g, const Sched& S, const Epi& E, const int wave_id) {
;     ...
;             PG8_WAIT_VN(8 + Epi::NS); if (strict) PG8_WAIT_V(8); PG8_WAIT_L(0); PG8_BAR; PG8_MMA(1, 0, At, B0); PG8_MMA(1, 1, At, B1); PG8_BAR; PG8_SCHED;
;             PG8_LDB(B0, 1, 0); PG8_LDB(B1, 1, 1); PG8_SCHED; PG8_LDA(At, 1, 0); PG8_STAGE(PG8_SA(0, 1), a2 + hstep, voffA);
;             PG8_WAIT_V(8); PG8_WAIT_L(0); PG8_BAR; PG8_MMA(0, 0, At, B0); PG8_MMA(0, 1, At, B1); PG8_BAR; PG8_SCHED;
;     ...
; #pragma unroll
;         for (int a = 0; a < 2; ++a)
; #pragma unroll
;             for (int b = 0; b < 2; ++b)
; #pragma unroll
;                 for (int m = 0; m < 4; ++m)
; #pragma unroll
;                     for (int n = 0; n < 2; ++n) acc[a][b][m][n] = (f32x4){0.f, 0.f, 0.f, 0.f};
;         }
;         cur = nxt; cA = nA; cB = nB; ++ui;
;         if constexpr (ALIGN_EPI) { if (wr == 1) PG8_BAR; }
.LBB0_1820:
	s_ashr_i32 s11, s10, 31
	s_lshl_b64 s[12:13], s[10:11], 19
	s_add_u32 s12, s31, s12
	s_addc_u32 s13, s34, s13
	s_and_b64 s[14:15], s[6:7], exec
	s_cselect_b32 s11, s13, s19
	s_cselect_b32 s63, s12, s18
	s_ashr_i32 s9, s8, 31
	s_lshl_b64 s[14:15], s[8:9], 19
	s_add_u32 s14, s35, s14
	s_addc_u32 s15, s36, s15
	s_and_b64 s[24:25], s[6:7], exec
	s_cselect_b32 s9, s15, s21
	s_cselect_b32 s67, s14, s20
	s_cmp_eq_u32 s22, 0
	s_cselect_b64 s[22:23], -1, 0
	s_add_u32 s68, s20, 0x100
	s_addc_u32 s69, s21, 0
	s_add_u32 s20, s18, 0x40080
	s_addc_u32 s21, s19, 0
	v_mov_b32_e32 v2, 0
	v_cndmask_b32_e64 v248, 0, 1, s[22:23]
	s_and_b32 s101, s22, 1
	v_lshl_add_u64 v[222:223], s[20:21], 0, v[218:219]
	v_lshl_add_u64 v[224:225], s[20:21], 0, v[220:221]
	s_mov_b32 s74, -2
	s_mov_b64 s[20:21], 0
	v_mov_b32_e32 v3, v2
	v_mov_b64_e32 v[4:5], 0
	v_mov_b64_e32 v[6:7], 0
	v_mov_b64_e32 v[8:9], 0
	v_mov_b64_e32 v[10:11], 0
	v_mov_b64_e32 v[12:13], 0
	v_mov_b64_e32 v[14:15], 0
	v_mov_b64_e32 v[16:17], 0
	v_mov_b64_e32 v[18:19], 0
	v_mov_b64_e32 v[20:21], 0
	v_mov_b64_e32 v[22:23], 0
	v_mov_b64_e32 v[24:25], 0
	v_mov_b64_e32 v[26:27], 0
	v_mov_b64_e32 v[28:29], 0
	v_mov_b64_e32 v[30:31], 0
	v_mov_b64_e32 v[32:33], 0
	v_mov_b64_e32 v[34:35], 0
	v_mov_b64_e32 v[36:37], 0
	v_mov_b64_e32 v[38:39], 0
	v_mov_b64_e32 v[40:41], 0
	v_mov_b64_e32 v[42:43], 0
	v_mov_b64_e32 v[44:45], 0
	v_mov_b64_e32 v[46:47], 0
	v_mov_b64_e32 v[48:49], 0
	v_mov_b64_e32 v[50:51], 0
	v_mov_b64_e32 v[52:53], 0
	v_mov_b64_e32 v[54:55], 0
	v_mov_b64_e32 v[56:57], 0
	v_mov_b64_e32 v[58:59], 0
	v_mov_b64_e32 v[60:61], 0
	v_mov_b64_e32 v[62:63], 0
	v_mov_b64_e32 v[64:65], 0
	v_mov_b64_e32 v[66:67], 0
	v_mov_b64_e32 v[68:69], 0
	v_mov_b64_e32 v[70:71], 0
	v_mov_b64_e32 v[72:73], 0
	v_mov_b64_e32 v[74:75], 0
	v_mov_b64_e32 v[76:77], 0
	v_mov_b64_e32 v[78:79], 0
	v_mov_b64_e32 v[80:81], 0
	v_mov_b64_e32 v[82:83], 0
	v_mov_b64_e32 v[84:85], 0
	v_mov_b64_e32 v[86:87], 0
	v_mov_b64_e32 v[88:89], 0
	v_mov_b64_e32 v[90:91], 0
	v_mov_b64_e32 v[92:93], 0
	v_mov_b64_e32 v[94:95], 0
	v_mov_b64_e32 v[96:97], 0
	v_mov_b64_e32 v[98:99], 0
	v_mov_b64_e32 v[100:101], 0
	v_mov_b64_e32 v[102:103], 0
	v_mov_b64_e32 v[104:105], 0
	v_mov_b64_e32 v[106:107], 0
	v_mov_b64_e32 v[108:109], 0
	v_mov_b64_e32 v[110:111], 0
	v_mov_b64_e32 v[112:113], 0
	v_mov_b64_e32 v[114:115], 0
	v_mov_b64_e32 v[116:117], 0
	v_mov_b64_e32 v[118:119], 0
	v_mov_b64_e32 v[120:121], 0
	v_mov_b64_e32 v[122:123], 0
	v_mov_b64_e32 v[124:125], 0
	v_mov_b64_e32 v[126:127], 0
	v_mov_b64_e32 v[128:129], 0
	s_cmp_eq_u32 s101, 0
	s_cbranch_scc0 .Lskew_skip_2
	s_andn2_b64 vcc, exec, s[2:3]
	s_cbranch_vccnz .Lskew_skip_2
	s_barrier
.Lskew_skip_2:
	s_branch .LBB0_1822
.LBB0_1821:
	s_waitcnt lgkmcnt(0)
	s_barrier
	s_setprio 1
	s_waitcnt lgkmcnt(0)
	v_mfma_f32_16x16x32_bf16 v[62:65], v[146:149], v[186:189], v[62:65]
	v_mfma_f32_16x16x32_bf16 v[58:61], v[154:157], v[186:189], v[58:61]
	v_mfma_f32_16x16x32_bf16 v[46:49], v[146:149], v[178:181], v[46:49]
	v_mfma_f32_16x16x32_bf16 v[42:45], v[154:157], v[178:181], v[42:45]
	v_mfma_f32_16x16x32_bf16 v[30:33], v[146:149], v[170:173], v[30:33]
	v_mfma_f32_16x16x32_bf16 v[26:29], v[154:157], v[170:173], v[26:29]
	v_mfma_f32_16x16x32_bf16 v[14:17], v[146:149], v[162:165], v[14:17]
	v_mfma_f32_16x16x32_bf16 v[10:13], v[154:157], v[162:165], v[10:13]
	v_mfma_f32_16x16x32_bf16 v[62:65], v[150:153], v[190:193], v[62:65]
	v_mfma_f32_16x16x32_bf16 v[58:61], v[158:161], v[190:193], v[58:61]
	v_mfma_f32_16x16x32_bf16 v[46:49], v[150:153], v[182:185], v[46:49]
	v_mfma_f32_16x16x32_bf16 v[42:45], v[158:161], v[182:185], v[42:45]
	v_mfma_f32_16x16x32_bf16 v[30:33], v[150:153], v[174:177], v[30:33]
	v_mfma_f32_16x16x32_bf16 v[26:29], v[158:161], v[174:177], v[26:29]
	v_mfma_f32_16x16x32_bf16 v[14:17], v[150:153], v[166:169], v[14:17]
	v_mfma_f32_16x16x32_bf16 v[10:13], v[158:161], v[166:169], v[10:13]
	s_setprio 0
	s_setprio 1
	v_mfma_f32_16x16x32_bf16 v[54:57], v[130:133], v[186:189], v[54:57]
	v_mfma_f32_16x16x32_bf16 v[50:53], v[138:141], v[186:189], v[50:53]
	v_mfma_f32_16x16x32_bf16 v[38:41], v[130:133], v[178:181], v[38:41]
	v_mfma_f32_16x16x32_bf16 v[34:37], v[138:141], v[178:181], v[34:37]
	v_mfma_f32_16x16x32_bf16 v[22:25], v[130:133], v[170:173], v[22:25]
	v_mfma_f32_16x16x32_bf16 v[18:21], v[138:141], v[170:173], v[18:21]
	v_mfma_f32_16x16x32_bf16 v[6:9], v[130:133], v[162:165], v[6:9]
	v_mfma_f32_16x16x32_bf16 v[2:5], v[138:141], v[162:165], v[2:5]
	v_mfma_f32_16x16x32_bf16 v[54:57], v[134:137], v[190:193], v[54:57]
	v_mfma_f32_16x16x32_bf16 v[50:53], v[142:145], v[190:193], v[50:53]
	v_mfma_f32_16x16x32_bf16 v[38:41], v[134:137], v[182:185], v[38:41]
	v_mfma_f32_16x16x32_bf16 v[34:37], v[142:145], v[182:185], v[34:37]
	v_mfma_f32_16x16x32_bf16 v[22:25], v[134:137], v[174:177], v[22:25]
	v_mfma_f32_16x16x32_bf16 v[18:21], v[142:145], v[174:177], v[18:21]
	v_mfma_f32_16x16x32_bf16 v[6:9], v[134:137], v[166:169], v[6:9]
	v_mfma_f32_16x16x32_bf16 v[2:5], v[142:145], v[166:169], v[2:5]
	s_setprio 0
	s_barrier
	s_add_i32 s26, 0, 0x18000
	s_add_i32 s27, 0, 0x1c000
	v_add_u32_e32 v142, s26, v246
	v_add_u32_e32 v158, s27, v246
	ds_read_b128 v[130:133], v142
	ds_read_b128 v[134:137], v142 offset:1024
	ds_read_b128 v[138:141], v142 offset:2048
	ds_read_b128 v[142:145], v142 offset:3072
	ds_read_b128 v[146:149], v158
	ds_read_b128 v[150:153], v158 offset:1024
	ds_read_b128 v[154:157], v158 offset:2048
	ds_read_b128 v[158:161], v158 offset:3072
	s_add_u32 s24, s24, 0x40000
	s_addc_u32 s25, s25, 0
	s_mov_b32 m0, s50
	v_lshl_add_u64 v[194:195], s[24:25], 0, v[210:211]
	ds_read_b128 v[162:165], v247 offset:32768
	ds_read_b128 v[166:169], v247 offset:33792
	ds_read_b128 v[170:173], v247 offset:34816
	ds_read_b128 v[174:177], v247 offset:35840
	ds_read_b128 v[178:181], v247 offset:36864
	ds_read_b128 v[182:185], v247 offset:37888
	ds_read_b128 v[186:189], v247 offset:38912
	ds_read_b128 v[190:193], v247 offset:39936
	global_load_lds_dwordx4 v[194:195], off
	v_lshl_add_u64 v[194:195], s[24:25], 0, v[214:215]
	s_mov_b32 m0, s51
	s_nop 0
	global_load_lds_dwordx4 v[194:195], off
	s_waitcnt vmcnt(26)
	s_cmp_eq_u32 s100, 0
	s_cbranch_scc1 .Lthird_wait_relaxed_3
	s_waitcnt vmcnt(8)

; #define GAS __attribute__((address_space(1)))
; __device__ __forceinline__ v4u tr4(int a, v4u x) { return (v4u){bperm(a, x.x), bperm(a, x.y), bperm(a, x.z), bperm(a, x.w)}; }
; __device__ __forceinline__ v4u pack8(const f32x4& a, const f32x4& b) { return (v4u){pg8::cvt_pk_bf16(a[0], a[1]), pg8::cvt_pk_bf16(a[2], a[3]), pg8::cvt_pk_bf16(b[0], b[1]), pg8::cvt_pk_bf16(b[2], b[3])}; }
;     __device__ __forceinline__ bool operator()(AccT& acc, const Unit& u, int wr, int wc, int fr, int fq) const {
;         asm volatile("" : "+s"(wr), "+s"(wc), "+v"(fr), "+v"(fq));
;         const LaneT t = lane_t(fr, fq);
;         const bf16* src = (const bf16*)(ws + WS_HB); bf16* dst = (bf16*)(ws + WS_YB);
;         const int row0 = u.pm * 256 + wr * 64 + t.tfr, col0 = u.pn * 256 + wc * 32 + 8 * t.tfq;
; #pragma unroll
;         for (int ai = 0; ai < 2; ++ai)
; #pragma unroll
;             for (int m = 0; m < 4; ++m) { const size_t off = (size_t)(row0 + ai * 128 + m * 16) * D + col0;
; #pragma unroll
;                 for (int bj = 0; bj < 2; ++bj) { const v4u r = tr4(t.push, *(const GAS v4u*)(src + off + bj * 128));
;                     const f32x4 y0 = (f32x4){bflo(r.x), bfhi(r.x), bflo(r.y), bfhi(r.y)} * ca + acc[ai][bj][m][0] * cb, y1 = (f32x4){bflo(r.z), bfhi(r.z), bflo(r.w), bfhi(r.w)} * ca + acc[ai][bj][m][1] * cb;
;                     *(GAS v4u*)(dst + off + bj * 128) = tr4(t.pull, pack8(y0, y1)); } }
.LBB0_1828:
	s_add_u32 s100, s63, 0x40080
	s_addc_u32 s101, s11, 0
	v_lshl_add_u64 v[194:195], s[100:101], 0, v[220:221]
	s_add_i32 m0, s39, 0xc000
	s_nop 0
	global_load_lds_dwordx4 v[194:195], off
	v_lshl_add_u64 v[194:195], s[100:101], 0, v[218:219]
	s_add_i32 m0, s39, 0xe000
	s_nop 0
	global_load_lds_dwordx4 v[194:195], off
	s_mov_b32 s9, s37
	v_mov_b32_e32 v130, v245
	s_mov_b32 s11, s52
	v_mov_b32_e32 v131, v1
	s_lshl_b32 s16, s16, 8
	v_lshl_add_u32 v132, v131, 4, v130
	s_lshl_b32 s9, s9, 6
	v_ashrrev_i32_e32 v134, 2, v132
	v_and_b32_e32 v135, 3, v130
	v_lshlrev_b32_e32 v130, 4, v130
	s_add_i32 s9, s9, s16
	v_lshl_add_u32 v133, v131, 2, v130
	v_add_u32_e32 v130, s9, v134
	s_lshl_b32 s9, s17, 8
	s_lshl_b32 s11, s11, 5
	s_add_i32 s11, s11, s9
	v_and_b32_e32 v132, -4, v132
	v_lshl_or_b32 v134, v135, 3, s11
	v_ashrrev_i32_e32 v131, 31, v130
	v_lshl_add_u32 v132, v135, 6, v132
	v_ashrrev_i32_e32 v135, 31, v134
	v_lshlrev_b64 v[130:131], 10, v[130:131]
	v_lshl_add_u64 v[130:131], v[130:131], 0, v[134:135]
	v_readlane_b32 s18, v253, 11
	v_lshlrev_b64 v[130:131], 1, v[130:131]
	v_readlane_b32 s19, v253, 12
	v_lshl_add_u64 v[140:141], s[60:61], 0, v[130:131]
	s_mov_b64 s[16:17], 0x8000
	v_lshl_add_u64 v[138:139], s[18:19], 0, v[130:131]
	v_mov_b64_e32 v[130:131], v[138:139]
	global_load_dwordx4 v[146:149], v[130:131], off
	s_andn2_b64 vcc, exec, s[6:7]
	global_load_dwordx4 v[150:153], v[130:131], off offset:256
	s_mov_b64 s[16:17], 0x8000
	v_lshl_add_u64 v[130:131], v[138:139], 0, s[16:17]
	global_load_dwordx4 v[154:157], v[130:131], off
	global_load_dwordx4 v[158:161], v[130:131], off offset:256
	s_mov_b64 s[16:17], 0x10000
	v_lshl_add_u64 v[130:131], v[138:139], 0, s[16:17]
	global_load_dwordx4 v[162:165], v[130:131], off
	global_load_dwordx4 v[166:169], v[130:131], off offset:256
	s_mov_b64 s[16:17], 0x18000
	v_lshl_add_u64 v[130:131], v[138:139], 0, s[16:17]
	global_load_dwordx4 v[170:173], v[130:131], off
	global_load_dwordx4 v[174:177], v[130:131], off offset:256
	s_mov_b64 s[16:17], 0x40000
	v_lshl_add_u64 v[130:131], v[138:139], 0, s[16:17]
	global_load_dwordx4 v[178:181], v[130:131], off
	global_load_dwordx4 v[182:185], v[130:131], off offset:256
	s_mov_b64 s[16:17], 0x48000
	v_lshl_add_u64 v[130:131], v[138:139], 0, s[16:17]
	global_load_dwordx4 v[186:189], v[130:131], off
	global_load_dwordx4 v[190:193], v[130:131], off offset:256
	s_waitcnt vmcnt(11)
	ds_bpermute_b32 v143, v133, v147
	ds_bpermute_b32 v142, v133, v146
	ds_bpermute_b32 v145, v133, v149
	ds_bpermute_b32 v144, v133, v148
	v_mov_b64_e32 v[134:135], v[140:141]
	s_waitcnt lgkmcnt(3)
	v_lshlrev_b32_e32 v136, 16, v143
	v_and_b32_e32 v137, 0xffff0000, v143
	s_waitcnt lgkmcnt(2)
	v_and_b32_e32 v143, 0xffff0000, v142
	v_lshlrev_b32_e32 v142, 16, v142
	v_pk_fma_f32 v[128:129], v[136:137], s[96:97], v[128:129] op_sel_hi:[1,0,1]
	v_pk_fma_f32 v[126:127], v[142:143], s[96:97], v[126:127] op_sel_hi:[1,0,1]
	s_waitcnt lgkmcnt(1)
	v_lshlrev_b32_e32 v136, 16, v145
	v_and_b32_e32 v137, 0xffff0000, v145
	s_waitcnt lgkmcnt(0)
	v_and_b32_e32 v145, 0xffff0000, v144
	v_lshlrev_b32_e32 v144, 16, v144
	v_pk_fma_f32 v[124:125], v[136:137], s[96:97], v[124:125] op_sel_hi:[1,0,1]
	v_pk_fma_f32 v[122:123], v[144:145], s[96:97], v[122:123] op_sel_hi:[1,0,1]
	v_cvt_pk_bf16_f32 v126, v126, v127
	v_cvt_pk_bf16_f32 v127, v128, v129
	v_cvt_pk_bf16_f32 v128, v122, v123
	v_cvt_pk_bf16_f32 v125, v124, v125
	s_nop 1
	ds_bpermute_b32 v122, v132, v126
	ds_bpermute_b32 v123, v132, v127
	ds_bpermute_b32 v124, v132, v128
	ds_bpermute_b32 v125, v132, v125
	s_waitcnt lgkmcnt(0)
	global_store_dwordx4 v[134:135], v[122:125], off
	s_mov_b64 s[16:17], 0x50000
	v_lshl_add_u64 v[130:131], v[138:139], 0, s[16:17]
	global_load_dwordx4 v[126:129], v[130:131], off
	s_waitcnt vmcnt(12)
	ds_bpermute_b32 v143, v133, v151
	ds_bpermute_b32 v142, v133, v150
	ds_bpermute_b32 v145, v133, v153
	ds_bpermute_b32 v144, v133, v152
	s_waitcnt lgkmcnt(3)
	v_lshlrev_b32_e32 v136, 16, v143
	v_and_b32_e32 v137, 0xffff0000, v143
	s_waitcnt lgkmcnt(2)
	v_and_b32_e32 v143, 0xffff0000, v142
	v_lshlrev_b32_e32 v142, 16, v142
	v_pk_fma_f32 v[120:121], v[136:137], s[96:97], v[120:121] op_sel_hi:[1,0,1]
	v_pk_fma_f32 v[118:119], v[142:143], s[96:97], v[118:119] op_sel_hi:[1,0,1]
	s_waitcnt lgkmcnt(1)
	v_lshlrev_b32_e32 v136, 16, v145
	v_and_b32_e32 v137, 0xffff0000, v145
	s_waitcnt lgkmcnt(0)
	v_and_b32_e32 v145, 0xffff0000, v144
	v_lshlrev_b32_e32 v144, 16, v144
	v_pk_fma_f32 v[116:117], v[136:137], s[96:97], v[116:117] op_sel_hi:[1,0,1]
	v_pk_fma_f32 v[114:115], v[144:145], s[96:97], v[114:115] op_sel_hi:[1,0,1]
	v_cvt_pk_bf16_f32 v118, v118, v119
	v_cvt_pk_bf16_f32 v119, v120, v121
	v_cvt_pk_bf16_f32 v120, v114, v115
	v_cvt_pk_bf16_f32 v117, v116, v117
	s_nop 1
	ds_bpermute_b32 v114, v132, v118
	ds_bpermute_b32 v115, v132, v119
	ds_bpermute_b32 v116, v132, v120
	ds_bpermute_b32 v117, v132, v117
	s_waitcnt lgkmcnt(0)
	global_store_dwordx4 v[134:135], v[114:117], off offset:256
	global_load_dwordx4 v[118:121], v[130:131], off offset:256
	s_waitcnt vmcnt(13)
	ds_bpermute_b32 v143, v133, v155
	ds_bpermute_b32 v142, v133, v154
	ds_bpermute_b32 v145, v133, v157
	ds_bpermute_b32 v144, v133, v156
	s_mov_b64 s[16:17], 0x8000
	v_lshl_add_u64 v[134:135], v[140:141], 0, s[16:17]
	s_waitcnt lgkmcnt(3)
	v_lshlrev_b32_e32 v136, 16, v143
	v_and_b32_e32 v137, 0xffff0000, v143
	s_waitcnt lgkmcnt(2)
	v_and_b32_e32 v143, 0xffff0000, v142
	v_lshlrev_b32_e32 v142, 16, v142
	v_pk_fma_f32 v[112:113], v[136:137], s[96:97], v[112:113] op_sel_hi:[1,0,1]
	v_pk_fma_f32 v[110:111], v[142:143], s[96:97], v[110:111] op_sel_hi:[1,0,1]
	s_waitcnt lgkmcnt(1)
; #define GAS __attribute__((address_space(1)))
; __device__ __forceinline__ v4u tr4(int a, v4u x) { return (v4u){bperm(a, x.x), bperm(a, x.y), bperm(a, x.z), bperm(a, x.w)}; }
; __device__ __forceinline__ v4u pack8(const f32x4& a, const f32x4& b) { return (v4u){pg8::cvt_pk_bf16(a[0], a[1]), pg8::cvt_pk_bf16(a[2], a[3]), pg8::cvt_pk_bf16(b[0], b[1]), pg8::cvt_pk_bf16(b[2], b[3])}; }
;     __device__ __forceinline__ bool operator()(AccT& acc, const Unit& u, int wr, int wc, int fr, int fq) const {
;     ...
;             for (int m = 0; m < 4; ++m) { const size_t off = (size_t)(row0 + ai * 128 + m * 16) * D + col0;
; #pragma unroll
;                 for (int bj = 0; bj < 2; ++bj) { const v4u r = tr4(t.push, *(const GAS v4u*)(src + off + bj * 128));
;                     const f32x4 y0 = (f32x4){bflo(r.x), bfhi(r.x), bflo(r.y), bfhi(r.y)} * ca + acc[ai][bj][m][0] * cb, y1 = (f32x4){bflo(r.z), bfhi(r.z), bflo(r.w), bfhi(r.w)} * ca + acc[ai][bj][m][1] * cb;
;                     *(GAS v4u*)(dst + off + bj * 128) = tr4(t.pull, pack8(y0, y1)); } }
	v_lshlrev_b32_e32 v136, 16, v145
	v_and_b32_e32 v137, 0xffff0000, v145
	s_waitcnt lgkmcnt(0)
	v_and_b32_e32 v145, 0xffff0000, v144
	v_lshlrev_b32_e32 v144, 16, v144
	v_pk_fma_f32 v[108:109], v[136:137], s[96:97], v[108:109] op_sel_hi:[1,0,1]
	v_pk_fma_f32 v[106:107], v[144:145], s[96:97], v[106:107] op_sel_hi:[1,0,1]
	v_cvt_pk_bf16_f32 v110, v110, v111
	v_cvt_pk_bf16_f32 v111, v112, v113
	v_cvt_pk_bf16_f32 v112, v106, v107
	v_cvt_pk_bf16_f32 v109, v108, v109
	s_nop 1
	ds_bpermute_b32 v106, v132, v110
	ds_bpermute_b32 v107, v132, v111
	ds_bpermute_b32 v108, v132, v112
	ds_bpermute_b32 v109, v132, v109
	s_waitcnt lgkmcnt(0)
	global_store_dwordx4 v[134:135], v[106:109], off
	s_mov_b64 s[16:17], 0x58000
	v_lshl_add_u64 v[130:131], v[138:139], 0, s[16:17]
	global_load_dwordx4 v[110:113], v[130:131], off
	s_waitcnt vmcnt(14)
	ds_bpermute_b32 v143, v133, v159
	ds_bpermute_b32 v142, v133, v158
	ds_bpermute_b32 v145, v133, v161
	ds_bpermute_b32 v144, v133, v160
	s_waitcnt lgkmcnt(3)
	v_lshlrev_b32_e32 v136, 16, v143
	v_and_b32_e32 v137, 0xffff0000, v143
	s_waitcnt lgkmcnt(2)
	v_and_b32_e32 v143, 0xffff0000, v142
	v_lshlrev_b32_e32 v142, 16, v142
	v_pk_fma_f32 v[104:105], v[136:137], s[96:97], v[104:105] op_sel_hi:[1,0,1]
	v_pk_fma_f32 v[102:103], v[142:143], s[96:97], v[102:103] op_sel_hi:[1,0,1]
	s_waitcnt lgkmcnt(1)
	v_lshlrev_b32_e32 v136, 16, v145
	v_and_b32_e32 v137, 0xffff0000, v145
	s_waitcnt lgkmcnt(0)
	v_and_b32_e32 v145, 0xffff0000, v144
	v_lshlrev_b32_e32 v144, 16, v144
	v_pk_fma_f32 v[100:101], v[136:137], s[96:97], v[100:101] op_sel_hi:[1,0,1]
	v_pk_fma_f32 v[98:99], v[144:145], s[96:97], v[98:99] op_sel_hi:[1,0,1]
	v_cvt_pk_bf16_f32 v102, v102, v103
	v_cvt_pk_bf16_f32 v103, v104, v105
	v_cvt_pk_bf16_f32 v104, v98, v99
	v_cvt_pk_bf16_f32 v101, v100, v101
	s_nop 1
	ds_bpermute_b32 v98, v132, v102
	ds_bpermute_b32 v99, v132, v103
	ds_bpermute_b32 v100, v132, v104
	ds_bpermute_b32 v101, v132, v101
	s_waitcnt lgkmcnt(0)
	global_store_dwordx4 v[134:135], v[98:101], off offset:256
	global_load_dwordx4 v[102:105], v[130:131], off offset:256
	s_waitcnt vmcnt(15)
	ds_bpermute_b32 v143, v133, v163
	ds_bpermute_b32 v142, v133, v162
	ds_bpermute_b32 v145, v133, v165
	ds_bpermute_b32 v144, v133, v164
	s_mov_b64 s[16:17], 0x10000
	v_lshl_add_u64 v[134:135], v[140:141], 0, s[16:17]
	s_waitcnt lgkmcnt(3)
	v_lshlrev_b32_e32 v136, 16, v143
	v_and_b32_e32 v137, 0xffff0000, v143
	s_waitcnt lgkmcnt(2)
	v_and_b32_e32 v143, 0xffff0000, v142
	v_lshlrev_b32_e32 v142, 16, v142
	v_pk_fma_f32 v[96:97], v[136:137], s[96:97], v[96:97] op_sel_hi:[1,0,1]
	v_pk_fma_f32 v[94:95], v[142:143], s[96:97], v[94:95] op_sel_hi:[1,0,1]
	s_waitcnt lgkmcnt(1)
	v_lshlrev_b32_e32 v136, 16, v145
	v_and_b32_e32 v137, 0xffff0000, v145
	s_waitcnt lgkmcnt(0)
	v_and_b32_e32 v145, 0xffff0000, v144
	v_lshlrev_b32_e32 v144, 16, v144
	v_pk_fma_f32 v[92:93], v[136:137], s[96:97], v[92:93] op_sel_hi:[1,0,1]
	v_pk_fma_f32 v[90:91], v[144:145], s[96:97], v[90:91] op_sel_hi:[1,0,1]
	v_cvt_pk_bf16_f32 v94, v94, v95
	v_cvt_pk_bf16_f32 v95, v96, v97
	v_cvt_pk_bf16_f32 v96, v90, v91
	v_cvt_pk_bf16_f32 v93, v92, v93
	s_nop 1
	ds_bpermute_b32 v90, v132, v94
	ds_bpermute_b32 v91, v132, v95
	ds_bpermute_b32 v92, v132, v96
	ds_bpermute_b32 v93, v132, v93
	s_waitcnt lgkmcnt(0)
	global_store_dwordx4 v[134:135], v[90:93], off
	s_waitcnt vmcnt(15)
	ds_bpermute_b32 v143, v133, v167
	ds_bpermute_b32 v142, v133, v166
	ds_bpermute_b32 v145, v133, v169
	ds_bpermute_b32 v144, v133, v168
	s_waitcnt lgkmcnt(3)
	v_lshlrev_b32_e32 v136, 16, v143
	v_and_b32_e32 v137, 0xffff0000, v143
	s_waitcnt lgkmcnt(2)
	v_and_b32_e32 v143, 0xffff0000, v142
	v_lshlrev_b32_e32 v142, 16, v142
	v_pk_fma_f32 v[88:89], v[136:137], s[96:97], v[88:89] op_sel_hi:[1,0,1]
	v_pk_fma_f32 v[86:87], v[142:143], s[96:97], v[86:87] op_sel_hi:[1,0,1]
	s_waitcnt lgkmcnt(1)
	v_lshlrev_b32_e32 v136, 16, v145
	v_and_b32_e32 v137, 0xffff0000, v145
	s_waitcnt lgkmcnt(0)
	v_and_b32_e32 v145, 0xffff0000, v144
	v_lshlrev_b32_e32 v144, 16, v144
	v_pk_fma_f32 v[84:85], v[136:137], s[96:97], v[84:85] op_sel_hi:[1,0,1]
	v_pk_fma_f32 v[82:83], v[144:145], s[96:97], v[82:83] op_sel_hi:[1,0,1]
	v_cvt_pk_bf16_f32 v86, v86, v87
	v_cvt_pk_bf16_f32 v87, v88, v89
	v_cvt_pk_bf16_f32 v88, v82, v83
	v_cvt_pk_bf16_f32 v85, v84, v85
	s_nop 1
	ds_bpermute_b32 v82, v132, v86
	ds_bpermute_b32 v83, v132, v87
	ds_bpermute_b32 v84, v132, v88
	ds_bpermute_b32 v85, v132, v85
	s_waitcnt lgkmcnt(0)
	global_store_dwordx4 v[134:135], v[82:85], off offset:256
	s_waitcnt vmcnt(15)
	ds_bpermute_b32 v143, v133, v171
	ds_bpermute_b32 v142, v133, v170
	ds_bpermute_b32 v145, v133, v173
	ds_bpermute_b32 v144, v133, v172
	s_mov_b64 s[16:17], 0x18000
	v_lshl_add_u64 v[134:135], v[140:141], 0, s[16:17]
	s_waitcnt lgkmcnt(3)
	v_lshlrev_b32_e32 v136, 16, v143
	v_and_b32_e32 v137, 0xffff0000, v143
	s_waitcnt lgkmcnt(2)
	v_and_b32_e32 v143, 0xffff0000, v142
	v_lshlrev_b32_e32 v142, 16, v142
	v_pk_fma_f32 v[80:81], v[136:137], s[96:97], v[80:81] op_sel_hi:[1,0,1]
	v_pk_fma_f32 v[78:79], v[142:143], s[96:97], v[78:79] op_sel_hi:[1,0,1]
	s_waitcnt lgkmcnt(1)
	v_lshlrev_b32_e32 v136, 16, v145
	v_and_b32_e32 v137, 0xffff0000, v145
	s_waitcnt lgkmcnt(0)
	v_and_b32_e32 v145, 0xffff0000, v144
	v_lshlrev_b32_e32 v144, 16, v144
	v_pk_fma_f32 v[76:77], v[136:137], s[96:97], v[76:77] op_sel_hi:[1,0,1]
	v_pk_fma_f32 v[74:75], v[144:145], s[96:97], v[74:75] op_sel_hi:[1,0,1]
	v_cvt_pk_bf16_f32 v78, v78, v79
	v_cvt_pk_bf16_f32 v79, v80, v81
	v_cvt_pk_bf16_f32 v80, v74, v75
	v_cvt_pk_bf16_f32 v77, v76, v77
	s_nop 1
	ds_bpermute_b32 v74, v132, v78
	ds_bpermute_b32 v75, v132, v79
	ds_bpermute_b32 v76, v132, v80
	ds_bpermute_b32 v77, v132, v77
	s_waitcnt lgkmcnt(0)
; #define GAS __attribute__((address_space(1)))
; __device__ __forceinline__ v4u tr4(int a, v4u x) { return (v4u){bperm(a, x.x), bperm(a, x.y), bperm(a, x.z), bperm(a, x.w)}; }
; __device__ __forceinline__ v4u pack8(const f32x4& a, const f32x4& b) { return (v4u){pg8::cvt_pk_bf16(a[0], a[1]), pg8::cvt_pk_bf16(a[2], a[3]), pg8::cvt_pk_bf16(b[0], b[1]), pg8::cvt_pk_bf16(b[2], b[3])}; }
;     __device__ __forceinline__ bool operator()(AccT& acc, const Unit& u, int wr, int wc, int fr, int fq) const {
;     ...
;             for (int m = 0; m < 4; ++m) { const size_t off = (size_t)(row0 + ai * 128 + m * 16) * D + col0;
; #pragma unroll
;                 for (int bj = 0; bj < 2; ++bj) { const v4u r = tr4(t.push, *(const GAS v4u*)(src + off + bj * 128));
;                     const f32x4 y0 = (f32x4){bflo(r.x), bfhi(r.x), bflo(r.y), bfhi(r.y)} * ca + acc[ai][bj][m][0] * cb, y1 = (f32x4){bflo(r.z), bfhi(r.z), bflo(r.w), bfhi(r.w)} * ca + acc[ai][bj][m][1] * cb;
;                     *(GAS v4u*)(dst + off + bj * 128) = tr4(t.pull, pack8(y0, y1)); } }
	global_store_dwordx4 v[134:135], v[74:77], off
	s_waitcnt vmcnt(15)
	ds_bpermute_b32 v143, v133, v175
	ds_bpermute_b32 v142, v133, v174
	ds_bpermute_b32 v145, v133, v177
	ds_bpermute_b32 v144, v133, v176
	s_waitcnt lgkmcnt(3)
	v_lshlrev_b32_e32 v136, 16, v143
	v_and_b32_e32 v137, 0xffff0000, v143
	s_waitcnt lgkmcnt(2)
	v_and_b32_e32 v143, 0xffff0000, v142
	v_lshlrev_b32_e32 v142, 16, v142
	v_pk_fma_f32 v[72:73], v[136:137], s[96:97], v[72:73] op_sel_hi:[1,0,1]
	v_pk_fma_f32 v[70:71], v[142:143], s[96:97], v[70:71] op_sel_hi:[1,0,1]
	s_waitcnt lgkmcnt(1)
	v_lshlrev_b32_e32 v136, 16, v145
	v_and_b32_e32 v137, 0xffff0000, v145
	s_waitcnt lgkmcnt(0)
	v_and_b32_e32 v145, 0xffff0000, v144
	v_lshlrev_b32_e32 v144, 16, v144
	v_pk_fma_f32 v[68:69], v[136:137], s[96:97], v[68:69] op_sel_hi:[1,0,1]
	v_pk_fma_f32 v[66:67], v[144:145], s[96:97], v[66:67] op_sel_hi:[1,0,1]
	v_cvt_pk_bf16_f32 v70, v70, v71
	v_cvt_pk_bf16_f32 v71, v72, v73
	v_cvt_pk_bf16_f32 v72, v66, v67
	v_cvt_pk_bf16_f32 v69, v68, v69
	s_nop 1
	ds_bpermute_b32 v66, v132, v70
	ds_bpermute_b32 v67, v132, v71
	ds_bpermute_b32 v68, v132, v72
	ds_bpermute_b32 v69, v132, v69
	s_waitcnt lgkmcnt(0)
	global_store_dwordx4 v[134:135], v[66:69], off offset:256
	s_waitcnt vmcnt(15)
	ds_bpermute_b32 v143, v133, v179
	ds_bpermute_b32 v142, v133, v178
	ds_bpermute_b32 v145, v133, v181
	ds_bpermute_b32 v144, v133, v180
	s_mov_b64 s[16:17], 0x40000
	v_lshl_add_u64 v[134:135], v[140:141], 0, s[16:17]
	s_waitcnt lgkmcnt(3)
	v_lshlrev_b32_e32 v136, 16, v143
	v_and_b32_e32 v137, 0xffff0000, v143
	s_waitcnt lgkmcnt(2)
	v_and_b32_e32 v143, 0xffff0000, v142
	v_lshlrev_b32_e32 v142, 16, v142
	v_pk_fma_f32 v[64:65], v[136:137], s[96:97], v[64:65] op_sel_hi:[1,0,1]
	v_pk_fma_f32 v[62:63], v[142:143], s[96:97], v[62:63] op_sel_hi:[1,0,1]
	s_waitcnt lgkmcnt(1)
	v_lshlrev_b32_e32 v136, 16, v145
	v_and_b32_e32 v137, 0xffff0000, v145
	s_waitcnt lgkmcnt(0)
	v_and_b32_e32 v145, 0xffff0000, v144
	v_lshlrev_b32_e32 v144, 16, v144
	v_pk_fma_f32 v[60:61], v[136:137], s[96:97], v[60:61] op_sel_hi:[1,0,1]
	v_pk_fma_f32 v[58:59], v[144:145], s[96:97], v[58:59] op_sel_hi:[1,0,1]
	v_cvt_pk_bf16_f32 v62, v62, v63
	v_cvt_pk_bf16_f32 v63, v64, v65
	v_cvt_pk_bf16_f32 v64, v58, v59
	v_cvt_pk_bf16_f32 v61, v60, v61
	s_nop 1
	ds_bpermute_b32 v58, v132, v62
	ds_bpermute_b32 v59, v132, v63
	ds_bpermute_b32 v60, v132, v64
	ds_bpermute_b32 v61, v132, v61
	s_waitcnt lgkmcnt(0)
	global_store_dwordx4 v[134:135], v[58:61], off
	s_waitcnt vmcnt(15)
	ds_bpermute_b32 v143, v133, v183
	ds_bpermute_b32 v142, v133, v182
	ds_bpermute_b32 v145, v133, v185
	ds_bpermute_b32 v144, v133, v184
	s_waitcnt lgkmcnt(3)
	v_lshlrev_b32_e32 v136, 16, v143
	v_and_b32_e32 v137, 0xffff0000, v143
	s_waitcnt lgkmcnt(2)
	v_and_b32_e32 v143, 0xffff0000, v142
	v_lshlrev_b32_e32 v142, 16, v142
	v_pk_fma_f32 v[56:57], v[136:137], s[96:97], v[56:57] op_sel_hi:[1,0,1]
	v_pk_fma_f32 v[54:55], v[142:143], s[96:97], v[54:55] op_sel_hi:[1,0,1]
	s_waitcnt lgkmcnt(1)
	v_lshlrev_b32_e32 v136, 16, v145
	v_and_b32_e32 v137, 0xffff0000, v145
	s_waitcnt lgkmcnt(0)
	v_and_b32_e32 v145, 0xffff0000, v144
	v_lshlrev_b32_e32 v144, 16, v144
	v_pk_fma_f32 v[52:53], v[136:137], s[96:97], v[52:53] op_sel_hi:[1,0,1]
	v_pk_fma_f32 v[50:51], v[144:145], s[96:97], v[50:51] op_sel_hi:[1,0,1]
	v_cvt_pk_bf16_f32 v54, v54, v55
	v_cvt_pk_bf16_f32 v55, v56, v57
	v_cvt_pk_bf16_f32 v56, v50, v51
	v_cvt_pk_bf16_f32 v53, v52, v53
	s_nop 1
	ds_bpermute_b32 v50, v132, v54
	ds_bpermute_b32 v51, v132, v55
	ds_bpermute_b32 v52, v132, v56
	ds_bpermute_b32 v53, v132, v53
	s_waitcnt lgkmcnt(0)
	global_store_dwordx4 v[134:135], v[50:53], off offset:256
	s_waitcnt vmcnt(15)
	ds_bpermute_b32 v143, v133, v187
	ds_bpermute_b32 v142, v133, v186
	ds_bpermute_b32 v145, v133, v189
	ds_bpermute_b32 v144, v133, v188
	s_mov_b64 s[16:17], 0x48000
	v_lshl_add_u64 v[134:135], v[140:141], 0, s[16:17]
	s_waitcnt lgkmcnt(3)
	v_lshlrev_b32_e32 v136, 16, v143
	v_and_b32_e32 v137, 0xffff0000, v143
	s_waitcnt lgkmcnt(2)
	v_and_b32_e32 v143, 0xffff0000, v142
	v_lshlrev_b32_e32 v142, 16, v142
	v_pk_fma_f32 v[48:49], v[136:137], s[96:97], v[48:49] op_sel_hi:[1,0,1]
	v_pk_fma_f32 v[46:47], v[142:143], s[96:97], v[46:47] op_sel_hi:[1,0,1]
	s_waitcnt lgkmcnt(1)
	v_lshlrev_b32_e32 v136, 16, v145
	v_and_b32_e32 v137, 0xffff0000, v145
	s_waitcnt lgkmcnt(0)
	v_and_b32_e32 v145, 0xffff0000, v144
	v_lshlrev_b32_e32 v144, 16, v144
	v_pk_fma_f32 v[44:45], v[136:137], s[96:97], v[44:45] op_sel_hi:[1,0,1]
	v_pk_fma_f32 v[42:43], v[144:145], s[96:97], v[42:43] op_sel_hi:[1,0,1]
	v_cvt_pk_bf16_f32 v46, v46, v47
	v_cvt_pk_bf16_f32 v47, v48, v49
	v_cvt_pk_bf16_f32 v48, v42, v43
	v_cvt_pk_bf16_f32 v45, v44, v45
	s_nop 1
	ds_bpermute_b32 v42, v132, v46
	ds_bpermute_b32 v43, v132, v47
	ds_bpermute_b32 v44, v132, v48
	ds_bpermute_b32 v45, v132, v45
	s_waitcnt lgkmcnt(0)
	global_store_dwordx4 v[134:135], v[42:45], off
	s_waitcnt vmcnt(15)
	ds_bpermute_b32 v143, v133, v191
	ds_bpermute_b32 v142, v133, v190
	ds_bpermute_b32 v145, v133, v193
	ds_bpermute_b32 v144, v133, v192
	s_waitcnt lgkmcnt(3)
	v_lshlrev_b32_e32 v136, 16, v143
	v_and_b32_e32 v137, 0xffff0000, v143
	s_waitcnt lgkmcnt(2)
	v_and_b32_e32 v143, 0xffff0000, v142
	v_lshlrev_b32_e32 v142, 16, v142
	v_pk_fma_f32 v[40:41], v[136:137], s[96:97], v[40:41] op_sel_hi:[1,0,1]
	v_pk_fma_f32 v[38:39], v[142:143], s[96:97], v[38:39] op_sel_hi:[1,0,1]
	s_waitcnt lgkmcnt(1)
	v_lshlrev_b32_e32 v136, 16, v145
	v_and_b32_e32 v137, 0xffff0000, v145
	s_waitcnt lgkmcnt(0)
; #define PG8_BAR __builtin_amdgcn_s_barrier()
; #define GAS __attribute__((address_space(1)))
; __device__ __forceinline__ v4u tr4(int a, v4u x) { return (v4u){bperm(a, x.x), bperm(a, x.y), bperm(a, x.z), bperm(a, x.w)}; }
; __device__ __forceinline__ v4u pack8(const f32x4& a, const f32x4& b) { return (v4u){pg8::cvt_pk_bf16(a[0], a[1]), pg8::cvt_pk_bf16(a[2], a[3]), pg8::cvt_pk_bf16(b[0], b[1]), pg8::cvt_pk_bf16(b[2], b[3])}; }
; template <class Epi, class Sched, bool ALIGN_EPI = false, bool SP2 = false>
; __device__ __forceinline__ void gemm_phase(PG8_LAS unsigned char* lds, const Gemm g, const Sched& S, const Epi& E, const int wave_id) {
;     ...
;         if (!has_next) break;
;         if (!keep_acc) {
; #pragma unroll
;         for (int a = 0; a < 2; ++a)
; #pragma unroll
;             for (int b = 0; b < 2; ++b)
; #pragma unroll
;                 for (int m = 0; m < 4; ++m)
; #pragma unroll
;                     for (int n = 0; n < 2; ++n) acc[a][b][m][n] = (f32x4){0.f, 0.f, 0.f, 0.f};
;         }
;         cur = nxt; cA = nA; cB = nB; ++ui;
;         if constexpr (ALIGN_EPI) { if (wr == 1) PG8_BAR; }
;     __device__ __forceinline__ bool operator()(AccT& acc, const Unit& u, int wr, int wc, int fr, int fq) const {
;     ...
;             for (int m = 0; m < 4; ++m) { const size_t off = (size_t)(row0 + ai * 128 + m * 16) * D + col0;
; #pragma unroll
;                 for (int bj = 0; bj < 2; ++bj) { const v4u r = tr4(t.push, *(const GAS v4u*)(src + off + bj * 128));
;                     const f32x4 y0 = (f32x4){bflo(r.x), bfhi(r.x), bflo(r.y), bfhi(r.y)} * ca + acc[ai][bj][m][0] * cb, y1 = (f32x4){bflo(r.z), bfhi(r.z), bflo(r.w), bfhi(r.w)} * ca + acc[ai][bj][m][1] * cb;
;                     *(GAS v4u*)(dst + off + bj * 128) = tr4(t.pull, pack8(y0, y1)); } }
	v_and_b32_e32 v145, 0xffff0000, v144
	v_lshlrev_b32_e32 v144, 16, v144
	v_pk_fma_f32 v[36:37], v[136:137], s[96:97], v[36:37] op_sel_hi:[1,0,1]
	v_pk_fma_f32 v[34:35], v[144:145], s[96:97], v[34:35] op_sel_hi:[1,0,1]
	v_cvt_pk_bf16_f32 v38, v38, v39
	v_cvt_pk_bf16_f32 v39, v40, v41
	v_cvt_pk_bf16_f32 v40, v34, v35
	v_cvt_pk_bf16_f32 v37, v36, v37
	s_nop 1
	ds_bpermute_b32 v34, v132, v38
	ds_bpermute_b32 v35, v132, v39
	ds_bpermute_b32 v36, v132, v40
	ds_bpermute_b32 v37, v132, v37
	s_waitcnt lgkmcnt(0)
	global_store_dwordx4 v[134:135], v[34:37], off offset:256
	s_waitcnt vmcnt(14)
	ds_bpermute_b32 v143, v133, v127
	ds_bpermute_b32 v142, v133, v126
	ds_bpermute_b32 v145, v133, v129
	ds_bpermute_b32 v144, v133, v128
	s_mov_b64 s[16:17], 0x50000
	v_lshl_add_u64 v[134:135], v[140:141], 0, s[16:17]
	s_waitcnt lgkmcnt(3)
	v_lshlrev_b32_e32 v136, 16, v143
	v_and_b32_e32 v137, 0xffff0000, v143
	s_waitcnt lgkmcnt(2)
	v_and_b32_e32 v143, 0xffff0000, v142
	v_lshlrev_b32_e32 v142, 16, v142
	v_pk_fma_f32 v[32:33], v[136:137], s[96:97], v[32:33] op_sel_hi:[1,0,1]
	v_pk_fma_f32 v[30:31], v[142:143], s[96:97], v[30:31] op_sel_hi:[1,0,1]
	s_waitcnt lgkmcnt(1)
	v_lshlrev_b32_e32 v136, 16, v145
	v_and_b32_e32 v137, 0xffff0000, v145
	s_waitcnt lgkmcnt(0)
	v_and_b32_e32 v145, 0xffff0000, v144
	v_lshlrev_b32_e32 v144, 16, v144
	v_pk_fma_f32 v[28:29], v[136:137], s[96:97], v[28:29] op_sel_hi:[1,0,1]
	v_pk_fma_f32 v[26:27], v[144:145], s[96:97], v[26:27] op_sel_hi:[1,0,1]
	v_cvt_pk_bf16_f32 v30, v30, v31
	v_cvt_pk_bf16_f32 v31, v32, v33
	v_cvt_pk_bf16_f32 v32, v26, v27
	v_cvt_pk_bf16_f32 v29, v28, v29
	s_nop 1
	ds_bpermute_b32 v26, v132, v30
	ds_bpermute_b32 v27, v132, v31
	ds_bpermute_b32 v28, v132, v32
	ds_bpermute_b32 v29, v132, v29
	s_waitcnt lgkmcnt(0)
	global_store_dwordx4 v[134:135], v[26:29], off
	s_waitcnt vmcnt(13)
	ds_bpermute_b32 v143, v133, v119
	ds_bpermute_b32 v142, v133, v118
	ds_bpermute_b32 v145, v133, v121
	ds_bpermute_b32 v144, v133, v120
	s_waitcnt lgkmcnt(3)
	v_lshlrev_b32_e32 v136, 16, v143
	v_and_b32_e32 v137, 0xffff0000, v143
	s_waitcnt lgkmcnt(2)
	v_and_b32_e32 v143, 0xffff0000, v142
	v_lshlrev_b32_e32 v142, 16, v142
	v_pk_fma_f32 v[24:25], v[136:137], s[96:97], v[24:25] op_sel_hi:[1,0,1]
	v_pk_fma_f32 v[22:23], v[142:143], s[96:97], v[22:23] op_sel_hi:[1,0,1]
	s_waitcnt lgkmcnt(1)
	v_lshlrev_b32_e32 v136, 16, v145
	v_and_b32_e32 v137, 0xffff0000, v145
	s_waitcnt lgkmcnt(0)
	v_and_b32_e32 v145, 0xffff0000, v144
	v_lshlrev_b32_e32 v144, 16, v144
	v_pk_fma_f32 v[20:21], v[136:137], s[96:97], v[20:21] op_sel_hi:[1,0,1]
	v_pk_fma_f32 v[18:19], v[144:145], s[96:97], v[18:19] op_sel_hi:[1,0,1]
	v_cvt_pk_bf16_f32 v22, v22, v23
	v_cvt_pk_bf16_f32 v23, v24, v25
	v_cvt_pk_bf16_f32 v24, v18, v19
	v_cvt_pk_bf16_f32 v21, v20, v21
	s_nop 1
	ds_bpermute_b32 v18, v132, v22
	ds_bpermute_b32 v19, v132, v23
	ds_bpermute_b32 v20, v132, v24
	ds_bpermute_b32 v21, v132, v21
	s_waitcnt lgkmcnt(0)
	global_store_dwordx4 v[134:135], v[18:21], off offset:256
	s_waitcnt vmcnt(12)
	ds_bpermute_b32 v143, v133, v111
	ds_bpermute_b32 v142, v133, v110
	ds_bpermute_b32 v145, v133, v113
	ds_bpermute_b32 v144, v133, v112
	s_mov_b64 s[16:17], 0x58000
	v_lshl_add_u64 v[134:135], v[140:141], 0, s[16:17]
	s_waitcnt lgkmcnt(3)
	v_lshlrev_b32_e32 v136, 16, v143
	v_and_b32_e32 v137, 0xffff0000, v143
	s_waitcnt lgkmcnt(2)
	v_and_b32_e32 v143, 0xffff0000, v142
	v_lshlrev_b32_e32 v142, 16, v142
	v_pk_fma_f32 v[16:17], v[136:137], s[96:97], v[16:17] op_sel_hi:[1,0,1]
	v_pk_fma_f32 v[14:15], v[142:143], s[96:97], v[14:15] op_sel_hi:[1,0,1]
	s_waitcnt lgkmcnt(1)
	v_lshlrev_b32_e32 v136, 16, v145
	v_and_b32_e32 v137, 0xffff0000, v145
	s_waitcnt lgkmcnt(0)
	v_and_b32_e32 v145, 0xffff0000, v144
	v_lshlrev_b32_e32 v144, 16, v144
	v_pk_fma_f32 v[12:13], v[136:137], s[96:97], v[12:13] op_sel_hi:[1,0,1]
	v_pk_fma_f32 v[10:11], v[144:145], s[96:97], v[10:11] op_sel_hi:[1,0,1]
	v_cvt_pk_bf16_f32 v14, v14, v15
	v_cvt_pk_bf16_f32 v15, v16, v17
	v_cvt_pk_bf16_f32 v16, v10, v11
	v_cvt_pk_bf16_f32 v13, v12, v13
	s_nop 1
	ds_bpermute_b32 v10, v132, v14
	ds_bpermute_b32 v11, v132, v15
	ds_bpermute_b32 v12, v132, v16
	ds_bpermute_b32 v13, v132, v13
	s_waitcnt lgkmcnt(0)
	global_store_dwordx4 v[134:135], v[10:13], off
	s_waitcnt vmcnt(11)
	ds_bpermute_b32 v143, v133, v103
	ds_bpermute_b32 v142, v133, v102
	ds_bpermute_b32 v145, v133, v105
	ds_bpermute_b32 v144, v133, v104
	s_waitcnt lgkmcnt(3)
	v_lshlrev_b32_e32 v136, 16, v143
	v_and_b32_e32 v137, 0xffff0000, v143
	s_waitcnt lgkmcnt(2)
	v_and_b32_e32 v143, 0xffff0000, v142
	v_lshlrev_b32_e32 v142, 16, v142
	v_pk_fma_f32 v[8:9], v[136:137], s[96:97], v[8:9] op_sel_hi:[1,0,1]
	v_pk_fma_f32 v[6:7], v[142:143], s[96:97], v[6:7] op_sel_hi:[1,0,1]
	s_waitcnt lgkmcnt(1)
	v_lshlrev_b32_e32 v136, 16, v145
	v_and_b32_e32 v137, 0xffff0000, v145
	s_waitcnt lgkmcnt(0)
	v_and_b32_e32 v145, 0xffff0000, v144
	v_lshlrev_b32_e32 v144, 16, v144
	v_pk_fma_f32 v[4:5], v[136:137], s[96:97], v[4:5] op_sel_hi:[1,0,1]
	v_pk_fma_f32 v[2:3], v[144:145], s[96:97], v[2:3] op_sel_hi:[1,0,1]
	v_cvt_pk_bf16_f32 v6, v6, v7
	v_cvt_pk_bf16_f32 v7, v8, v9
	v_cvt_pk_bf16_f32 v8, v2, v3
	v_cvt_pk_bf16_f32 v5, v4, v5
	s_nop 1
	ds_bpermute_b32 v2, v132, v6
	ds_bpermute_b32 v3, v132, v7
	ds_bpermute_b32 v4, v132, v8
	ds_bpermute_b32 v5, v132, v5
	s_waitcnt lgkmcnt(0)
	global_store_dwordx4 v[134:135], v[2:5], off offset:256
	s_mov_b64 s[16:17], -1
	s_cbranch_vccnz .LBB0_1813
	s_andn2_b64 vcc, exec, s[2:3]
	s_cbranch_vccnz .LBB0_1812
	s_branch .LBB0_1812

; #define PG8_STAGE(bufoff, gbase, voff) do { _Pragma("unroll") for (int _i = 0; _i < 2; ++_i) \
;         __builtin_amdgcn_global_load_lds((const unsigned*)((const char*)(gbase) + (voff)[_i]), (PG8_LAS unsigned*)(lds + (bufoff) + ldsw + _i * 8192), 16, 0, 0); } while (0)
; #define PG8_LDA(dst, b, h) do { _Pragma("unroll") for (int m = 0; m < 4; ++m) _Pragma("unroll") for (int k = 0; k < 2; ++k) dst[m][k] = *(const PG8_LAS bf16x8*)(lds + PG8_SA(b, h) + aoff + m * 2048 + k * 1024); } while (0)
; #define PG8_LDB(dst, b, h) do { _Pragma("unroll") for (int n = 0; n < 2; ++n) _Pragma("unroll") for (int k = 0; k < 2; ++k) dst[n][k] = *(const PG8_LAS bf16x8*)(lds + PG8_SB(b, h) + boff + n * 2048 + k * 1024); } while (0)
; #define PG8_MMA(ai, bj, At, Bt) do { __builtin_amdgcn_s_setprio(1); _Pragma("unroll") for (int m = 0; m < 4; ++m) _Pragma("unroll") for (int n = 0; n < 2; ++n) _Pragma("unroll") for (int k = 0; k < 2; ++k) \
;         acc[ai][bj][m][n] = __builtin_amdgcn_mfma_f32_16x16x32_bf16(Bt[n][k], At[m][k], acc[ai][bj][m][n], 0, 0, 0); __builtin_amdgcn_s_setprio(0); } while (0)
; #define PG8_WAIT_V(n) asm volatile("s_waitcnt vmcnt(" #n ")" ::: "memory")
; #define PG8_WAIT_VN(n) asm volatile("s_waitcnt vmcnt(%0)" :: "n"(n) : "memory")
; #define PG8_WAIT_L(n) asm volatile("s_waitcnt lgkmcnt(" #n ")" ::: "memory")
; template <class Epi, class Sched, bool ALIGN_EPI = false, bool SP2 = false>
; __device__ __forceinline__ void gemm_phase(PG8_LAS unsigned char* lds, const Gemm g, const Sched& S, const Epi& E, const int wave_id) {
;     ...
;             PG8_WAIT_VN(8 + Epi::NS); if (strict) PG8_WAIT_V(8); PG8_WAIT_L(0); PG8_BAR; PG8_MMA(1, 0, At, B0); PG8_MMA(1, 1, At, B1); PG8_BAR; PG8_SCHED;
;             PG8_LDB(B0, 1, 0); PG8_LDB(B1, 1, 1); PG8_SCHED; PG8_LDA(At, 1, 0); PG8_STAGE(PG8_SA(0, 1), a2 + hstep, voffA);
;             PG8_WAIT_V(8); PG8_WAIT_L(0); PG8_BAR; PG8_MMA(0, 0, At, B0); PG8_MMA(0, 1, At, B1); PG8_BAR; PG8_SCHED;
;     ...
; #pragma unroll
;         for (int a = 0; a < 2; ++a)
; #pragma unroll
;             for (int b = 0; b < 2; ++b)
; #pragma unroll
;                 for (int m = 0; m < 4; ++m)
; #pragma unroll
;                     for (int n = 0; n < 2; ++n) acc[a][b][m][n] = (f32x4){0.f, 0.f, 0.f, 0.f};
;         }
;         cur = nxt; cA = nA; cB = nB; ++ui;
;         if constexpr (ALIGN_EPI) { if (wr == 1) PG8_BAR; }
.LBB0_1951:
	s_ashr_i32 s13, s12, 31
	s_lshl_b64 s[14:15], s[12:13], 19
	s_add_u32 s14, s34, s14
	s_addc_u32 s15, s35, s15
	s_and_b64 s[16:17], s[6:7], exec
	s_cselect_b32 s13, s15, s21
	s_cselect_b32 s68, s14, s20
	s_ashr_i32 s11, s10, 31
	s_lshl_b64 s[16:17], s[10:11], 19
	s_add_u32 s16, s36, s16
	s_addc_u32 s17, s37, s17
	s_and_b64 s[26:27], s[6:7], exec
	s_cselect_b32 s11, s17, s23
	s_cselect_b32 s69, s16, s22
	s_cmp_eq_u32 s24, 0
	s_cselect_b64 s[24:25], -1, 0
	s_add_u32 s74, s22, 0x100
	s_addc_u32 s75, s23, 0
	s_add_u32 s22, s20, 0x40080
	s_addc_u32 s23, s21, 0
	v_mov_b32_e32 v2, 0
	v_cndmask_b32_e64 v248, 0, 1, s[24:25]
	s_and_b32 s101, s24, 1
	v_lshl_add_u64 v[222:223], s[22:23], 0, v[218:219]
	v_lshl_add_u64 v[224:225], s[22:23], 0, v[220:221]
	s_mov_b32 s76, -2
	s_mov_b64 s[22:23], 0
	v_mov_b32_e32 v3, v2
	v_mov_b64_e32 v[4:5], 0
	v_mov_b64_e32 v[6:7], 0
	v_mov_b64_e32 v[8:9], 0
	v_mov_b64_e32 v[10:11], 0
	v_mov_b64_e32 v[12:13], 0
	v_mov_b64_e32 v[14:15], 0
	v_mov_b64_e32 v[16:17], 0
	v_mov_b64_e32 v[18:19], 0
	v_mov_b64_e32 v[20:21], 0
	v_mov_b64_e32 v[22:23], 0
	v_mov_b64_e32 v[24:25], 0
	v_mov_b64_e32 v[26:27], 0
	v_mov_b64_e32 v[28:29], 0
	v_mov_b64_e32 v[30:31], 0
	v_mov_b64_e32 v[32:33], 0
	v_mov_b64_e32 v[34:35], 0
	v_mov_b64_e32 v[36:37], 0
	v_mov_b64_e32 v[38:39], 0
	v_mov_b64_e32 v[40:41], 0
	v_mov_b64_e32 v[42:43], 0
	v_mov_b64_e32 v[44:45], 0
	v_mov_b64_e32 v[46:47], 0
	v_mov_b64_e32 v[48:49], 0
	v_mov_b64_e32 v[50:51], 0
	v_mov_b64_e32 v[52:53], 0
	v_mov_b64_e32 v[54:55], 0
	v_mov_b64_e32 v[56:57], 0
	v_mov_b64_e32 v[58:59], 0
	v_mov_b64_e32 v[60:61], 0
	v_mov_b64_e32 v[62:63], 0
	v_mov_b64_e32 v[64:65], 0
	v_mov_b64_e32 v[66:67], 0
	v_mov_b64_e32 v[68:69], 0
	v_mov_b64_e32 v[70:71], 0
	v_mov_b64_e32 v[72:73], 0
	v_mov_b64_e32 v[74:75], 0
	v_mov_b64_e32 v[76:77], 0
	v_mov_b64_e32 v[78:79], 0
	v_mov_b64_e32 v[80:81], 0
	v_mov_b64_e32 v[82:83], 0
	v_mov_b64_e32 v[84:85], 0
	v_mov_b64_e32 v[86:87], 0
	v_mov_b64_e32 v[88:89], 0
	v_mov_b64_e32 v[90:91], 0
	v_mov_b64_e32 v[92:93], 0
	v_mov_b64_e32 v[94:95], 0
	v_mov_b64_e32 v[96:97], 0
	v_mov_b64_e32 v[98:99], 0
	v_mov_b64_e32 v[100:101], 0
	v_mov_b64_e32 v[102:103], 0
	v_mov_b64_e32 v[104:105], 0
	v_mov_b64_e32 v[106:107], 0
	v_mov_b64_e32 v[108:109], 0
	v_mov_b64_e32 v[110:111], 0
	v_mov_b64_e32 v[112:113], 0
	v_mov_b64_e32 v[114:115], 0
	v_mov_b64_e32 v[116:117], 0
	v_mov_b64_e32 v[118:119], 0
	v_mov_b64_e32 v[120:121], 0
	v_mov_b64_e32 v[122:123], 0
	v_mov_b64_e32 v[124:125], 0
	v_mov_b64_e32 v[126:127], 0
	v_mov_b64_e32 v[128:129], 0
	s_cmp_eq_u32 s101, 0
	s_cbranch_scc0 .Lskew_skip_1
	s_andn2_b64 vcc, exec, s[2:3]
	s_cbranch_vccnz .Lskew_skip_1
	s_barrier
.Lskew_skip_1:
	s_branch .LBB0_1953
.LBB0_1952:
	s_waitcnt lgkmcnt(0)
	s_barrier
	s_setprio 1
	s_waitcnt lgkmcnt(0)
	v_mfma_f32_16x16x32_bf16 v[62:65], v[146:149], v[186:189], v[62:65]
	v_mfma_f32_16x16x32_bf16 v[58:61], v[154:157], v[186:189], v[58:61]
	v_mfma_f32_16x16x32_bf16 v[54:57], v[146:149], v[178:181], v[54:57]
	v_mfma_f32_16x16x32_bf16 v[50:53], v[154:157], v[178:181], v[50:53]
	v_mfma_f32_16x16x32_bf16 v[30:33], v[146:149], v[170:173], v[30:33]
	v_mfma_f32_16x16x32_bf16 v[26:29], v[154:157], v[170:173], v[26:29]
	v_mfma_f32_16x16x32_bf16 v[22:25], v[146:149], v[162:165], v[22:25]
	v_mfma_f32_16x16x32_bf16 v[18:21], v[154:157], v[162:165], v[18:21]
	v_mfma_f32_16x16x32_bf16 v[62:65], v[150:153], v[190:193], v[62:65]
	v_mfma_f32_16x16x32_bf16 v[58:61], v[158:161], v[190:193], v[58:61]
	v_mfma_f32_16x16x32_bf16 v[54:57], v[150:153], v[182:185], v[54:57]
	v_mfma_f32_16x16x32_bf16 v[50:53], v[158:161], v[182:185], v[50:53]
	v_mfma_f32_16x16x32_bf16 v[30:33], v[150:153], v[174:177], v[30:33]
	v_mfma_f32_16x16x32_bf16 v[26:29], v[158:161], v[174:177], v[26:29]
	v_mfma_f32_16x16x32_bf16 v[22:25], v[150:153], v[166:169], v[22:25]
	v_mfma_f32_16x16x32_bf16 v[18:21], v[158:161], v[166:169], v[18:21]
	s_setprio 0
	s_setprio 1
	v_mfma_f32_16x16x32_bf16 v[46:49], v[130:133], v[186:189], v[46:49]
	v_mfma_f32_16x16x32_bf16 v[42:45], v[138:141], v[186:189], v[42:45]
	v_mfma_f32_16x16x32_bf16 v[38:41], v[130:133], v[178:181], v[38:41]
	v_mfma_f32_16x16x32_bf16 v[34:37], v[138:141], v[178:181], v[34:37]
	v_mfma_f32_16x16x32_bf16 v[14:17], v[130:133], v[170:173], v[14:17]
	v_mfma_f32_16x16x32_bf16 v[10:13], v[138:141], v[170:173], v[10:13]
	v_mfma_f32_16x16x32_bf16 v[6:9], v[130:133], v[162:165], v[6:9]
	v_mfma_f32_16x16x32_bf16 v[2:5], v[138:141], v[162:165], v[2:5]
	v_mfma_f32_16x16x32_bf16 v[46:49], v[134:137], v[190:193], v[46:49]
	v_mfma_f32_16x16x32_bf16 v[42:45], v[142:145], v[190:193], v[42:45]
	v_mfma_f32_16x16x32_bf16 v[38:41], v[134:137], v[182:185], v[38:41]
	v_mfma_f32_16x16x32_bf16 v[34:37], v[142:145], v[182:185], v[34:37]
	v_mfma_f32_16x16x32_bf16 v[14:17], v[134:137], v[174:177], v[14:17]
	v_mfma_f32_16x16x32_bf16 v[10:13], v[142:145], v[174:177], v[10:13]
	v_mfma_f32_16x16x32_bf16 v[6:9], v[134:137], v[166:169], v[6:9]
	v_mfma_f32_16x16x32_bf16 v[2:5], v[142:145], v[166:169], v[2:5]
	s_setprio 0
	s_barrier
	s_add_i32 s28, 0, 0x18000
	s_add_i32 s29, 0, 0x1c000
	v_add_u32_e32 v142, s28, v246
	v_add_u32_e32 v158, s29, v246
	ds_read_b128 v[130:133], v142
	ds_read_b128 v[134:137], v142 offset:1024
	ds_read_b128 v[138:141], v142 offset:2048
	ds_read_b128 v[142:145], v142 offset:3072
	ds_read_b128 v[146:149], v158
	ds_read_b128 v[150:153], v158 offset:1024
	ds_read_b128 v[154:157], v158 offset:2048
	ds_read_b128 v[158:161], v158 offset:3072
	s_add_u32 s26, s26, 0x40000
	s_addc_u32 s27, s27, 0
	s_mov_b32 m0, s52
	v_lshl_add_u64 v[194:195], s[26:27], 0, v[216:217]
	ds_read_b128 v[162:165], v247 offset:32768
	ds_read_b128 v[166:169], v247 offset:33792
	ds_read_b128 v[170:173], v247 offset:34816
	ds_read_b128 v[174:177], v247 offset:35840
	ds_read_b128 v[178:181], v247 offset:36864
	ds_read_b128 v[182:185], v247 offset:37888
	ds_read_b128 v[186:189], v247 offset:38912
	ds_read_b128 v[190:193], v247 offset:39936
	global_load_lds_dwordx4 v[194:195], off
	v_lshl_add_u64 v[194:195], s[26:27], 0, v[212:213]
	s_mov_b32 m0, s54
	s_nop 0
	global_load_lds_dwordx4 v[194:195], off
	s_waitcnt vmcnt(18)
	s_cmp_eq_u32 s100, 0
	s_cbranch_scc1 .Lthird_wait_relaxed_2
	s_waitcnt vmcnt(8)

; __device__ __forceinline__ unsigned cvt_pk_bf16(float lo, float hi) { unsigned r; asm volatile("v_cvt_pk_bf16_f32 %0, %1, %2" : "=v"(r) : "v"(lo), "v"(hi)); return r; }
; #define GAS __attribute__((address_space(1)))
; __device__ __forceinline__ float siluf_(float x) { return x * sigmoidf_(x); }
;     __device__ __forceinline__ bool operator()(AccT& acc, const Unit& u, int wr, int wc, int fr, int fq) const {
;         asm volatile("" : "+s"(wr), "+s"(wc), "+v"(fr), "+v"(fq));
;         const int row0 = u.pm * 256 + wr * 64 + fr + 16 * (fq & 1), col0 = u.pn * 128 + wc * 16 + 4 * (fq & 2);
; #pragma unroll
;         for (int ai = 0; ai < 2; ++ai)
; #pragma unroll
;             for (int mp = 0; mp < 2; ++mp) { bf16* rowp = act + (size_t)(row0 + ai * 128 + mp * 32) * DFF + col0;
; #pragma unroll
;                 for (int bj = 0; bj < 2; ++bj) { unsigned pk[2][2];
; #pragma unroll
;                     for (int k = 0; k < 2; ++k) { const f32x4 g = acc[ai][bj][2 * mp + k][0], up = acc[ai][bj][2 * mp + k][1];
;                         pk[k][0] = pg8::cvt_pk_bf16(siluf_(g[0]) * up[0], siluf_(g[1]) * up[1]); pk[k][1] = pg8::cvt_pk_bf16(siluf_(g[2]) * up[2], siluf_(g[3]) * up[3]); }
;                     const auto sx = __builtin_amdgcn_permlane16_swap(pk[0][0], pk[1][0], false, false), sy = __builtin_amdgcn_permlane16_swap(pk[0][1], pk[1][1], false, false);
;                     *(GAS v4u*)(rowp + bj * 64) = (v4u){sx[0], sy[0], sx[1], sy[1]}; } }
.LBB0_1959:
	s_add_u32 s100, s68, 0x40080
	s_addc_u32 s101, s13, 0
	v_lshl_add_u64 v[194:195], s[100:101], 0, v[220:221]
	s_add_i32 m0, s41, 0xc000
	s_nop 0
	global_load_lds_dwordx4 v[194:195], off
	v_lshl_add_u64 v[194:195], s[100:101], 0, v[218:219]
	s_add_i32 m0, s41, 0xe000
	s_nop 0
	global_load_lds_dwordx4 v[194:195], off
	s_mov_b32 s100, 0xbfb8aa3b
	s_mov_b32 s101, 0xbfb8aa3b
	s_mov_b32 s11, s56
	v_mov_b32_e32 v130, v245
	s_mov_b32 s13, s38
	v_mov_b32_e32 v131, v1
	s_lshl_b32 s19, s19, 7
	s_lshl_b32 s11, s11, 4
	s_lshl_b32 s18, s18, 8
	s_lshl_b32 s13, s13, 6
	v_lshlrev_b32_e32 v132, 4, v130
	s_add_i32 s11, s11, s19
	v_lshlrev_b32_e32 v130, 2, v130
	v_and_b32_e32 v133, 16, v132
	v_and_or_b32 v132, v130, 8, s11
	s_add_i32 s13, s13, s18
	v_add3_u32 v136, s13, v131, v133
	v_ashrrev_i32_e32 v133, 31, v132
	v_mov_b64_e32 v[130:131], s[4:5]
	s_movk_i32 s11, 0x1600
	v_mad_i64_i32 v[134:135], s[18:19], v136, s11, v[130:131]
	v_lshlrev_b64 v[132:133], 1, v[132:133]
	v_lshl_add_u64 v[134:135], v[134:135], 0, v[132:133]
	s_andn2_b64 vcc, exec, s[6:7]
	v_pk_mul_f32 v[138:139], v[126:127], s[100:101]
	v_pk_mul_f32 v[140:141], v[128:129], s[100:101]
	v_pk_mul_f32 v[142:143], v[118:119], s[100:101]
	v_pk_mul_f32 v[144:145], v[120:121], s[100:101]
	v_exp_f32_e32 v138, v138
	v_exp_f32_e32 v139, v139
	v_exp_f32_e32 v140, v140
	v_exp_f32_e32 v141, v141
	v_exp_f32_e32 v142, v142
	v_exp_f32_e32 v143, v143
	v_exp_f32_e32 v144, v144
	v_exp_f32_e32 v145, v145
	v_pk_add_f32 v[138:139], v[138:139], 1.0 op_sel_hi:[1,0]
	v_pk_add_f32 v[140:141], v[140:141], 1.0 op_sel_hi:[1,0]
	v_pk_add_f32 v[142:143], v[142:143], 1.0 op_sel_hi:[1,0]
	v_pk_add_f32 v[144:145], v[144:145], 1.0 op_sel_hi:[1,0]
	v_rcp_f32_e32 v138, v138
	v_rcp_f32_e32 v139, v139
	v_rcp_f32_e32 v140, v140
	v_rcp_f32_e32 v141, v141
	v_rcp_f32_e32 v142, v142
	v_rcp_f32_e32 v143, v143
	v_rcp_f32_e32 v144, v144
	v_rcp_f32_e32 v145, v145
	v_pk_mul_f32 v[126:127], v[126:127], v[138:139]
	v_pk_mul_f32 v[128:129], v[128:129], v[140:141]
	v_pk_mul_f32 v[118:119], v[118:119], v[142:143]
	v_pk_mul_f32 v[120:121], v[120:121], v[144:145]
	v_pk_mul_f32 v[122:123], v[122:123], v[126:127]
	v_pk_mul_f32 v[124:125], v[124:125], v[128:129]
	v_pk_mul_f32 v[114:115], v[114:115], v[118:119]
	v_pk_mul_f32 v[116:117], v[116:117], v[120:121]
	v_cvt_pk_bf16_f32 v122, v122, v123
	v_cvt_pk_bf16_f32 v123, v124, v125
	v_cvt_pk_bf16_f32 v124, v114, v115
	v_cvt_pk_bf16_f32 v125, v116, v117
	s_nop 1
	v_permlane16_swap_b32_e32 v122, v124
	v_permlane16_swap_b32_e32 v123, v125
	global_store_dwordx4 v[134:135], v[122:125], off
	v_pk_mul_f32 v[138:139], v[110:111], s[100:101]
	v_pk_mul_f32 v[140:141], v[112:113], s[100:101]
	v_pk_mul_f32 v[142:143], v[102:103], s[100:101]
	v_pk_mul_f32 v[144:145], v[104:105], s[100:101]
	v_exp_f32_e32 v138, v138
	v_exp_f32_e32 v139, v139
	v_exp_f32_e32 v140, v140
	v_exp_f32_e32 v141, v141
	v_exp_f32_e32 v142, v142
	v_exp_f32_e32 v143, v143
	v_exp_f32_e32 v144, v144
	v_exp_f32_e32 v145, v145
	v_pk_add_f32 v[138:139], v[138:139], 1.0 op_sel_hi:[1,0]
	v_pk_add_f32 v[140:141], v[140:141], 1.0 op_sel_hi:[1,0]
	v_pk_add_f32 v[142:143], v[142:143], 1.0 op_sel_hi:[1,0]
	v_pk_add_f32 v[144:145], v[144:145], 1.0 op_sel_hi:[1,0]
	v_rcp_f32_e32 v138, v138
	v_rcp_f32_e32 v139, v139
	v_rcp_f32_e32 v140, v140
	v_rcp_f32_e32 v141, v141
	v_rcp_f32_e32 v142, v142
	v_rcp_f32_e32 v143, v143
	v_rcp_f32_e32 v144, v144
	v_rcp_f32_e32 v145, v145
	v_pk_mul_f32 v[110:111], v[110:111], v[138:139]
	v_pk_mul_f32 v[112:113], v[112:113], v[140:141]
	v_pk_mul_f32 v[102:103], v[102:103], v[142:143]
	v_pk_mul_f32 v[104:105], v[104:105], v[144:145]
	v_pk_mul_f32 v[106:107], v[106:107], v[110:111]
	v_pk_mul_f32 v[108:109], v[108:109], v[112:113]
	v_pk_mul_f32 v[98:99], v[98:99], v[102:103]
	v_pk_mul_f32 v[100:101], v[100:101], v[104:105]
	v_cvt_pk_bf16_f32 v106, v106, v107
	v_cvt_pk_bf16_f32 v107, v108, v109
	v_cvt_pk_bf16_f32 v108, v98, v99
	v_cvt_pk_bf16_f32 v109, v100, v101
	s_nop 1
	v_permlane16_swap_b32_e32 v106, v108
	v_permlane16_swap_b32_e32 v107, v109
	global_store_dwordx4 v[134:135], v[106:109], off offset:128
	v_add_u32_e32 v98, 32, v136
	v_mad_i64_i32 v[98:99], s[18:19], v98, s11, v[130:131]
	v_lshl_add_u64 v[98:99], v[98:99], 0, v[132:133]
	v_pk_mul_f32 v[138:139], v[94:95], s[100:101]
	v_pk_mul_f32 v[140:141], v[96:97], s[100:101]
	v_pk_mul_f32 v[142:143], v[86:87], s[100:101]
	v_pk_mul_f32 v[144:145], v[88:89], s[100:101]
	v_exp_f32_e32 v138, v138
	v_exp_f32_e32 v139, v139
	v_exp_f32_e32 v140, v140
	v_exp_f32_e32 v141, v141
	v_exp_f32_e32 v142, v142
	v_exp_f32_e32 v143, v143
	v_exp_f32_e32 v144, v144
	v_exp_f32_e32 v145, v145
	v_pk_add_f32 v[138:139], v[138:139], 1.0 op_sel_hi:[1,0]
	v_pk_add_f32 v[140:141], v[140:141], 1.0 op_sel_hi:[1,0]
	v_pk_add_f32 v[142:143], v[142:143], 1.0 op_sel_hi:[1,0]
	v_pk_add_f32 v[144:145], v[144:145], 1.0 op_sel_hi:[1,0]
	v_rcp_f32_e32 v138, v138
	v_rcp_f32_e32 v139, v139
	v_rcp_f32_e32 v140, v140
	v_rcp_f32_e32 v141, v141
	v_rcp_f32_e32 v142, v142
	v_rcp_f32_e32 v143, v143
	v_rcp_f32_e32 v144, v144
	v_rcp_f32_e32 v145, v145
	v_pk_mul_f32 v[94:95], v[94:95], v[138:139]
	v_pk_mul_f32 v[96:97], v[96:97], v[140:141]
	v_pk_mul_f32 v[86:87], v[86:87], v[142:143]
	v_pk_mul_f32 v[88:89], v[88:89], v[144:145]
	v_pk_mul_f32 v[90:91], v[90:91], v[94:95]
	v_pk_mul_f32 v[92:93], v[92:93], v[96:97]
	v_pk_mul_f32 v[82:83], v[82:83], v[86:87]
	v_pk_mul_f32 v[84:85], v[84:85], v[88:89]
	v_cvt_pk_bf16_f32 v90, v90, v91
	v_cvt_pk_bf16_f32 v91, v92, v93
	v_cvt_pk_bf16_f32 v92, v82, v83
	v_cvt_pk_bf16_f32 v93, v84, v85
	s_nop 1
	v_permlane16_swap_b32_e32 v90, v92
	v_permlane16_swap_b32_e32 v91, v93
; __device__ __forceinline__ unsigned cvt_pk_bf16(float lo, float hi) { unsigned r; asm volatile("v_cvt_pk_bf16_f32 %0, %1, %2" : "=v"(r) : "v"(lo), "v"(hi)); return r; }
; #define GAS __attribute__((address_space(1)))
; __device__ __forceinline__ float siluf_(float x) { return x * sigmoidf_(x); }
;     __device__ __forceinline__ bool operator()(AccT& acc, const Unit& u, int wr, int wc, int fr, int fq) const {
;     ...
;             for (int mp = 0; mp < 2; ++mp) { bf16* rowp = act + (size_t)(row0 + ai * 128 + mp * 32) * DFF + col0;
; #pragma unroll
;                 for (int bj = 0; bj < 2; ++bj) { unsigned pk[2][2];
; #pragma unroll
;                     for (int k = 0; k < 2; ++k) { const f32x4 g = acc[ai][bj][2 * mp + k][0], up = acc[ai][bj][2 * mp + k][1];
;                         pk[k][0] = pg8::cvt_pk_bf16(siluf_(g[0]) * up[0], siluf_(g[1]) * up[1]); pk[k][1] = pg8::cvt_pk_bf16(siluf_(g[2]) * up[2], siluf_(g[3]) * up[3]); }
;                     const auto sx = __builtin_amdgcn_permlane16_swap(pk[0][0], pk[1][0], false, false), sy = __builtin_amdgcn_permlane16_swap(pk[0][1], pk[1][1], false, false);
;                     *(GAS v4u*)(rowp + bj * 64) = (v4u){sx[0], sy[0], sx[1], sy[1]}; } }
	global_store_dwordx4 v[98:99], v[90:93], off
	v_pk_mul_f32 v[138:139], v[78:79], s[100:101]
	v_pk_mul_f32 v[140:141], v[80:81], s[100:101]
	v_pk_mul_f32 v[142:143], v[70:71], s[100:101]
	v_pk_mul_f32 v[144:145], v[72:73], s[100:101]
	v_exp_f32_e32 v138, v138
	v_exp_f32_e32 v139, v139
	v_exp_f32_e32 v140, v140
	v_exp_f32_e32 v141, v141
	v_exp_f32_e32 v142, v142
	v_exp_f32_e32 v143, v143
	v_exp_f32_e32 v144, v144
	v_exp_f32_e32 v145, v145
	v_pk_add_f32 v[138:139], v[138:139], 1.0 op_sel_hi:[1,0]
	v_pk_add_f32 v[140:141], v[140:141], 1.0 op_sel_hi:[1,0]
	v_pk_add_f32 v[142:143], v[142:143], 1.0 op_sel_hi:[1,0]
	v_pk_add_f32 v[144:145], v[144:145], 1.0 op_sel_hi:[1,0]
	v_rcp_f32_e32 v138, v138
	v_rcp_f32_e32 v139, v139
	v_rcp_f32_e32 v140, v140
	v_rcp_f32_e32 v141, v141
	v_rcp_f32_e32 v142, v142
	v_rcp_f32_e32 v143, v143
	v_rcp_f32_e32 v144, v144
	v_rcp_f32_e32 v145, v145
	v_pk_mul_f32 v[78:79], v[78:79], v[138:139]
	v_pk_mul_f32 v[80:81], v[80:81], v[140:141]
	v_pk_mul_f32 v[70:71], v[70:71], v[142:143]
	v_pk_mul_f32 v[72:73], v[72:73], v[144:145]
	v_pk_mul_f32 v[74:75], v[74:75], v[78:79]
	v_pk_mul_f32 v[76:77], v[76:77], v[80:81]
	v_pk_mul_f32 v[66:67], v[66:67], v[70:71]
	v_pk_mul_f32 v[68:69], v[68:69], v[72:73]
	v_cvt_pk_bf16_f32 v74, v74, v75
	v_cvt_pk_bf16_f32 v75, v76, v77
	v_cvt_pk_bf16_f32 v76, v66, v67
	v_cvt_pk_bf16_f32 v77, v68, v69
	s_nop 1
	v_permlane16_swap_b32_e32 v74, v76
	v_permlane16_swap_b32_e32 v75, v77
	global_store_dwordx4 v[98:99], v[74:77], off offset:128
	v_add_u32_e32 v66, 0x80, v136
	v_mad_i64_i32 v[66:67], s[18:19], v66, s11, v[130:131]
	v_lshl_add_u64 v[66:67], v[66:67], 0, v[132:133]
	v_pk_mul_f32 v[138:139], v[62:63], s[100:101]
	v_pk_mul_f32 v[140:141], v[64:65], s[100:101]
	v_pk_mul_f32 v[142:143], v[54:55], s[100:101]
	v_pk_mul_f32 v[144:145], v[56:57], s[100:101]
	v_exp_f32_e32 v138, v138
	v_exp_f32_e32 v139, v139
	v_exp_f32_e32 v140, v140
	v_exp_f32_e32 v141, v141
	v_exp_f32_e32 v142, v142
	v_exp_f32_e32 v143, v143
	v_exp_f32_e32 v144, v144
	v_exp_f32_e32 v145, v145
	v_pk_add_f32 v[138:139], v[138:139], 1.0 op_sel_hi:[1,0]
	v_pk_add_f32 v[140:141], v[140:141], 1.0 op_sel_hi:[1,0]
	v_pk_add_f32 v[142:143], v[142:143], 1.0 op_sel_hi:[1,0]
	v_pk_add_f32 v[144:145], v[144:145], 1.0 op_sel_hi:[1,0]
	v_rcp_f32_e32 v138, v138
	v_rcp_f32_e32 v139, v139
	v_rcp_f32_e32 v140, v140
	v_rcp_f32_e32 v141, v141
	v_rcp_f32_e32 v142, v142
	v_rcp_f32_e32 v143, v143
	v_rcp_f32_e32 v144, v144
	v_rcp_f32_e32 v145, v145
	v_pk_mul_f32 v[62:63], v[62:63], v[138:139]
	v_pk_mul_f32 v[64:65], v[64:65], v[140:141]
	v_pk_mul_f32 v[54:55], v[54:55], v[142:143]
	v_pk_mul_f32 v[56:57], v[56:57], v[144:145]
	v_pk_mul_f32 v[58:59], v[58:59], v[62:63]
	v_pk_mul_f32 v[60:61], v[60:61], v[64:65]
	v_pk_mul_f32 v[50:51], v[50:51], v[54:55]
	v_pk_mul_f32 v[52:53], v[52:53], v[56:57]
	v_cvt_pk_bf16_f32 v58, v58, v59
	v_cvt_pk_bf16_f32 v59, v60, v61
	v_cvt_pk_bf16_f32 v60, v50, v51
	v_cvt_pk_bf16_f32 v61, v52, v53
	s_nop 1
	v_permlane16_swap_b32_e32 v58, v60
	v_permlane16_swap_b32_e32 v59, v61
	global_store_dwordx4 v[66:67], v[58:61], off
	v_pk_mul_f32 v[138:139], v[46:47], s[100:101]
	v_pk_mul_f32 v[140:141], v[48:49], s[100:101]
	v_pk_mul_f32 v[142:143], v[38:39], s[100:101]
	v_pk_mul_f32 v[144:145], v[40:41], s[100:101]
	v_exp_f32_e32 v138, v138
	v_exp_f32_e32 v139, v139
	v_exp_f32_e32 v140, v140
	v_exp_f32_e32 v141, v141
	v_exp_f32_e32 v142, v142
	v_exp_f32_e32 v143, v143
	v_exp_f32_e32 v144, v144
	v_exp_f32_e32 v145, v145
	v_pk_add_f32 v[138:139], v[138:139], 1.0 op_sel_hi:[1,0]
	v_pk_add_f32 v[140:141], v[140:141], 1.0 op_sel_hi:[1,0]
	v_pk_add_f32 v[142:143], v[142:143], 1.0 op_sel_hi:[1,0]
	v_pk_add_f32 v[144:145], v[144:145], 1.0 op_sel_hi:[1,0]
	v_rcp_f32_e32 v138, v138
	v_rcp_f32_e32 v139, v139
	v_rcp_f32_e32 v140, v140
	v_rcp_f32_e32 v141, v141
	v_rcp_f32_e32 v142, v142
; __device__ __forceinline__ unsigned cvt_pk_bf16(float lo, float hi) { unsigned r; asm volatile("v_cvt_pk_bf16_f32 %0, %1, %2" : "=v"(r) : "v"(lo), "v"(hi)); return r; }
; #define PG8_BAR __builtin_amdgcn_s_barrier()
; #define GAS __attribute__((address_space(1)))
; __device__ __forceinline__ float siluf_(float x) { return x * sigmoidf_(x); }
; template <class Epi, class Sched, bool ALIGN_EPI = false, bool SP2 = false>
; __device__ __forceinline__ void gemm_phase(PG8_LAS unsigned char* lds, const Gemm g, const Sched& S, const Epi& E, const int wave_id) {
;     ...
;         if (!has_next) break;
;         if (!keep_acc) {
; #pragma unroll
;         for (int a = 0; a < 2; ++a)
; #pragma unroll
;             for (int b = 0; b < 2; ++b)
; #pragma unroll
;                 for (int m = 0; m < 4; ++m)
; #pragma unroll
;                     for (int n = 0; n < 2; ++n) acc[a][b][m][n] = (f32x4){0.f, 0.f, 0.f, 0.f};
;         }
;         cur = nxt; cA = nA; cB = nB; ++ui;
;         if constexpr (ALIGN_EPI) { if (wr == 1) PG8_BAR; }
;     __device__ __forceinline__ bool operator()(AccT& acc, const Unit& u, int wr, int wc, int fr, int fq) const {
;     ...
;             for (int mp = 0; mp < 2; ++mp) { bf16* rowp = act + (size_t)(row0 + ai * 128 + mp * 32) * DFF + col0;
; #pragma unroll
;                 for (int bj = 0; bj < 2; ++bj) { unsigned pk[2][2];
; #pragma unroll
;                     for (int k = 0; k < 2; ++k) { const f32x4 g = acc[ai][bj][2 * mp + k][0], up = acc[ai][bj][2 * mp + k][1];
;                         pk[k][0] = pg8::cvt_pk_bf16(siluf_(g[0]) * up[0], siluf_(g[1]) * up[1]); pk[k][1] = pg8::cvt_pk_bf16(siluf_(g[2]) * up[2], siluf_(g[3]) * up[3]); }
;                     const auto sx = __builtin_amdgcn_permlane16_swap(pk[0][0], pk[1][0], false, false), sy = __builtin_amdgcn_permlane16_swap(pk[0][1], pk[1][1], false, false);
;                     *(GAS v4u*)(rowp + bj * 64) = (v4u){sx[0], sy[0], sx[1], sy[1]}; } }
	v_rcp_f32_e32 v143, v143
	v_rcp_f32_e32 v144, v144
	v_rcp_f32_e32 v145, v145
	v_pk_mul_f32 v[46:47], v[46:47], v[138:139]
	v_pk_mul_f32 v[48:49], v[48:49], v[140:141]
	v_pk_mul_f32 v[38:39], v[38:39], v[142:143]
	v_pk_mul_f32 v[40:41], v[40:41], v[144:145]
	v_pk_mul_f32 v[42:43], v[42:43], v[46:47]
	v_pk_mul_f32 v[44:45], v[44:45], v[48:49]
	v_pk_mul_f32 v[34:35], v[34:35], v[38:39]
	v_pk_mul_f32 v[36:37], v[36:37], v[40:41]
	v_cvt_pk_bf16_f32 v42, v42, v43
	v_cvt_pk_bf16_f32 v43, v44, v45
	v_cvt_pk_bf16_f32 v44, v34, v35
	v_cvt_pk_bf16_f32 v45, v36, v37
	s_nop 1
	v_permlane16_swap_b32_e32 v42, v44
	v_permlane16_swap_b32_e32 v43, v45
	global_store_dwordx4 v[66:67], v[42:45], off offset:128
	v_add_u32_e32 v34, 0xa0, v136
	v_mad_i64_i32 v[34:35], s[18:19], v34, s11, v[130:131]
	v_lshl_add_u64 v[34:35], v[34:35], 0, v[132:133]
	s_mov_b64 s[18:19], -1
	v_pk_mul_f32 v[138:139], v[30:31], s[100:101]
	v_pk_mul_f32 v[140:141], v[32:33], s[100:101]
	v_pk_mul_f32 v[142:143], v[22:23], s[100:101]
	v_pk_mul_f32 v[144:145], v[24:25], s[100:101]
	v_exp_f32_e32 v138, v138
	v_exp_f32_e32 v139, v139
	v_exp_f32_e32 v140, v140
	v_exp_f32_e32 v141, v141
	v_exp_f32_e32 v142, v142
	v_exp_f32_e32 v143, v143
	v_exp_f32_e32 v144, v144
	v_exp_f32_e32 v145, v145
	v_pk_add_f32 v[138:139], v[138:139], 1.0 op_sel_hi:[1,0]
	v_pk_add_f32 v[140:141], v[140:141], 1.0 op_sel_hi:[1,0]
	v_pk_add_f32 v[142:143], v[142:143], 1.0 op_sel_hi:[1,0]
	v_pk_add_f32 v[144:145], v[144:145], 1.0 op_sel_hi:[1,0]
	v_rcp_f32_e32 v138, v138
	v_rcp_f32_e32 v139, v139
	v_rcp_f32_e32 v140, v140
	v_rcp_f32_e32 v141, v141
	v_rcp_f32_e32 v142, v142
	v_rcp_f32_e32 v143, v143
	v_rcp_f32_e32 v144, v144
	v_rcp_f32_e32 v145, v145
	v_pk_mul_f32 v[30:31], v[30:31], v[138:139]
	v_pk_mul_f32 v[32:33], v[32:33], v[140:141]
	v_pk_mul_f32 v[22:23], v[22:23], v[142:143]
	v_pk_mul_f32 v[24:25], v[24:25], v[144:145]
	v_pk_mul_f32 v[26:27], v[26:27], v[30:31]
	v_pk_mul_f32 v[28:29], v[28:29], v[32:33]
	v_pk_mul_f32 v[18:19], v[18:19], v[22:23]
	v_pk_mul_f32 v[20:21], v[20:21], v[24:25]
	v_cvt_pk_bf16_f32 v26, v26, v27
	v_cvt_pk_bf16_f32 v27, v28, v29
	v_cvt_pk_bf16_f32 v28, v18, v19
	v_cvt_pk_bf16_f32 v29, v20, v21
	s_nop 1
	v_permlane16_swap_b32_e32 v26, v28
	v_permlane16_swap_b32_e32 v27, v29
	global_store_dwordx4 v[34:35], v[26:29], off
	v_pk_mul_f32 v[138:139], v[14:15], s[100:101]
	v_pk_mul_f32 v[140:141], v[16:17], s[100:101]
	v_pk_mul_f32 v[142:143], v[6:7], s[100:101]
	v_pk_mul_f32 v[144:145], v[8:9], s[100:101]
	v_exp_f32_e32 v138, v138
	v_exp_f32_e32 v139, v139
	v_exp_f32_e32 v140, v140
	v_exp_f32_e32 v141, v141
	v_exp_f32_e32 v142, v142
	v_exp_f32_e32 v143, v143
	v_exp_f32_e32 v144, v144
	v_exp_f32_e32 v145, v145
	v_pk_add_f32 v[138:139], v[138:139], 1.0 op_sel_hi:[1,0]
	v_pk_add_f32 v[140:141], v[140:141], 1.0 op_sel_hi:[1,0]
	v_pk_add_f32 v[142:143], v[142:143], 1.0 op_sel_hi:[1,0]
	v_pk_add_f32 v[144:145], v[144:145], 1.0 op_sel_hi:[1,0]
	v_rcp_f32_e32 v138, v138
	v_rcp_f32_e32 v139, v139
	v_rcp_f32_e32 v140, v140
	v_rcp_f32_e32 v141, v141
	v_rcp_f32_e32 v142, v142
	v_rcp_f32_e32 v143, v143
	v_rcp_f32_e32 v144, v144
	v_rcp_f32_e32 v145, v145
	v_pk_mul_f32 v[14:15], v[14:15], v[138:139]
	v_pk_mul_f32 v[16:17], v[16:17], v[140:141]
	v_pk_mul_f32 v[6:7], v[6:7], v[142:143]
	v_pk_mul_f32 v[8:9], v[8:9], v[144:145]
	v_pk_mul_f32 v[10:11], v[10:11], v[14:15]
	v_pk_mul_f32 v[12:13], v[12:13], v[16:17]
	v_pk_mul_f32 v[2:3], v[2:3], v[6:7]
	v_pk_mul_f32 v[4:5], v[4:5], v[8:9]
	v_cvt_pk_bf16_f32 v10, v10, v11
	v_cvt_pk_bf16_f32 v11, v12, v13
	v_cvt_pk_bf16_f32 v12, v2, v3
	v_cvt_pk_bf16_f32 v13, v4, v5
	s_nop 1
	v_permlane16_swap_b32_e32 v10, v12
	v_permlane16_swap_b32_e32 v11, v13
	global_store_dwordx4 v[34:35], v[10:13], off offset:128
	s_cbranch_vccnz .LBB0_1948
	s_andn2_b64 vcc, exec, s[2:3]
	s_cbranch_vccnz .LBB0_1947
	s_branch .LBB0_1947

; #define PG8_STAGE(bufoff, gbase, voff) do { _Pragma("unroll") for (int _i = 0; _i < 2; ++_i) \
;         __builtin_amdgcn_global_load_lds((const unsigned*)((const char*)(gbase) + (voff)[_i]), (PG8_LAS unsigned*)(lds + (bufoff) + ldsw + _i * 8192), 16, 0, 0); } while (0)
; #define PG8_LDA(dst, b, h) do { _Pragma("unroll") for (int m = 0; m < 4; ++m) _Pragma("unroll") for (int k = 0; k < 2; ++k) dst[m][k] = *(const PG8_LAS bf16x8*)(lds + PG8_SA(b, h) + aoff + m * 2048 + k * 1024); } while (0)
; #define PG8_LDB(dst, b, h) do { _Pragma("unroll") for (int n = 0; n < 2; ++n) _Pragma("unroll") for (int k = 0; k < 2; ++k) dst[n][k] = *(const PG8_LAS bf16x8*)(lds + PG8_SB(b, h) + boff + n * 2048 + k * 1024); } while (0)
; #define PG8_MMA(ai, bj, At, Bt) do { __builtin_amdgcn_s_setprio(1); _Pragma("unroll") for (int m = 0; m < 4; ++m) _Pragma("unroll") for (int n = 0; n < 2; ++n) _Pragma("unroll") for (int k = 0; k < 2; ++k) \
;         acc[ai][bj][m][n] = __builtin_amdgcn_mfma_f32_16x16x32_bf16(Bt[n][k], At[m][k], acc[ai][bj][m][n], 0, 0, 0); __builtin_amdgcn_s_setprio(0); } while (0)
; #define PG8_WAIT_V(n) asm volatile("s_waitcnt vmcnt(" #n ")" ::: "memory")
; #define PG8_WAIT_VN(n) asm volatile("s_waitcnt vmcnt(%0)" :: "n"(n) : "memory")
; #define PG8_WAIT_L(n) asm volatile("s_waitcnt lgkmcnt(" #n ")" ::: "memory")
; #define PG8_BAR __builtin_amdgcn_s_barrier()
; #define PG8_SCHED __builtin_amdgcn_sched_barrier(0)
; template <class Epi, class Sched, bool ALIGN_EPI = false, bool SP2 = false>
; __device__ __forceinline__ void gemm_phase(PG8_LAS unsigned char* lds, const Gemm g, const Sched& S, const Epi& E, const int wave_id) {
;     ...
;             PG8_WAIT_VN(8 + Epi::NS); if (strict) PG8_WAIT_V(8); PG8_WAIT_L(0); PG8_BAR; PG8_MMA(1, 0, At, B0); PG8_MMA(1, 1, At, B1); PG8_BAR; PG8_SCHED;
;             PG8_LDB(B0, 1, 0); PG8_LDB(B1, 1, 1); PG8_SCHED; PG8_LDA(At, 1, 0); PG8_STAGE(PG8_SA(0, 1), a2 + hstep, voffA);
;             PG8_WAIT_V(8); PG8_WAIT_L(0); PG8_BAR; PG8_MMA(0, 0, At, B0); PG8_MMA(0, 1, At, B1); PG8_BAR; PG8_SCHED;
;     ...
;         if constexpr (ALIGN_EPI) { if (wr == 1) PG8_BAR; }
.Lskew_skip_0:
	s_branch .LBB0_2031
.LBB0_2030:
	s_waitcnt lgkmcnt(0)
	s_barrier
	s_setprio 1
	s_waitcnt lgkmcnt(0)
	v_mfma_f32_16x16x32_bf16 v[62:65], v[146:149], v[186:189], v[62:65]
	v_mfma_f32_16x16x32_bf16 v[58:61], v[154:157], v[186:189], v[58:61]
	v_mfma_f32_16x16x32_bf16 v[46:49], v[146:149], v[178:181], v[46:49]
	v_mfma_f32_16x16x32_bf16 v[42:45], v[154:157], v[178:181], v[42:45]
	v_mfma_f32_16x16x32_bf16 v[30:33], v[146:149], v[170:173], v[30:33]
	v_mfma_f32_16x16x32_bf16 v[26:29], v[154:157], v[170:173], v[26:29]
	v_mfma_f32_16x16x32_bf16 v[14:17], v[146:149], v[162:165], v[14:17]
	v_mfma_f32_16x16x32_bf16 v[10:13], v[154:157], v[162:165], v[10:13]
	v_mfma_f32_16x16x32_bf16 v[62:65], v[150:153], v[190:193], v[62:65]
	v_mfma_f32_16x16x32_bf16 v[58:61], v[158:161], v[190:193], v[58:61]
	v_mfma_f32_16x16x32_bf16 v[46:49], v[150:153], v[182:185], v[46:49]
	v_mfma_f32_16x16x32_bf16 v[42:45], v[158:161], v[182:185], v[42:45]
	v_mfma_f32_16x16x32_bf16 v[30:33], v[150:153], v[174:177], v[30:33]
	v_mfma_f32_16x16x32_bf16 v[26:29], v[158:161], v[174:177], v[26:29]
	v_mfma_f32_16x16x32_bf16 v[14:17], v[150:153], v[166:169], v[14:17]
	v_mfma_f32_16x16x32_bf16 v[10:13], v[158:161], v[166:169], v[10:13]
	s_setprio 0
	s_setprio 1
	v_mfma_f32_16x16x32_bf16 v[54:57], v[130:133], v[186:189], v[54:57]
	v_mfma_f32_16x16x32_bf16 v[50:53], v[138:141], v[186:189], v[50:53]
	v_mfma_f32_16x16x32_bf16 v[38:41], v[130:133], v[178:181], v[38:41]
	v_mfma_f32_16x16x32_bf16 v[34:37], v[138:141], v[178:181], v[34:37]
	v_mfma_f32_16x16x32_bf16 v[22:25], v[130:133], v[170:173], v[22:25]
	v_mfma_f32_16x16x32_bf16 v[18:21], v[138:141], v[170:173], v[18:21]
	v_mfma_f32_16x16x32_bf16 v[6:9], v[130:133], v[162:165], v[6:9]
	v_mfma_f32_16x16x32_bf16 v[2:5], v[138:141], v[162:165], v[2:5]
	v_mfma_f32_16x16x32_bf16 v[54:57], v[134:137], v[190:193], v[54:57]
	v_mfma_f32_16x16x32_bf16 v[50:53], v[142:145], v[190:193], v[50:53]
	v_mfma_f32_16x16x32_bf16 v[38:41], v[134:137], v[182:185], v[38:41]
	v_mfma_f32_16x16x32_bf16 v[34:37], v[142:145], v[182:185], v[34:37]
	v_mfma_f32_16x16x32_bf16 v[22:25], v[134:137], v[174:177], v[22:25]
	v_mfma_f32_16x16x32_bf16 v[18:21], v[142:145], v[174:177], v[18:21]
	v_mfma_f32_16x16x32_bf16 v[6:9], v[134:137], v[166:169], v[6:9]
	v_mfma_f32_16x16x32_bf16 v[2:5], v[142:145], v[166:169], v[2:5]
	s_setprio 0
	s_barrier
	s_add_i32 s20, 0, 0x18000
	s_add_i32 s21, 0, 0x1c000
	v_add_u32_e32 v142, s20, v246
	v_add_u32_e32 v158, s21, v246
	ds_read_b128 v[130:133], v142
	ds_read_b128 v[134:137], v142 offset:1024
	ds_read_b128 v[138:141], v142 offset:2048
	ds_read_b128 v[142:145], v142 offset:3072
	ds_read_b128 v[146:149], v158
	ds_read_b128 v[150:153], v158 offset:1024
	ds_read_b128 v[154:157], v158 offset:2048
	ds_read_b128 v[158:161], v158 offset:3072
	s_add_u32 s18, s18, 0xb0000
	s_addc_u32 s19, s19, 0
	s_mov_b32 m0, s39
	v_lshl_add_u64 v[194:195], s[18:19], 0, v[210:211]
	ds_read_b128 v[162:165], v247 offset:32768
	ds_read_b128 v[166:169], v247 offset:33792
	ds_read_b128 v[170:173], v247 offset:34816
	ds_read_b128 v[174:177], v247 offset:35840
	ds_read_b128 v[178:181], v247 offset:36864
	ds_read_b128 v[182:185], v247 offset:37888
	ds_read_b128 v[186:189], v247 offset:38912
	ds_read_b128 v[190:193], v247 offset:39936
	global_load_lds_dwordx4 v[194:195], off
	v_lshl_add_u64 v[194:195], s[18:19], 0, v[214:215]
	s_mov_b32 m0, s40
	s_nop 0
	global_load_lds_dwordx4 v[194:195], off
	s_waitcnt vmcnt(26)
	s_cmp_eq_u32 s100, 0
	s_cbranch_scc1 .Lthird_wait_relaxed_1
	s_waitcnt vmcnt(8)

; #define GAS __attribute__((address_space(1)))
; __device__ __forceinline__ v4u tr4(int a, v4u x) { return (v4u){bperm(a, x.x), bperm(a, x.y), bperm(a, x.z), bperm(a, x.w)}; }
; __device__ __forceinline__ v4u pack8(const f32x4& a, const f32x4& b) { return (v4u){pg8::cvt_pk_bf16(a[0], a[1]), pg8::cvt_pk_bf16(a[2], a[3]), pg8::cvt_pk_bf16(b[0], b[1]), pg8::cvt_pk_bf16(b[2], b[3])}; }
;     __device__ __forceinline__ bool operator()(AccT& acc, const Unit& u, int wr, int wc, int fr, int fq) const {
;         asm volatile("" : "+s"(wr), "+s"(wc), "+v"(fr), "+v"(fq));
;         const LaneT t = lane_t(fr, fq);
;         const bf16* src = (const bf16*)(ws + WS_HB); bf16* dst = (bf16*)(ws + WS_YB);
;         const int row0 = u.pm * 256 + wr * 64 + t.tfr, col0 = u.pn * 256 + wc * 32 + 8 * t.tfq;
; #pragma unroll
;         for (int ai = 0; ai < 2; ++ai)
; #pragma unroll
;             for (int m = 0; m < 4; ++m) { const size_t off = (size_t)(row0 + ai * 128 + m * 16) * D + col0;
; #pragma unroll
;                 for (int bj = 0; bj < 2; ++bj) { const v4u r = tr4(t.push, *(const GAS v4u*)(src + off + bj * 128));
;                     const f32x4 y0 = (f32x4){bflo(r.x), bfhi(r.x), bflo(r.y), bfhi(r.y)} * ca + acc[ai][bj][m][0] * cb, y1 = (f32x4){bflo(r.z), bfhi(r.z), bflo(r.w), bfhi(r.w)} * ca + acc[ai][bj][m][1] * cb;
;                     *(GAS v4u*)(dst + off + bj * 128) = tr4(t.pull, pack8(y0, y1)); } }
.LBB0_2037:
	s_add_u32 s100, s8, 0xb0080
	s_addc_u32 s101, s9, 0
	v_lshl_add_u64 v[194:195], s[100:101], 0, v[220:221]
	s_add_i32 m0, s31, 0xc000
	s_nop 0
	global_load_lds_dwordx4 v[194:195], off
	v_lshl_add_u64 v[194:195], s[100:101], 0, v[218:219]
	s_add_i32 m0, s31, 0xe000
	s_nop 0
	global_load_lds_dwordx4 v[194:195], off
	s_mov_b32 s12, s41
	v_mov_b32_e32 v130, v1
	s_mov_b32 s13, s29
	v_mov_b32_e32 v131, v245
	s_lshl_b32 s14, s54, 8
	v_lshl_add_u32 v132, v130, 4, v131
	s_lshl_b32 s13, s13, 6
	v_ashrrev_i32_e32 v134, 2, v132
	v_and_b32_e32 v135, 3, v131
	v_lshlrev_b32_e32 v131, 4, v131
	s_add_i32 s13, s13, s14
	v_lshl_add_u32 v133, v130, 2, v131
	v_add_u32_e32 v130, s13, v134
	s_lshl_b32 s13, s56, 8
	s_lshl_b32 s12, s12, 5
	s_add_i32 s12, s12, s13
	v_and_b32_e32 v132, -4, v132
	v_lshl_or_b32 v134, v135, 3, s12
	v_ashrrev_i32_e32 v131, 31, v130
	v_lshl_add_u32 v132, v135, 6, v132
	v_ashrrev_i32_e32 v135, 31, v134
	v_lshlrev_b64 v[130:131], 10, v[130:131]
	v_lshl_add_u64 v[130:131], v[130:131], 0, v[134:135]
	v_readlane_b32 s14, v253, 11
	v_lshlrev_b64 v[130:131], 1, v[130:131]
	v_readlane_b32 s15, v253, 12
	v_lshl_add_u64 v[140:141], s[60:61], 0, v[130:131]
	s_mov_b64 s[12:13], 0x8000
	v_lshl_add_u64 v[138:139], s[14:15], 0, v[130:131]
	v_mov_b64_e32 v[130:131], v[138:139]
	global_load_dwordx4 v[146:149], v[130:131], off
	s_and_b64 vcc, exec, s[6:7]
	global_load_dwordx4 v[150:153], v[130:131], off offset:256
	s_mov_b64 s[12:13], 0x8000
	v_lshl_add_u64 v[130:131], v[138:139], 0, s[12:13]
	global_load_dwordx4 v[154:157], v[130:131], off
	global_load_dwordx4 v[158:161], v[130:131], off offset:256
	s_mov_b64 s[12:13], 0x10000
	v_lshl_add_u64 v[130:131], v[138:139], 0, s[12:13]
	global_load_dwordx4 v[162:165], v[130:131], off
	global_load_dwordx4 v[166:169], v[130:131], off offset:256
	s_mov_b64 s[12:13], 0x18000
	v_lshl_add_u64 v[130:131], v[138:139], 0, s[12:13]
	global_load_dwordx4 v[170:173], v[130:131], off
	global_load_dwordx4 v[174:177], v[130:131], off offset:256
	s_mov_b64 s[12:13], 0x40000
	v_lshl_add_u64 v[130:131], v[138:139], 0, s[12:13]
	global_load_dwordx4 v[178:181], v[130:131], off
	global_load_dwordx4 v[182:185], v[130:131], off offset:256
	s_mov_b64 s[12:13], 0x48000
	v_lshl_add_u64 v[130:131], v[138:139], 0, s[12:13]
	global_load_dwordx4 v[186:189], v[130:131], off
	global_load_dwordx4 v[190:193], v[130:131], off offset:256
	s_waitcnt vmcnt(11)
	ds_bpermute_b32 v143, v133, v147
	ds_bpermute_b32 v142, v133, v146
	ds_bpermute_b32 v145, v133, v149
	ds_bpermute_b32 v144, v133, v148
	v_mov_b64_e32 v[134:135], v[140:141]
	s_waitcnt lgkmcnt(3)
	v_lshlrev_b32_e32 v136, 16, v143
	v_and_b32_e32 v137, 0xffff0000, v143
	s_waitcnt lgkmcnt(2)
	v_and_b32_e32 v143, 0xffff0000, v142
	v_lshlrev_b32_e32 v142, 16, v142
	v_pk_mul_f32 v[136:137], v[136:137], s[96:97] op_sel_hi:[1,0]
	v_pk_fma_f32 v[128:129], v[128:129], 0.5, v[136:137] op_sel_hi:[1,0,1]
	v_pk_mul_f32 v[142:143], v[142:143], s[96:97] op_sel_hi:[1,0]
	v_pk_fma_f32 v[126:127], v[126:127], 0.5, v[142:143] op_sel_hi:[1,0,1]
	s_waitcnt lgkmcnt(1)
	v_lshlrev_b32_e32 v136, 16, v145
	v_and_b32_e32 v137, 0xffff0000, v145
	s_waitcnt lgkmcnt(0)
	v_and_b32_e32 v145, 0xffff0000, v144
	v_lshlrev_b32_e32 v144, 16, v144
	v_pk_mul_f32 v[136:137], v[136:137], s[96:97] op_sel_hi:[1,0]
	v_pk_fma_f32 v[124:125], v[124:125], 0.5, v[136:137] op_sel_hi:[1,0,1]
	v_pk_mul_f32 v[144:145], v[144:145], s[96:97] op_sel_hi:[1,0]
	v_pk_fma_f32 v[122:123], v[122:123], 0.5, v[144:145] op_sel_hi:[1,0,1]
	v_cvt_pk_bf16_f32 v126, v126, v127
	v_cvt_pk_bf16_f32 v127, v128, v129
	v_cvt_pk_bf16_f32 v128, v122, v123
	v_cvt_pk_bf16_f32 v125, v124, v125
	s_nop 1
	ds_bpermute_b32 v122, v132, v126
	ds_bpermute_b32 v123, v132, v127
	ds_bpermute_b32 v124, v132, v128
	ds_bpermute_b32 v125, v132, v125
	s_waitcnt lgkmcnt(0)
	global_store_dwordx4 v[134:135], v[122:125], off
	s_mov_b64 s[12:13], 0x50000
	v_lshl_add_u64 v[130:131], v[138:139], 0, s[12:13]
	global_load_dwordx4 v[126:129], v[130:131], off
	s_waitcnt vmcnt(12)
	ds_bpermute_b32 v143, v133, v151
	ds_bpermute_b32 v142, v133, v150
	ds_bpermute_b32 v145, v133, v153
	ds_bpermute_b32 v144, v133, v152
	s_waitcnt lgkmcnt(3)
	v_lshlrev_b32_e32 v136, 16, v143
	v_and_b32_e32 v137, 0xffff0000, v143
	s_waitcnt lgkmcnt(2)
	v_and_b32_e32 v143, 0xffff0000, v142
	v_lshlrev_b32_e32 v142, 16, v142
	v_pk_mul_f32 v[136:137], v[136:137], s[96:97] op_sel_hi:[1,0]
	v_pk_fma_f32 v[120:121], v[120:121], 0.5, v[136:137] op_sel_hi:[1,0,1]
	v_pk_mul_f32 v[142:143], v[142:143], s[96:97] op_sel_hi:[1,0]
	v_pk_fma_f32 v[118:119], v[118:119], 0.5, v[142:143] op_sel_hi:[1,0,1]
	s_waitcnt lgkmcnt(1)
	v_lshlrev_b32_e32 v136, 16, v145
	v_and_b32_e32 v137, 0xffff0000, v145
	s_waitcnt lgkmcnt(0)
	v_and_b32_e32 v145, 0xffff0000, v144
	v_lshlrev_b32_e32 v144, 16, v144
	v_pk_mul_f32 v[136:137], v[136:137], s[96:97] op_sel_hi:[1,0]
	v_pk_fma_f32 v[116:117], v[116:117], 0.5, v[136:137] op_sel_hi:[1,0,1]
	v_pk_mul_f32 v[144:145], v[144:145], s[96:97] op_sel_hi:[1,0]
	v_pk_fma_f32 v[114:115], v[114:115], 0.5, v[144:145] op_sel_hi:[1,0,1]
	v_cvt_pk_bf16_f32 v118, v118, v119
	v_cvt_pk_bf16_f32 v119, v120, v121
	v_cvt_pk_bf16_f32 v120, v114, v115
	v_cvt_pk_bf16_f32 v117, v116, v117
	s_nop 1
	ds_bpermute_b32 v114, v132, v118
	ds_bpermute_b32 v115, v132, v119
	ds_bpermute_b32 v116, v132, v120
	ds_bpermute_b32 v117, v132, v117
	s_waitcnt lgkmcnt(0)
	global_store_dwordx4 v[134:135], v[114:117], off offset:256
	global_load_dwordx4 v[118:121], v[130:131], off offset:256
	s_waitcnt vmcnt(13)
	ds_bpermute_b32 v143, v133, v155
	ds_bpermute_b32 v142, v133, v154
	ds_bpermute_b32 v145, v133, v157
	ds_bpermute_b32 v144, v133, v156
	s_mov_b64 s[12:13], 0x8000
	v_lshl_add_u64 v[134:135], v[140:141], 0, s[12:13]
	s_waitcnt lgkmcnt(3)
; #define GAS __attribute__((address_space(1)))
; __device__ __forceinline__ v4u tr4(int a, v4u x) { return (v4u){bperm(a, x.x), bperm(a, x.y), bperm(a, x.z), bperm(a, x.w)}; }
; __device__ __forceinline__ v4u pack8(const f32x4& a, const f32x4& b) { return (v4u){pg8::cvt_pk_bf16(a[0], a[1]), pg8::cvt_pk_bf16(a[2], a[3]), pg8::cvt_pk_bf16(b[0], b[1]), pg8::cvt_pk_bf16(b[2], b[3])}; }
;     __device__ __forceinline__ bool operator()(AccT& acc, const Unit& u, int wr, int wc, int fr, int fq) const {
;     ...
;             for (int m = 0; m < 4; ++m) { const size_t off = (size_t)(row0 + ai * 128 + m * 16) * D + col0;
; #pragma unroll
;                 for (int bj = 0; bj < 2; ++bj) { const v4u r = tr4(t.push, *(const GAS v4u*)(src + off + bj * 128));
;                     const f32x4 y0 = (f32x4){bflo(r.x), bfhi(r.x), bflo(r.y), bfhi(r.y)} * ca + acc[ai][bj][m][0] * cb, y1 = (f32x4){bflo(r.z), bfhi(r.z), bflo(r.w), bfhi(r.w)} * ca + acc[ai][bj][m][1] * cb;
;                     *(GAS v4u*)(dst + off + bj * 128) = tr4(t.pull, pack8(y0, y1)); } }
	v_lshlrev_b32_e32 v136, 16, v143
	v_and_b32_e32 v137, 0xffff0000, v143
	s_waitcnt lgkmcnt(2)
	v_and_b32_e32 v143, 0xffff0000, v142
	v_lshlrev_b32_e32 v142, 16, v142
	v_pk_mul_f32 v[136:137], v[136:137], s[96:97] op_sel_hi:[1,0]
	v_pk_fma_f32 v[112:113], v[112:113], 0.5, v[136:137] op_sel_hi:[1,0,1]
	v_pk_mul_f32 v[142:143], v[142:143], s[96:97] op_sel_hi:[1,0]
	v_pk_fma_f32 v[110:111], v[110:111], 0.5, v[142:143] op_sel_hi:[1,0,1]
	s_waitcnt lgkmcnt(1)
	v_lshlrev_b32_e32 v136, 16, v145
	v_and_b32_e32 v137, 0xffff0000, v145
	s_waitcnt lgkmcnt(0)
	v_and_b32_e32 v145, 0xffff0000, v144
	v_lshlrev_b32_e32 v144, 16, v144
	v_pk_mul_f32 v[136:137], v[136:137], s[96:97] op_sel_hi:[1,0]
	v_pk_fma_f32 v[108:109], v[108:109], 0.5, v[136:137] op_sel_hi:[1,0,1]
	v_pk_mul_f32 v[144:145], v[144:145], s[96:97] op_sel_hi:[1,0]
	v_pk_fma_f32 v[106:107], v[106:107], 0.5, v[144:145] op_sel_hi:[1,0,1]
	v_cvt_pk_bf16_f32 v110, v110, v111
	v_cvt_pk_bf16_f32 v111, v112, v113
	v_cvt_pk_bf16_f32 v112, v106, v107
	v_cvt_pk_bf16_f32 v109, v108, v109
	s_nop 1
	ds_bpermute_b32 v106, v132, v110
	ds_bpermute_b32 v107, v132, v111
	ds_bpermute_b32 v108, v132, v112
	ds_bpermute_b32 v109, v132, v109
	s_waitcnt lgkmcnt(0)
	global_store_dwordx4 v[134:135], v[106:109], off
	s_mov_b64 s[12:13], 0x58000
	v_lshl_add_u64 v[130:131], v[138:139], 0, s[12:13]
	global_load_dwordx4 v[110:113], v[130:131], off
	s_waitcnt vmcnt(14)
	ds_bpermute_b32 v143, v133, v159
	ds_bpermute_b32 v142, v133, v158
	ds_bpermute_b32 v145, v133, v161
	ds_bpermute_b32 v144, v133, v160
	s_waitcnt lgkmcnt(3)
	v_lshlrev_b32_e32 v136, 16, v143
	v_and_b32_e32 v137, 0xffff0000, v143
	s_waitcnt lgkmcnt(2)
	v_and_b32_e32 v143, 0xffff0000, v142
	v_lshlrev_b32_e32 v142, 16, v142
	v_pk_mul_f32 v[136:137], v[136:137], s[96:97] op_sel_hi:[1,0]
	v_pk_fma_f32 v[104:105], v[104:105], 0.5, v[136:137] op_sel_hi:[1,0,1]
	v_pk_mul_f32 v[142:143], v[142:143], s[96:97] op_sel_hi:[1,0]
	v_pk_fma_f32 v[102:103], v[102:103], 0.5, v[142:143] op_sel_hi:[1,0,1]
	s_waitcnt lgkmcnt(1)
	v_lshlrev_b32_e32 v136, 16, v145
	v_and_b32_e32 v137, 0xffff0000, v145
	s_waitcnt lgkmcnt(0)
	v_and_b32_e32 v145, 0xffff0000, v144
	v_lshlrev_b32_e32 v144, 16, v144
	v_pk_mul_f32 v[136:137], v[136:137], s[96:97] op_sel_hi:[1,0]
	v_pk_fma_f32 v[100:101], v[100:101], 0.5, v[136:137] op_sel_hi:[1,0,1]
	v_pk_mul_f32 v[144:145], v[144:145], s[96:97] op_sel_hi:[1,0]
	v_pk_fma_f32 v[98:99], v[98:99], 0.5, v[144:145] op_sel_hi:[1,0,1]
	v_cvt_pk_bf16_f32 v102, v102, v103
	v_cvt_pk_bf16_f32 v103, v104, v105
	v_cvt_pk_bf16_f32 v104, v98, v99
	v_cvt_pk_bf16_f32 v101, v100, v101
	s_nop 1
	ds_bpermute_b32 v98, v132, v102
	ds_bpermute_b32 v99, v132, v103
	ds_bpermute_b32 v100, v132, v104
	ds_bpermute_b32 v101, v132, v101
	s_waitcnt lgkmcnt(0)
	global_store_dwordx4 v[134:135], v[98:101], off offset:256
	global_load_dwordx4 v[102:105], v[130:131], off offset:256
	s_waitcnt vmcnt(15)
	ds_bpermute_b32 v143, v133, v163
	ds_bpermute_b32 v142, v133, v162
	ds_bpermute_b32 v145, v133, v165
	ds_bpermute_b32 v144, v133, v164
	s_mov_b64 s[12:13], 0x10000
	v_lshl_add_u64 v[134:135], v[140:141], 0, s[12:13]
	s_waitcnt lgkmcnt(3)
	v_lshlrev_b32_e32 v136, 16, v143
	v_and_b32_e32 v137, 0xffff0000, v143
	s_waitcnt lgkmcnt(2)
	v_and_b32_e32 v143, 0xffff0000, v142
	v_lshlrev_b32_e32 v142, 16, v142
	v_pk_mul_f32 v[136:137], v[136:137], s[96:97] op_sel_hi:[1,0]
	v_pk_fma_f32 v[96:97], v[96:97], 0.5, v[136:137] op_sel_hi:[1,0,1]
	v_pk_mul_f32 v[142:143], v[142:143], s[96:97] op_sel_hi:[1,0]
	v_pk_fma_f32 v[94:95], v[94:95], 0.5, v[142:143] op_sel_hi:[1,0,1]
	s_waitcnt lgkmcnt(1)
	v_lshlrev_b32_e32 v136, 16, v145
	v_and_b32_e32 v137, 0xffff0000, v145
	s_waitcnt lgkmcnt(0)
	v_and_b32_e32 v145, 0xffff0000, v144
	v_lshlrev_b32_e32 v144, 16, v144
	v_pk_mul_f32 v[136:137], v[136:137], s[96:97] op_sel_hi:[1,0]
	v_pk_fma_f32 v[92:93], v[92:93], 0.5, v[136:137] op_sel_hi:[1,0,1]
	v_pk_mul_f32 v[144:145], v[144:145], s[96:97] op_sel_hi:[1,0]
	v_pk_fma_f32 v[90:91], v[90:91], 0.5, v[144:145] op_sel_hi:[1,0,1]
	v_cvt_pk_bf16_f32 v94, v94, v95
	v_cvt_pk_bf16_f32 v95, v96, v97
	v_cvt_pk_bf16_f32 v96, v90, v91
	v_cvt_pk_bf16_f32 v93, v92, v93
	s_nop 1
	ds_bpermute_b32 v90, v132, v94
	ds_bpermute_b32 v91, v132, v95
	ds_bpermute_b32 v92, v132, v96
	ds_bpermute_b32 v93, v132, v93
	s_waitcnt lgkmcnt(0)
	global_store_dwordx4 v[134:135], v[90:93], off
	s_waitcnt vmcnt(15)
	ds_bpermute_b32 v143, v133, v167
	ds_bpermute_b32 v142, v133, v166
	ds_bpermute_b32 v145, v133, v169
	ds_bpermute_b32 v144, v133, v168
	s_waitcnt lgkmcnt(3)
	v_lshlrev_b32_e32 v136, 16, v143
	v_and_b32_e32 v137, 0xffff0000, v143
	s_waitcnt lgkmcnt(2)
	v_and_b32_e32 v143, 0xffff0000, v142
	v_lshlrev_b32_e32 v142, 16, v142
	v_pk_mul_f32 v[136:137], v[136:137], s[96:97] op_sel_hi:[1,0]
	v_pk_fma_f32 v[88:89], v[88:89], 0.5, v[136:137] op_sel_hi:[1,0,1]
	v_pk_mul_f32 v[142:143], v[142:143], s[96:97] op_sel_hi:[1,0]
	v_pk_fma_f32 v[86:87], v[86:87], 0.5, v[142:143] op_sel_hi:[1,0,1]
	s_waitcnt lgkmcnt(1)
	v_lshlrev_b32_e32 v136, 16, v145
	v_and_b32_e32 v137, 0xffff0000, v145
	s_waitcnt lgkmcnt(0)
	v_and_b32_e32 v145, 0xffff0000, v144
	v_lshlrev_b32_e32 v144, 16, v144
	v_pk_mul_f32 v[136:137], v[136:137], s[96:97] op_sel_hi:[1,0]
	v_pk_fma_f32 v[84:85], v[84:85], 0.5, v[136:137] op_sel_hi:[1,0,1]
	v_pk_mul_f32 v[144:145], v[144:145], s[96:97] op_sel_hi:[1,0]
	v_pk_fma_f32 v[82:83], v[82:83], 0.5, v[144:145] op_sel_hi:[1,0,1]
	v_cvt_pk_bf16_f32 v86, v86, v87
	v_cvt_pk_bf16_f32 v87, v88, v89
	v_cvt_pk_bf16_f32 v88, v82, v83
	v_cvt_pk_bf16_f32 v85, v84, v85
	s_nop 1
	ds_bpermute_b32 v82, v132, v86
	ds_bpermute_b32 v83, v132, v87
	ds_bpermute_b32 v84, v132, v88
	ds_bpermute_b32 v85, v132, v85
	s_waitcnt lgkmcnt(0)
; #define GAS __attribute__((address_space(1)))
; __device__ __forceinline__ v4u tr4(int a, v4u x) { return (v4u){bperm(a, x.x), bperm(a, x.y), bperm(a, x.z), bperm(a, x.w)}; }
; __device__ __forceinline__ v4u pack8(const f32x4& a, const f32x4& b) { return (v4u){pg8::cvt_pk_bf16(a[0], a[1]), pg8::cvt_pk_bf16(a[2], a[3]), pg8::cvt_pk_bf16(b[0], b[1]), pg8::cvt_pk_bf16(b[2], b[3])}; }
;     __device__ __forceinline__ bool operator()(AccT& acc, const Unit& u, int wr, int wc, int fr, int fq) const {
;     ...
;             for (int m = 0; m < 4; ++m) { const size_t off = (size_t)(row0 + ai * 128 + m * 16) * D + col0;
; #pragma unroll
;                 for (int bj = 0; bj < 2; ++bj) { const v4u r = tr4(t.push, *(const GAS v4u*)(src + off + bj * 128));
;                     const f32x4 y0 = (f32x4){bflo(r.x), bfhi(r.x), bflo(r.y), bfhi(r.y)} * ca + acc[ai][bj][m][0] * cb, y1 = (f32x4){bflo(r.z), bfhi(r.z), bflo(r.w), bfhi(r.w)} * ca + acc[ai][bj][m][1] * cb;
;                     *(GAS v4u*)(dst + off + bj * 128) = tr4(t.pull, pack8(y0, y1)); } }
	global_store_dwordx4 v[134:135], v[82:85], off offset:256
	s_waitcnt vmcnt(15)
	ds_bpermute_b32 v143, v133, v171
	ds_bpermute_b32 v142, v133, v170
	ds_bpermute_b32 v145, v133, v173
	ds_bpermute_b32 v144, v133, v172
	s_mov_b64 s[12:13], 0x18000
	v_lshl_add_u64 v[134:135], v[140:141], 0, s[12:13]
	s_waitcnt lgkmcnt(3)
	v_lshlrev_b32_e32 v136, 16, v143
	v_and_b32_e32 v137, 0xffff0000, v143
	s_waitcnt lgkmcnt(2)
	v_and_b32_e32 v143, 0xffff0000, v142
	v_lshlrev_b32_e32 v142, 16, v142
	v_pk_mul_f32 v[136:137], v[136:137], s[96:97] op_sel_hi:[1,0]
	v_pk_fma_f32 v[80:81], v[80:81], 0.5, v[136:137] op_sel_hi:[1,0,1]
	v_pk_mul_f32 v[142:143], v[142:143], s[96:97] op_sel_hi:[1,0]
	v_pk_fma_f32 v[78:79], v[78:79], 0.5, v[142:143] op_sel_hi:[1,0,1]
	s_waitcnt lgkmcnt(1)
	v_lshlrev_b32_e32 v136, 16, v145
	v_and_b32_e32 v137, 0xffff0000, v145
	s_waitcnt lgkmcnt(0)
	v_and_b32_e32 v145, 0xffff0000, v144
	v_lshlrev_b32_e32 v144, 16, v144
	v_pk_mul_f32 v[136:137], v[136:137], s[96:97] op_sel_hi:[1,0]
	v_pk_fma_f32 v[76:77], v[76:77], 0.5, v[136:137] op_sel_hi:[1,0,1]
	v_pk_mul_f32 v[144:145], v[144:145], s[96:97] op_sel_hi:[1,0]
	v_pk_fma_f32 v[74:75], v[74:75], 0.5, v[144:145] op_sel_hi:[1,0,1]
	v_cvt_pk_bf16_f32 v78, v78, v79
	v_cvt_pk_bf16_f32 v79, v80, v81
	v_cvt_pk_bf16_f32 v80, v74, v75
	v_cvt_pk_bf16_f32 v77, v76, v77
	s_nop 1
	ds_bpermute_b32 v74, v132, v78
	ds_bpermute_b32 v75, v132, v79
	ds_bpermute_b32 v76, v132, v80
	ds_bpermute_b32 v77, v132, v77
	s_waitcnt lgkmcnt(0)
	global_store_dwordx4 v[134:135], v[74:77], off
	s_waitcnt vmcnt(15)
	ds_bpermute_b32 v143, v133, v175
	ds_bpermute_b32 v142, v133, v174
	ds_bpermute_b32 v145, v133, v177
	ds_bpermute_b32 v144, v133, v176
	s_waitcnt lgkmcnt(3)
	v_lshlrev_b32_e32 v136, 16, v143
	v_and_b32_e32 v137, 0xffff0000, v143
	s_waitcnt lgkmcnt(2)
	v_and_b32_e32 v143, 0xffff0000, v142
	v_lshlrev_b32_e32 v142, 16, v142
	v_pk_mul_f32 v[136:137], v[136:137], s[96:97] op_sel_hi:[1,0]
	v_pk_fma_f32 v[72:73], v[72:73], 0.5, v[136:137] op_sel_hi:[1,0,1]
	v_pk_mul_f32 v[142:143], v[142:143], s[96:97] op_sel_hi:[1,0]
	v_pk_fma_f32 v[70:71], v[70:71], 0.5, v[142:143] op_sel_hi:[1,0,1]
	s_waitcnt lgkmcnt(1)
	v_lshlrev_b32_e32 v136, 16, v145
	v_and_b32_e32 v137, 0xffff0000, v145
	s_waitcnt lgkmcnt(0)
	v_and_b32_e32 v145, 0xffff0000, v144
	v_lshlrev_b32_e32 v144, 16, v144
	v_pk_mul_f32 v[136:137], v[136:137], s[96:97] op_sel_hi:[1,0]
	v_pk_fma_f32 v[68:69], v[68:69], 0.5, v[136:137] op_sel_hi:[1,0,1]
	v_pk_mul_f32 v[144:145], v[144:145], s[96:97] op_sel_hi:[1,0]
	v_pk_fma_f32 v[66:67], v[66:67], 0.5, v[144:145] op_sel_hi:[1,0,1]
	v_cvt_pk_bf16_f32 v70, v70, v71
	v_cvt_pk_bf16_f32 v71, v72, v73
	v_cvt_pk_bf16_f32 v72, v66, v67
	v_cvt_pk_bf16_f32 v69, v68, v69
	s_nop 1
	ds_bpermute_b32 v66, v132, v70
	ds_bpermute_b32 v67, v132, v71
	ds_bpermute_b32 v68, v132, v72
	ds_bpermute_b32 v69, v132, v69
	s_waitcnt lgkmcnt(0)
	global_store_dwordx4 v[134:135], v[66:69], off offset:256
	s_waitcnt vmcnt(15)
	ds_bpermute_b32 v143, v133, v179
	ds_bpermute_b32 v142, v133, v178
	ds_bpermute_b32 v145, v133, v181
	ds_bpermute_b32 v144, v133, v180
	s_mov_b64 s[12:13], 0x40000
	v_lshl_add_u64 v[134:135], v[140:141], 0, s[12:13]
	s_waitcnt lgkmcnt(3)
	v_lshlrev_b32_e32 v136, 16, v143
	v_and_b32_e32 v137, 0xffff0000, v143
	s_waitcnt lgkmcnt(2)
	v_and_b32_e32 v143, 0xffff0000, v142
	v_lshlrev_b32_e32 v142, 16, v142
	v_pk_mul_f32 v[136:137], v[136:137], s[96:97] op_sel_hi:[1,0]
	v_pk_fma_f32 v[64:65], v[64:65], 0.5, v[136:137] op_sel_hi:[1,0,1]
	v_pk_mul_f32 v[142:143], v[142:143], s[96:97] op_sel_hi:[1,0]
	v_pk_fma_f32 v[62:63], v[62:63], 0.5, v[142:143] op_sel_hi:[1,0,1]
	s_waitcnt lgkmcnt(1)
	v_lshlrev_b32_e32 v136, 16, v145
	v_and_b32_e32 v137, 0xffff0000, v145
	s_waitcnt lgkmcnt(0)
	v_and_b32_e32 v145, 0xffff0000, v144
	v_lshlrev_b32_e32 v144, 16, v144
	v_pk_mul_f32 v[136:137], v[136:137], s[96:97] op_sel_hi:[1,0]
	v_pk_fma_f32 v[60:61], v[60:61], 0.5, v[136:137] op_sel_hi:[1,0,1]
	v_pk_mul_f32 v[144:145], v[144:145], s[96:97] op_sel_hi:[1,0]
	v_pk_fma_f32 v[58:59], v[58:59], 0.5, v[144:145] op_sel_hi:[1,0,1]
	v_cvt_pk_bf16_f32 v62, v62, v63
	v_cvt_pk_bf16_f32 v63, v64, v65
	v_cvt_pk_bf16_f32 v64, v58, v59
	v_cvt_pk_bf16_f32 v61, v60, v61
	s_nop 1
	ds_bpermute_b32 v58, v132, v62
	ds_bpermute_b32 v59, v132, v63
	ds_bpermute_b32 v60, v132, v64
	ds_bpermute_b32 v61, v132, v61
	s_waitcnt lgkmcnt(0)
	global_store_dwordx4 v[134:135], v[58:61], off
	s_waitcnt vmcnt(15)
	ds_bpermute_b32 v143, v133, v183
	ds_bpermute_b32 v142, v133, v182
	ds_bpermute_b32 v145, v133, v185
	ds_bpermute_b32 v144, v133, v184
	s_waitcnt lgkmcnt(3)
	v_lshlrev_b32_e32 v136, 16, v143
	v_and_b32_e32 v137, 0xffff0000, v143
	s_waitcnt lgkmcnt(2)
	v_and_b32_e32 v143, 0xffff0000, v142
	v_lshlrev_b32_e32 v142, 16, v142
	v_pk_mul_f32 v[136:137], v[136:137], s[96:97] op_sel_hi:[1,0]
	v_pk_fma_f32 v[56:57], v[56:57], 0.5, v[136:137] op_sel_hi:[1,0,1]
	v_pk_mul_f32 v[142:143], v[142:143], s[96:97] op_sel_hi:[1,0]
	v_pk_fma_f32 v[54:55], v[54:55], 0.5, v[142:143] op_sel_hi:[1,0,1]
	s_waitcnt lgkmcnt(1)
	v_lshlrev_b32_e32 v136, 16, v145
	v_and_b32_e32 v137, 0xffff0000, v145
	s_waitcnt lgkmcnt(0)
	v_and_b32_e32 v145, 0xffff0000, v144
	v_lshlrev_b32_e32 v144, 16, v144
	v_pk_mul_f32 v[136:137], v[136:137], s[96:97] op_sel_hi:[1,0]
	v_pk_fma_f32 v[52:53], v[52:53], 0.5, v[136:137] op_sel_hi:[1,0,1]
	v_pk_mul_f32 v[144:145], v[144:145], s[96:97] op_sel_hi:[1,0]
	v_pk_fma_f32 v[50:51], v[50:51], 0.5, v[144:145] op_sel_hi:[1,0,1]
	v_cvt_pk_bf16_f32 v54, v54, v55
	v_cvt_pk_bf16_f32 v55, v56, v57
	v_cvt_pk_bf16_f32 v56, v50, v51
	v_cvt_pk_bf16_f32 v53, v52, v53
	s_nop 1
	ds_bpermute_b32 v50, v132, v54
	ds_bpermute_b32 v51, v132, v55
	ds_bpermute_b32 v52, v132, v56
	ds_bpermute_b32 v53, v132, v53
	s_waitcnt lgkmcnt(0)
; #define GAS __attribute__((address_space(1)))
; __device__ __forceinline__ v4u tr4(int a, v4u x) { return (v4u){bperm(a, x.x), bperm(a, x.y), bperm(a, x.z), bperm(a, x.w)}; }
; __device__ __forceinline__ v4u pack8(const f32x4& a, const f32x4& b) { return (v4u){pg8::cvt_pk_bf16(a[0], a[1]), pg8::cvt_pk_bf16(a[2], a[3]), pg8::cvt_pk_bf16(b[0], b[1]), pg8::cvt_pk_bf16(b[2], b[3])}; }
;     __device__ __forceinline__ bool operator()(AccT& acc, const Unit& u, int wr, int wc, int fr, int fq) const {
;     ...
;             for (int m = 0; m < 4; ++m) { const size_t off = (size_t)(row0 + ai * 128 + m * 16) * D + col0;
; #pragma unroll
;                 for (int bj = 0; bj < 2; ++bj) { const v4u r = tr4(t.push, *(const GAS v4u*)(src + off + bj * 128));
;                     const f32x4 y0 = (f32x4){bflo(r.x), bfhi(r.x), bflo(r.y), bfhi(r.y)} * ca + acc[ai][bj][m][0] * cb, y1 = (f32x4){bflo(r.z), bfhi(r.z), bflo(r.w), bfhi(r.w)} * ca + acc[ai][bj][m][1] * cb;
;                     *(GAS v4u*)(dst + off + bj * 128) = tr4(t.pull, pack8(y0, y1)); } }
	global_store_dwordx4 v[134:135], v[50:53], off offset:256
	s_waitcnt vmcnt(15)
	ds_bpermute_b32 v143, v133, v187
	ds_bpermute_b32 v142, v133, v186
	ds_bpermute_b32 v145, v133, v189
	ds_bpermute_b32 v144, v133, v188
	s_mov_b64 s[12:13], 0x48000
	v_lshl_add_u64 v[134:135], v[140:141], 0, s[12:13]
	s_waitcnt lgkmcnt(3)
	v_lshlrev_b32_e32 v136, 16, v143
	v_and_b32_e32 v137, 0xffff0000, v143
	s_waitcnt lgkmcnt(2)
	v_and_b32_e32 v143, 0xffff0000, v142
	v_lshlrev_b32_e32 v142, 16, v142
	v_pk_mul_f32 v[136:137], v[136:137], s[96:97] op_sel_hi:[1,0]
	v_pk_fma_f32 v[48:49], v[48:49], 0.5, v[136:137] op_sel_hi:[1,0,1]
	v_pk_mul_f32 v[142:143], v[142:143], s[96:97] op_sel_hi:[1,0]
	v_pk_fma_f32 v[46:47], v[46:47], 0.5, v[142:143] op_sel_hi:[1,0,1]
	s_waitcnt lgkmcnt(1)
	v_lshlrev_b32_e32 v136, 16, v145
	v_and_b32_e32 v137, 0xffff0000, v145
	s_waitcnt lgkmcnt(0)
	v_and_b32_e32 v145, 0xffff0000, v144
	v_lshlrev_b32_e32 v144, 16, v144
	v_pk_mul_f32 v[136:137], v[136:137], s[96:97] op_sel_hi:[1,0]
	v_pk_fma_f32 v[44:45], v[44:45], 0.5, v[136:137] op_sel_hi:[1,0,1]
	v_pk_mul_f32 v[144:145], v[144:145], s[96:97] op_sel_hi:[1,0]
	v_pk_fma_f32 v[42:43], v[42:43], 0.5, v[144:145] op_sel_hi:[1,0,1]
	v_cvt_pk_bf16_f32 v46, v46, v47
	v_cvt_pk_bf16_f32 v47, v48, v49
	v_cvt_pk_bf16_f32 v48, v42, v43
	v_cvt_pk_bf16_f32 v45, v44, v45
	s_nop 1
	ds_bpermute_b32 v42, v132, v46
	ds_bpermute_b32 v43, v132, v47
	ds_bpermute_b32 v44, v132, v48
	ds_bpermute_b32 v45, v132, v45
	s_waitcnt lgkmcnt(0)
	global_store_dwordx4 v[134:135], v[42:45], off
	s_waitcnt vmcnt(15)
	ds_bpermute_b32 v143, v133, v191
	ds_bpermute_b32 v142, v133, v190
	ds_bpermute_b32 v145, v133, v193
	ds_bpermute_b32 v144, v133, v192
	s_waitcnt lgkmcnt(3)
	v_lshlrev_b32_e32 v136, 16, v143
	v_and_b32_e32 v137, 0xffff0000, v143
	s_waitcnt lgkmcnt(2)
	v_and_b32_e32 v143, 0xffff0000, v142
	v_lshlrev_b32_e32 v142, 16, v142
	v_pk_mul_f32 v[136:137], v[136:137], s[96:97] op_sel_hi:[1,0]
	v_pk_fma_f32 v[40:41], v[40:41], 0.5, v[136:137] op_sel_hi:[1,0,1]
	v_pk_mul_f32 v[142:143], v[142:143], s[96:97] op_sel_hi:[1,0]
	v_pk_fma_f32 v[38:39], v[38:39], 0.5, v[142:143] op_sel_hi:[1,0,1]
	s_waitcnt lgkmcnt(1)
	v_lshlrev_b32_e32 v136, 16, v145
	v_and_b32_e32 v137, 0xffff0000, v145
	s_waitcnt lgkmcnt(0)
	v_and_b32_e32 v145, 0xffff0000, v144
	v_lshlrev_b32_e32 v144, 16, v144
	v_pk_mul_f32 v[136:137], v[136:137], s[96:97] op_sel_hi:[1,0]
	v_pk_fma_f32 v[36:37], v[36:37], 0.5, v[136:137] op_sel_hi:[1,0,1]
	v_pk_mul_f32 v[144:145], v[144:145], s[96:97] op_sel_hi:[1,0]
	v_pk_fma_f32 v[34:35], v[34:35], 0.5, v[144:145] op_sel_hi:[1,0,1]
	v_cvt_pk_bf16_f32 v38, v38, v39
	v_cvt_pk_bf16_f32 v39, v40, v41
	v_cvt_pk_bf16_f32 v40, v34, v35
	v_cvt_pk_bf16_f32 v37, v36, v37
	s_nop 1
	ds_bpermute_b32 v34, v132, v38
	ds_bpermute_b32 v35, v132, v39
	ds_bpermute_b32 v36, v132, v40
	ds_bpermute_b32 v37, v132, v37
	s_waitcnt lgkmcnt(0)
	global_store_dwordx4 v[134:135], v[34:37], off offset:256
	s_waitcnt vmcnt(14)
	ds_bpermute_b32 v143, v133, v127
	ds_bpermute_b32 v142, v133, v126
	ds_bpermute_b32 v145, v133, v129
	ds_bpermute_b32 v144, v133, v128
	s_mov_b64 s[12:13], 0x50000
	v_lshl_add_u64 v[134:135], v[140:141], 0, s[12:13]
	s_waitcnt lgkmcnt(3)
	v_lshlrev_b32_e32 v136, 16, v143
	v_and_b32_e32 v137, 0xffff0000, v143
	s_waitcnt lgkmcnt(2)
	v_and_b32_e32 v143, 0xffff0000, v142
	v_lshlrev_b32_e32 v142, 16, v142
	v_pk_mul_f32 v[136:137], v[136:137], s[96:97] op_sel_hi:[1,0]
	v_pk_fma_f32 v[32:33], v[32:33], 0.5, v[136:137] op_sel_hi:[1,0,1]
	v_pk_mul_f32 v[142:143], v[142:143], s[96:97] op_sel_hi:[1,0]
	v_pk_fma_f32 v[30:31], v[30:31], 0.5, v[142:143] op_sel_hi:[1,0,1]
	s_waitcnt lgkmcnt(1)
	v_lshlrev_b32_e32 v136, 16, v145
	v_and_b32_e32 v137, 0xffff0000, v145
	s_waitcnt lgkmcnt(0)
	v_and_b32_e32 v145, 0xffff0000, v144
	v_lshlrev_b32_e32 v144, 16, v144
	v_pk_mul_f32 v[136:137], v[136:137], s[96:97] op_sel_hi:[1,0]
	v_pk_fma_f32 v[28:29], v[28:29], 0.5, v[136:137] op_sel_hi:[1,0,1]
	v_pk_mul_f32 v[144:145], v[144:145], s[96:97] op_sel_hi:[1,0]
	v_pk_fma_f32 v[26:27], v[26:27], 0.5, v[144:145] op_sel_hi:[1,0,1]
	v_cvt_pk_bf16_f32 v30, v30, v31
	v_cvt_pk_bf16_f32 v31, v32, v33
	v_cvt_pk_bf16_f32 v32, v26, v27
	v_cvt_pk_bf16_f32 v29, v28, v29
	s_nop 1
	ds_bpermute_b32 v26, v132, v30
	ds_bpermute_b32 v27, v132, v31
	ds_bpermute_b32 v28, v132, v32
	ds_bpermute_b32 v29, v132, v29
	s_waitcnt lgkmcnt(0)
; #define PG8_BAR __builtin_amdgcn_s_barrier()
; #define GAS __attribute__((address_space(1)))
; __device__ __forceinline__ v4u tr4(int a, v4u x) { return (v4u){bperm(a, x.x), bperm(a, x.y), bperm(a, x.z), bperm(a, x.w)}; }
; __device__ __forceinline__ v4u pack8(const f32x4& a, const f32x4& b) { return (v4u){pg8::cvt_pk_bf16(a[0], a[1]), pg8::cvt_pk_bf16(a[2], a[3]), pg8::cvt_pk_bf16(b[0], b[1]), pg8::cvt_pk_bf16(b[2], b[3])}; }
; template <class Epi, class Sched, bool ALIGN_EPI = false, bool SP2 = false>
; __device__ __forceinline__ void gemm_phase(PG8_LAS unsigned char* lds, const Gemm g, const Sched& S, const Epi& E, const int wave_id) {
;     ...
;         if (!has_next) break;
;         if (!keep_acc) {
; #pragma unroll
;         for (int a = 0; a < 2; ++a)
; #pragma unroll
;             for (int b = 0; b < 2; ++b)
; #pragma unroll
;                 for (int m = 0; m < 4; ++m)
; #pragma unroll
;                     for (int n = 0; n < 2; ++n) acc[a][b][m][n] = (f32x4){0.f, 0.f, 0.f, 0.f};
;         }
;         cur = nxt; cA = nA; cB = nB; ++ui;
;         if constexpr (ALIGN_EPI) { if (wr == 1) PG8_BAR; }
;     __device__ __forceinline__ bool operator()(AccT& acc, const Unit& u, int wr, int wc, int fr, int fq) const {
;     ...
;             for (int m = 0; m < 4; ++m) { const size_t off = (size_t)(row0 + ai * 128 + m * 16) * D + col0;
; #pragma unroll
;                 for (int bj = 0; bj < 2; ++bj) { const v4u r = tr4(t.push, *(const GAS v4u*)(src + off + bj * 128));
;                     const f32x4 y0 = (f32x4){bflo(r.x), bfhi(r.x), bflo(r.y), bfhi(r.y)} * ca + acc[ai][bj][m][0] * cb, y1 = (f32x4){bflo(r.z), bfhi(r.z), bflo(r.w), bfhi(r.w)} * ca + acc[ai][bj][m][1] * cb;
;                     *(GAS v4u*)(dst + off + bj * 128) = tr4(t.pull, pack8(y0, y1)); } }
	global_store_dwordx4 v[134:135], v[26:29], off
	s_waitcnt vmcnt(13)
	ds_bpermute_b32 v143, v133, v119
	ds_bpermute_b32 v142, v133, v118
	ds_bpermute_b32 v145, v133, v121
	ds_bpermute_b32 v144, v133, v120
	s_waitcnt lgkmcnt(3)
	v_lshlrev_b32_e32 v136, 16, v143
	v_and_b32_e32 v137, 0xffff0000, v143
	s_waitcnt lgkmcnt(2)
	v_and_b32_e32 v143, 0xffff0000, v142
	v_lshlrev_b32_e32 v142, 16, v142
	v_pk_mul_f32 v[136:137], v[136:137], s[96:97] op_sel_hi:[1,0]
	v_pk_fma_f32 v[24:25], v[24:25], 0.5, v[136:137] op_sel_hi:[1,0,1]
	v_pk_mul_f32 v[142:143], v[142:143], s[96:97] op_sel_hi:[1,0]
	v_pk_fma_f32 v[22:23], v[22:23], 0.5, v[142:143] op_sel_hi:[1,0,1]
	s_waitcnt lgkmcnt(1)
	v_lshlrev_b32_e32 v136, 16, v145
	v_and_b32_e32 v137, 0xffff0000, v145
	s_waitcnt lgkmcnt(0)
	v_and_b32_e32 v145, 0xffff0000, v144
	v_lshlrev_b32_e32 v144, 16, v144
	v_pk_mul_f32 v[136:137], v[136:137], s[96:97] op_sel_hi:[1,0]
	v_pk_fma_f32 v[20:21], v[20:21], 0.5, v[136:137] op_sel_hi:[1,0,1]
	v_pk_mul_f32 v[144:145], v[144:145], s[96:97] op_sel_hi:[1,0]
	v_pk_fma_f32 v[18:19], v[18:19], 0.5, v[144:145] op_sel_hi:[1,0,1]
	v_cvt_pk_bf16_f32 v22, v22, v23
	v_cvt_pk_bf16_f32 v23, v24, v25
	v_cvt_pk_bf16_f32 v24, v18, v19
	v_cvt_pk_bf16_f32 v21, v20, v21
	s_nop 1
	ds_bpermute_b32 v18, v132, v22
	ds_bpermute_b32 v19, v132, v23
	ds_bpermute_b32 v20, v132, v24
	ds_bpermute_b32 v21, v132, v21
	s_waitcnt lgkmcnt(0)
	global_store_dwordx4 v[134:135], v[18:21], off offset:256
	s_waitcnt vmcnt(12)
	ds_bpermute_b32 v143, v133, v111
	ds_bpermute_b32 v142, v133, v110
	ds_bpermute_b32 v145, v133, v113
	ds_bpermute_b32 v144, v133, v112
	s_mov_b64 s[12:13], 0x58000
	v_lshl_add_u64 v[134:135], v[140:141], 0, s[12:13]
	s_waitcnt lgkmcnt(3)
	v_lshlrev_b32_e32 v136, 16, v143
	v_and_b32_e32 v137, 0xffff0000, v143
	s_waitcnt lgkmcnt(2)
	v_and_b32_e32 v143, 0xffff0000, v142
	v_lshlrev_b32_e32 v142, 16, v142
	v_pk_mul_f32 v[136:137], v[136:137], s[96:97] op_sel_hi:[1,0]
	v_pk_fma_f32 v[16:17], v[16:17], 0.5, v[136:137] op_sel_hi:[1,0,1]
	v_pk_mul_f32 v[142:143], v[142:143], s[96:97] op_sel_hi:[1,0]
	v_pk_fma_f32 v[14:15], v[14:15], 0.5, v[142:143] op_sel_hi:[1,0,1]
	s_waitcnt lgkmcnt(1)
	v_lshlrev_b32_e32 v136, 16, v145
	v_and_b32_e32 v137, 0xffff0000, v145
	s_waitcnt lgkmcnt(0)
	v_and_b32_e32 v145, 0xffff0000, v144
	v_lshlrev_b32_e32 v144, 16, v144
	v_pk_mul_f32 v[136:137], v[136:137], s[96:97] op_sel_hi:[1,0]
	v_pk_fma_f32 v[12:13], v[12:13], 0.5, v[136:137] op_sel_hi:[1,0,1]
	v_pk_mul_f32 v[144:145], v[144:145], s[96:97] op_sel_hi:[1,0]
	v_pk_fma_f32 v[10:11], v[10:11], 0.5, v[144:145] op_sel_hi:[1,0,1]
	v_cvt_pk_bf16_f32 v14, v14, v15
	v_cvt_pk_bf16_f32 v15, v16, v17
	v_cvt_pk_bf16_f32 v16, v10, v11
	v_cvt_pk_bf16_f32 v13, v12, v13
	s_nop 1
	ds_bpermute_b32 v10, v132, v14
	ds_bpermute_b32 v11, v132, v15
	ds_bpermute_b32 v12, v132, v16
	ds_bpermute_b32 v13, v132, v13
	s_waitcnt lgkmcnt(0)
	global_store_dwordx4 v[134:135], v[10:13], off
	s_waitcnt vmcnt(11)
	ds_bpermute_b32 v143, v133, v103
	ds_bpermute_b32 v142, v133, v102
	ds_bpermute_b32 v145, v133, v105
	ds_bpermute_b32 v144, v133, v104
	s_waitcnt lgkmcnt(3)
	v_lshlrev_b32_e32 v136, 16, v143
	v_and_b32_e32 v137, 0xffff0000, v143
	s_waitcnt lgkmcnt(2)
	v_and_b32_e32 v143, 0xffff0000, v142
	v_lshlrev_b32_e32 v142, 16, v142
	v_pk_mul_f32 v[136:137], v[136:137], s[96:97] op_sel_hi:[1,0]
	v_pk_fma_f32 v[8:9], v[8:9], 0.5, v[136:137] op_sel_hi:[1,0,1]
	v_pk_mul_f32 v[142:143], v[142:143], s[96:97] op_sel_hi:[1,0]
	v_pk_fma_f32 v[6:7], v[6:7], 0.5, v[142:143] op_sel_hi:[1,0,1]
	s_waitcnt lgkmcnt(1)
	v_lshlrev_b32_e32 v136, 16, v145
	v_and_b32_e32 v137, 0xffff0000, v145
	s_waitcnt lgkmcnt(0)
	v_and_b32_e32 v145, 0xffff0000, v144
	v_lshlrev_b32_e32 v144, 16, v144
	v_pk_mul_f32 v[136:137], v[136:137], s[96:97] op_sel_hi:[1,0]
	v_pk_fma_f32 v[4:5], v[4:5], 0.5, v[136:137] op_sel_hi:[1,0,1]
	v_pk_mul_f32 v[144:145], v[144:145], s[96:97] op_sel_hi:[1,0]
	v_pk_fma_f32 v[2:3], v[2:3], 0.5, v[144:145] op_sel_hi:[1,0,1]
	v_cvt_pk_bf16_f32 v6, v6, v7
	v_cvt_pk_bf16_f32 v7, v8, v9
	v_cvt_pk_bf16_f32 v8, v2, v3
	v_cvt_pk_bf16_f32 v5, v4, v5
	s_nop 1
	ds_bpermute_b32 v2, v132, v6
	ds_bpermute_b32 v3, v132, v7
	ds_bpermute_b32 v4, v132, v8
	ds_bpermute_b32 v5, v132, v5
	s_waitcnt lgkmcnt(0)
	global_store_dwordx4 v[134:135], v[2:5], off offset:256
	s_mov_b64 s[12:13], -1
	s_cbranch_vccnz .LBB0_2018
	s_andn2_b64 vcc, exec, s[2:3]
	s_cbranch_vccnz .LBB0_2017
	s_branch .LBB0_2017
